# hand-written rmsnorm phases (all loads in flight), residual GEMM epilogues with batched loads, G_UP epilogue 16-byte write-through stores via permlane16_swap
# speedup vs baseline: 1.0593x; 1.0419x over previous
.LBB0_15:
	s_cmp_eq_u32 s50, 45
	s_mov_b64 s[0:1], -1
	s_cbranch_scc0 .LBB0_40
	v_readlane_b32 s4, v217, 0
	v_readlane_b32 s38, v217, 1
	v_readlane_b32 s39, v217, 2
	v_lshrrev_b32_e32 v197, 6, v142
	s_sub_u32 s38, s38, 0xd0
	s_subb_u32 s39, s39, 0
	v_readfirstlane_b32 s6, v197
	s_load_dwordx2 s[96:97], s[38:39], 0xb8
	s_load_dwordx2 s[38:39], s[38:39], 0xb0
	v_and_b32_e32 v194, 63, v142
	v_lshlrev_b32_e32 v195, 3, v194
	v_lshlrev_b32_e32 v194, 4, v194
	v_mov_b32_e32 v196, 0x358637bd
	s_lshr_b32 s7, s4, 3
	s_lshl_b32 s7, s7, 3
	s_add_u32 s7, s7, s6
	s_and_b32 s10, s4, 7
	s_mul_i32 s10, s10, 192
	s_add_u32 s11, s7, 0
	s_mul_i32 s12, s11, 43691
	s_lshr_b32 s12, s12, 23
	s_mul_i32 s12, s12, 1344
	s_add_u32 s11, s11, s12
	s_add_u32 s98, s11, s10
	s_add_u32 s11, s7, 256
	s_mul_i32 s12, s11, 43691
	s_lshr_b32 s12, s12, 23
	s_mul_i32 s12, s12, 1344
	s_add_u32 s11, s11, s12
	s_add_u32 s99, s11, s10
	s_add_u32 s11, s7, 512
	s_mul_i32 s12, s11, 43691
	s_lshr_b32 s12, s12, 23
	s_mul_i32 s12, s12, 1344
	s_add_u32 s11, s11, s12
	s_add_u32 s17, s11, s10
	s_waitcnt lgkmcnt(0)
	s_lshl_b32 s11, s98, 12
	s_add_u32 s68, s48, s11
	s_addc_u32 s69, s49, 0
	global_load_dwordx4 v[2:5], v194, s[68:69] offset:0
	global_load_dwordx4 v[6:9], v194, s[68:69] offset:1024
	global_load_dwordx4 v[10:13], v194, s[68:69] offset:2048
	global_load_dwordx4 v[14:17], v194, s[68:69] offset:3072
	s_lshl_b32 s11, s99, 12
	s_add_u32 s70, s48, s11
	s_addc_u32 s71, s49, 0
	global_load_dwordx4 v[18:21], v194, s[70:71] offset:0
	global_load_dwordx4 v[22:25], v194, s[70:71] offset:1024
	global_load_dwordx4 v[26:29], v194, s[70:71] offset:2048
	global_load_dwordx4 v[30:33], v194, s[70:71] offset:3072
	s_lshl_b32 s11, s17, 12
	s_add_u32 s72, s48, s11
	s_addc_u32 s73, s49, 0
	global_load_dwordx4 v[34:37], v194, s[72:73] offset:0
	global_load_dwordx4 v[38:41], v194, s[72:73] offset:1024
	global_load_dwordx4 v[42:45], v194, s[72:73] offset:2048
	global_load_dwordx4 v[46:49], v194, s[72:73] offset:3072
	s_mov_b32 s42, s17
	global_load_dwordx4 v[50:53], v194, s[38:39] offset:0
	global_load_dwordx4 v[54:57], v194, s[38:39] offset:1024
	global_load_dwordx4 v[58:61], v194, s[38:39] offset:2048
	global_load_dwordx4 v[62:65], v194, s[38:39] offset:3072
	s_waitcnt vmcnt(4)
	s_lshl_b32 s11, s98, 12
	s_add_u32 s68, s96, s11
	s_addc_u32 s69, s97, 0
	s_lshl_b32 s11, s99, 12
	s_add_u32 s70, s96, s11
	s_addc_u32 s71, s97, 0
	s_lshl_b32 s11, s42, 12
	s_add_u32 s72, s96, s11
	s_addc_u32 s73, s97, 0
	v_mul_f32_e32 v198, v2, v2
	v_mul_f32_e32 v199, v18, v18
	v_mul_f32_e32 v200, v34, v34
	v_fmac_f32_e32 v198, v3, v3
	v_fmac_f32_e32 v199, v19, v19
	v_fmac_f32_e32 v200, v35, v35
	v_fmac_f32_e32 v198, v4, v4
	v_fmac_f32_e32 v199, v20, v20
	v_fmac_f32_e32 v200, v36, v36
	v_fmac_f32_e32 v198, v5, v5
	v_fmac_f32_e32 v199, v21, v21
	v_fmac_f32_e32 v200, v37, v37
	v_fmac_f32_e32 v198, v6, v6
	v_fmac_f32_e32 v199, v22, v22
	v_fmac_f32_e32 v200, v38, v38
	v_fmac_f32_e32 v198, v7, v7
	v_fmac_f32_e32 v199, v23, v23
	v_fmac_f32_e32 v200, v39, v39
	v_fmac_f32_e32 v198, v8, v8
	v_fmac_f32_e32 v199, v24, v24
	v_fmac_f32_e32 v200, v40, v40
	v_fmac_f32_e32 v198, v9, v9
	v_fmac_f32_e32 v199, v25, v25
	v_fmac_f32_e32 v200, v41, v41
	v_fmac_f32_e32 v198, v10, v10
	v_fmac_f32_e32 v199, v26, v26
	v_fmac_f32_e32 v200, v42, v42
	v_fmac_f32_e32 v198, v11, v11
	v_fmac_f32_e32 v199, v27, v27
	v_fmac_f32_e32 v200, v43, v43
	v_fmac_f32_e32 v198, v12, v12
	v_fmac_f32_e32 v199, v28, v28
	v_fmac_f32_e32 v200, v44, v44
	v_fmac_f32_e32 v198, v13, v13
	v_fmac_f32_e32 v199, v29, v29
	v_fmac_f32_e32 v200, v45, v45
	v_fmac_f32_e32 v198, v14, v14
	v_fmac_f32_e32 v199, v30, v30
	v_fmac_f32_e32 v200, v46, v46
	v_fmac_f32_e32 v198, v15, v15
	v_fmac_f32_e32 v199, v31, v31
	v_fmac_f32_e32 v200, v47, v47
	v_fmac_f32_e32 v198, v16, v16
	v_fmac_f32_e32 v199, v32, v32
	v_fmac_f32_e32 v200, v48, v48
	v_fmac_f32_e32 v198, v17, v17
	v_fmac_f32_e32 v199, v33, v33
	v_fmac_f32_e32 v200, v49, v49
	s_nop 1
	v_add_f32_dpp v198, v198, v198 quad_perm:[1,0,3,2] row_mask:0xf bank_mask:0xf
	v_add_f32_dpp v199, v199, v199 quad_perm:[1,0,3,2] row_mask:0xf bank_mask:0xf
	v_add_f32_dpp v200, v200, v200 quad_perm:[1,0,3,2] row_mask:0xf bank_mask:0xf
	s_nop 1
	v_add_f32_dpp v198, v198, v198 quad_perm:[2,3,0,1] row_mask:0xf bank_mask:0xf
	v_add_f32_dpp v199, v199, v199 quad_perm:[2,3,0,1] row_mask:0xf bank_mask:0xf
	v_add_f32_dpp v200, v200, v200 quad_perm:[2,3,0,1] row_mask:0xf bank_mask:0xf
	s_nop 1
	v_add_f32_dpp v198, v198, v198 row_half_mirror row_mask:0xf bank_mask:0xf
	v_add_f32_dpp v199, v199, v199 row_half_mirror row_mask:0xf bank_mask:0xf
	v_add_f32_dpp v200, v200, v200 row_half_mirror row_mask:0xf bank_mask:0xf
	s_nop 1
	v_add_f32_dpp v198, v198, v198 row_mirror row_mask:0xf bank_mask:0xf
	v_add_f32_dpp v199, v199, v199 row_mirror row_mask:0xf bank_mask:0xf
	v_add_f32_dpp v200, v200, v200 row_mirror row_mask:0xf bank_mask:0xf
	s_nop 1
	v_add_f32_dpp v198, v198, v198 row_bcast:15 row_mask:0xa bank_mask:0xf
	v_add_f32_dpp v199, v199, v199 row_bcast:15 row_mask:0xa bank_mask:0xf
	v_add_f32_dpp v200, v200, v200 row_bcast:15 row_mask:0xa bank_mask:0xf
	s_nop 1
	v_add_f32_dpp v198, v198, v198 row_bcast:31 row_mask:0xc bank_mask:0xf
	v_add_f32_dpp v199, v199, v199 row_bcast:31 row_mask:0xc bank_mask:0xf
	v_add_f32_dpp v200, v200, v200 row_bcast:31 row_mask:0xc bank_mask:0xf
	s_nop 1
	v_readlane_b32 s32, v198, 63
	v_readlane_b32 s20, v199, 63
	v_readlane_b32 s94, v200, 63
	s_nop 0
	v_mov_b32_e32 v201, s32
	v_mov_b32_e32 v202, s20
	v_mov_b32_e32 v203, s94
	v_fmamk_f32 v201, v201, 0x3a800000, v196
	v_fmamk_f32 v202, v202, 0x3a800000, v196
	v_fmamk_f32 v203, v203, 0x3a800000, v196
	v_rsq_f32_e32 v201, v201
	v_rsq_f32_e32 v202, v202
	v_rsq_f32_e32 v203, v203
	s_waitcnt vmcnt(0)
	v_mul_f32_e32 v204, v2, v201
	v_mul_f32_e32 v205, v3, v201
	v_mul_f32_e32 v206, v4, v201
	v_mul_f32_e32 v207, v5, v201
	v_mul_f32_e32 v204, v50, v204
	v_mul_f32_e32 v205, v51, v205
	v_mul_f32_e32 v206, v52, v206
	v_mul_f32_e32 v207, v53, v207
	global_store_dwordx4 v194, v[204:207], s[68:69] offset:0
	s_nop 1
	v_mul_f32_e32 v204, v6, v201
	v_mul_f32_e32 v205, v7, v201
	v_mul_f32_e32 v206, v8, v201
	v_mul_f32_e32 v207, v9, v201
	v_mul_f32_e32 v204, v54, v204
	v_mul_f32_e32 v205, v55, v205
	v_mul_f32_e32 v206, v56, v206
	v_mul_f32_e32 v207, v57, v207
	global_store_dwordx4 v194, v[204:207], s[68:69] offset:1024
	s_nop 1
	v_mul_f32_e32 v204, v10, v201
	v_mul_f32_e32 v205, v11, v201
	v_mul_f32_e32 v206, v12, v201
	v_mul_f32_e32 v207, v13, v201
	v_mul_f32_e32 v204, v58, v204
	v_mul_f32_e32 v205, v59, v205
	v_mul_f32_e32 v206, v60, v206
	v_mul_f32_e32 v207, v61, v207
	global_store_dwordx4 v194, v[204:207], s[68:69] offset:2048
	s_nop 1
	v_mul_f32_e32 v204, v14, v201
	v_mul_f32_e32 v205, v15, v201
	v_mul_f32_e32 v206, v16, v201
	v_mul_f32_e32 v207, v17, v201
	v_mul_f32_e32 v204, v62, v204
	v_mul_f32_e32 v205, v63, v205
	v_mul_f32_e32 v206, v64, v206
	v_mul_f32_e32 v207, v65, v207
	global_store_dwordx4 v194, v[204:207], s[68:69] offset:3072
	s_nop 1
	v_mul_f32_e32 v204, v18, v202
	v_mul_f32_e32 v205, v19, v202
	v_mul_f32_e32 v206, v20, v202
	v_mul_f32_e32 v207, v21, v202
	v_mul_f32_e32 v204, v50, v204
	v_mul_f32_e32 v205, v51, v205
	v_mul_f32_e32 v206, v52, v206
	v_mul_f32_e32 v207, v53, v207
	global_store_dwordx4 v194, v[204:207], s[70:71] offset:0
	s_nop 1
	v_mul_f32_e32 v204, v22, v202
	v_mul_f32_e32 v205, v23, v202
	v_mul_f32_e32 v206, v24, v202
	v_mul_f32_e32 v207, v25, v202
	v_mul_f32_e32 v204, v54, v204
	v_mul_f32_e32 v205, v55, v205
	v_mul_f32_e32 v206, v56, v206
	v_mul_f32_e32 v207, v57, v207
	global_store_dwordx4 v194, v[204:207], s[70:71] offset:1024
	s_nop 1
	v_mul_f32_e32 v204, v26, v202
	v_mul_f32_e32 v205, v27, v202
	v_mul_f32_e32 v206, v28, v202
	v_mul_f32_e32 v207, v29, v202
	v_mul_f32_e32 v204, v58, v204
	v_mul_f32_e32 v205, v59, v205
	v_mul_f32_e32 v206, v60, v206
	v_mul_f32_e32 v207, v61, v207
	global_store_dwordx4 v194, v[204:207], s[70:71] offset:2048
	s_nop 1
	v_mul_f32_e32 v204, v30, v202
	v_mul_f32_e32 v205, v31, v202
	v_mul_f32_e32 v206, v32, v202
	v_mul_f32_e32 v207, v33, v202
	v_mul_f32_e32 v204, v62, v204
	v_mul_f32_e32 v205, v63, v205
	v_mul_f32_e32 v206, v64, v206
	v_mul_f32_e32 v207, v65, v207
	global_store_dwordx4 v194, v[204:207], s[70:71] offset:3072
	s_nop 1
	v_mul_f32_e32 v204, v34, v203
	v_mul_f32_e32 v205, v35, v203
	v_mul_f32_e32 v206, v36, v203
	v_mul_f32_e32 v207, v37, v203
	v_mul_f32_e32 v204, v50, v204
	v_mul_f32_e32 v205, v51, v205
	v_mul_f32_e32 v206, v52, v206
	v_mul_f32_e32 v207, v53, v207
	global_store_dwordx4 v194, v[204:207], s[72:73] offset:0
	s_nop 1
	v_mul_f32_e32 v204, v38, v203
	v_mul_f32_e32 v205, v39, v203
	v_mul_f32_e32 v206, v40, v203
	v_mul_f32_e32 v207, v41, v203
	v_mul_f32_e32 v204, v54, v204
	v_mul_f32_e32 v205, v55, v205
	v_mul_f32_e32 v206, v56, v206
	v_mul_f32_e32 v207, v57, v207
	global_store_dwordx4 v194, v[204:207], s[72:73] offset:1024
	s_nop 1
	v_mul_f32_e32 v204, v42, v203
	v_mul_f32_e32 v205, v43, v203
	v_mul_f32_e32 v206, v44, v203
	v_mul_f32_e32 v207, v45, v203
	v_mul_f32_e32 v204, v58, v204
	v_mul_f32_e32 v205, v59, v205
	v_mul_f32_e32 v206, v60, v206
	v_mul_f32_e32 v207, v61, v207
	global_store_dwordx4 v194, v[204:207], s[72:73] offset:2048
	s_nop 1
	v_mul_f32_e32 v204, v46, v203
	v_mul_f32_e32 v205, v47, v203
	v_mul_f32_e32 v206, v48, v203
	v_mul_f32_e32 v207, v49, v203
	v_mul_f32_e32 v204, v62, v204
	v_mul_f32_e32 v205, v63, v205
	v_mul_f32_e32 v206, v64, v206
	v_mul_f32_e32 v207, v65, v207
	global_store_dwordx4 v194, v[204:207], s[72:73] offset:3072
	s_nop 1
	s_mov_b64 s[0:1], 0
	s_branch .LBB0_40

.LBB0_42:
	s_add_i32 s0, s50, -1
	s_mul_hi_i32 s1, s0, 0x2e8ba2e9
	s_lshr_b32 s2, s1, 31
	s_ashr_i32 s1, s1, 1
	s_add_i32 s4, s1, s2
	s_mov_b32 s2, s4
	v_writelane_b32 v214, s2, 57
	s_mul_i32 s1, s4, 11
	s_sub_i32 s21, s0, s1
	v_writelane_b32 v214, s3, 58
	s_mov_b64 s[2:3], 0
	s_mov_b64 s[0:1], -1
	s_cmp_lt_i32 s21, 5
	v_writelane_b32 v214, s2, 59
	s_nop 1
	v_writelane_b32 v214, s3, 60
	s_cbranch_scc1 .LBB0_167
	s_cmp_gt_i32 s21, 6
	s_cbranch_scc0 .LBB0_57
	v_readlane_b32 s8, v217, 20
	s_cmp_gt_i32 s21, 7
	v_readlane_b32 s9, v217, 21
	s_cbranch_scc0 .LBB0_58
	s_cmp_gt_i32 s21, 8
	s_cbranch_scc0 .LBB0_59
	s_cmp_eq_u32 s21, 9
	s_cbranch_scc0 .LBB0_71
	v_readlane_b32 s11, v217, 0
	v_readlane_b32 s12, v214, 57
	s_and_b32 s14, s11, 7
	s_lshr_b32 s15, s11, 3
	s_mul_hi_u32 s16, s12, 0x3500000
	s_mul_i32 s12, s12, 0x3500000
	s_add_u32 s40, s48, s12
	s_addc_u32 s41, s49, s16
	s_add_u32 s40, s40, 0x11a4e000
	s_addc_u32 s41, s41, 0
	v_and_b32_e32 v141, 15, v142
	v_lshrrev_b32_e32 v139, 4, v142
	v_and_b32_e32 v139, 3, v139
	v_lshlrev_b32_e32 v140, 6, v141
	v_lshl_add_u32 v140, v139, 4, v140
	v_lshrrev_b32_e32 v139, 3, v141
	v_lshlrev_b32_e32 v139, 5, v139
	v_xor_b32_e32 v135, v140, v139
	v_lshrrev_b32_e32 v139, 7, v142
	v_lshl_add_u32 v134, v139, 12, v135
	v_lshrrev_b32_e32 v139, 6, v142
	v_and_b32_e32 v139, 1, v139
	v_lshl_add_u32 v135, v139, 12, v135
	v_add_u32_e32 v135, 0x4000, v135
	v_and_b32_e32 v141, 63, v142
	v_lshrrev_b32_e32 v139, 2, v141
	v_lshrrev_b32_e32 v140, 6, v142
	v_lshl_add_u32 v139, v140, 4, v139
	v_lshlrev_b32_e32 v139, 11, v139
	v_and_b32_e32 v140, 3, v141
	v_lshlrev_b32_e32 v140, 4, v140
	v_lshrrev_b32_e32 v141, 5, v141
	v_lshlrev_b32_e32 v141, 5, v141
	v_xor_b32_e32 v140, v140, v141
	v_add_u32_e32 v136, v139, v140
	v_add_u32_e32 v137, 0x40000, v136
	v_lshrrev_b32_e32 v139, 7, v142
	v_and_b32_e32 v141, 15, v142
	v_lshl_add_u32 v139, v139, 6, v141
	v_mul_u32_u24_e32 v139, 0x1600, v139
	v_lshrrev_b32_e32 v140, 6, v142
	v_and_b32_e32 v140, 1, v140
	v_lshlrev_b32_e32 v140, 6, v140
	v_lshrrev_b32_e32 v141, 4, v142
	v_and_b32_e32 v141, 3, v141
	v_lshl_add_u32 v140, v141, 3, v140
	v_add_u32_e32 v138, v139, v140
	v_and_b32_e32 v141, 1, v141
	v_mul_u32_u24_e32 v141, 24, v141
	v_add_u32_e32 v138, v138, v141
	v_lshlrev_b32_e32 v161, 11, v142
	v_lshrrev_b32_e32 v141, 6, v142
	v_lshlrev_b32_e32 v141, 10, v141
	s_nop 0
	v_readfirstlane_b32 s6, v141
	s_mov_b32 s10, s15

.Lg2_a_kdone3:
	s_nop 7
	s_nop 1
	v_mov_b32_e32 v176, v138
	v_mul_f32_e32 v162, 0xbfb8aa3b, v2
	v_mul_f32_e32 v163, 0xbfb8aa3b, v3
	v_mul_f32_e32 v164, 0xbfb8aa3b, v4
	v_mul_f32_e32 v165, 0xbfb8aa3b, v5
	v_exp_f32_e32 v162, v162
	v_exp_f32_e32 v163, v163
	v_exp_f32_e32 v164, v164
	v_exp_f32_e32 v165, v165
	v_add_f32_e32 v162, 1.0, v162
	v_add_f32_e32 v163, 1.0, v163
	v_add_f32_e32 v164, 1.0, v164
	v_add_f32_e32 v165, 1.0, v165
	v_rcp_f32_e32 v162, v162
	v_rcp_f32_e32 v163, v163
	v_rcp_f32_e32 v164, v164
	v_rcp_f32_e32 v165, v165
	v_mul_f32_e32 v162, v2, v162
	v_mul_f32_e32 v163, v3, v163
	v_mul_f32_e32 v164, v4, v164
	v_mul_f32_e32 v165, v5, v165
	v_mul_f32_e32 v162, v10, v162
	v_mul_f32_e32 v163, v11, v163
	v_mul_f32_e32 v164, v12, v164
	v_mul_f32_e32 v165, v13, v165
	v_cvt_pk_bf16_f32 v168, v162, v163
	v_cvt_pk_bf16_f32 v169, v164, v165
	v_mul_f32_e32 v162, 0xbfb8aa3b, v6
	v_mul_f32_e32 v163, 0xbfb8aa3b, v7
	v_mul_f32_e32 v164, 0xbfb8aa3b, v8
	v_mul_f32_e32 v165, 0xbfb8aa3b, v9
	v_exp_f32_e32 v162, v162
	v_exp_f32_e32 v163, v163
	v_exp_f32_e32 v164, v164
	v_exp_f32_e32 v165, v165
	v_add_f32_e32 v162, 1.0, v162
	v_add_f32_e32 v163, 1.0, v163
	v_add_f32_e32 v164, 1.0, v164
	v_add_f32_e32 v165, 1.0, v165
	v_rcp_f32_e32 v162, v162
	v_rcp_f32_e32 v163, v163
	v_rcp_f32_e32 v164, v164
	v_rcp_f32_e32 v165, v165
	v_mul_f32_e32 v162, v6, v162
	v_mul_f32_e32 v163, v7, v163
	v_mul_f32_e32 v164, v8, v164
	v_mul_f32_e32 v165, v9, v165
	v_mul_f32_e32 v162, v14, v162
	v_mul_f32_e32 v163, v15, v163
	v_mul_f32_e32 v164, v16, v164
	v_mul_f32_e32 v165, v17, v165
	v_cvt_pk_bf16_f32 v170, v162, v163
	v_cvt_pk_bf16_f32 v171, v164, v165
	s_nop 1
	v_permlane16_swap_b32_e32 v168, v170
	v_permlane16_swap_b32_e32 v169, v171
	global_store_dwordx4 v176, v[168:171], s[4:5] offset:0 sc1
	v_mul_f32_e32 v162, 0xbfb8aa3b, v66
	v_mul_f32_e32 v163, 0xbfb8aa3b, v67
	v_mul_f32_e32 v164, 0xbfb8aa3b, v68
	v_mul_f32_e32 v165, 0xbfb8aa3b, v69
	v_exp_f32_e32 v162, v162
	v_exp_f32_e32 v163, v163
	v_exp_f32_e32 v164, v164
	v_exp_f32_e32 v165, v165
	v_add_f32_e32 v162, 1.0, v162
	v_add_f32_e32 v163, 1.0, v163
	v_add_f32_e32 v164, 1.0, v164
	v_add_f32_e32 v165, 1.0, v165
	v_rcp_f32_e32 v162, v162
	v_rcp_f32_e32 v163, v163
	v_rcp_f32_e32 v164, v164
	v_rcp_f32_e32 v165, v165
	v_mul_f32_e32 v162, v66, v162
	v_mul_f32_e32 v163, v67, v163
	v_mul_f32_e32 v164, v68, v164
	v_mul_f32_e32 v165, v69, v165
	v_mul_f32_e32 v162, v74, v162
	v_mul_f32_e32 v163, v75, v163
	v_mul_f32_e32 v164, v76, v164
	v_mul_f32_e32 v165, v77, v165
	v_cvt_pk_bf16_f32 v172, v162, v163
	v_cvt_pk_bf16_f32 v173, v164, v165
	v_mul_f32_e32 v162, 0xbfb8aa3b, v70
	v_mul_f32_e32 v163, 0xbfb8aa3b, v71
	v_mul_f32_e32 v164, 0xbfb8aa3b, v72
	v_mul_f32_e32 v165, 0xbfb8aa3b, v73
	v_exp_f32_e32 v162, v162
	v_exp_f32_e32 v163, v163
	v_exp_f32_e32 v164, v164
	v_exp_f32_e32 v165, v165
	v_add_f32_e32 v162, 1.0, v162
	v_add_f32_e32 v163, 1.0, v163
	v_add_f32_e32 v164, 1.0, v164
	v_add_f32_e32 v165, 1.0, v165
	v_rcp_f32_e32 v162, v162
	v_rcp_f32_e32 v163, v163
	v_rcp_f32_e32 v164, v164
	v_rcp_f32_e32 v165, v165
	v_mul_f32_e32 v162, v70, v162
	v_mul_f32_e32 v163, v71, v163
	v_mul_f32_e32 v164, v72, v164
	v_mul_f32_e32 v165, v73, v165
	v_mul_f32_e32 v162, v78, v162
	v_mul_f32_e32 v163, v79, v163
	v_mul_f32_e32 v164, v80, v164
	v_mul_f32_e32 v165, v81, v165
	v_cvt_pk_bf16_f32 v174, v162, v163
	v_cvt_pk_bf16_f32 v175, v164, v165
	s_nop 1
	v_permlane16_swap_b32_e32 v172, v174
	v_permlane16_swap_b32_e32 v173, v175
	global_store_dwordx4 v176, v[172:175], s[4:5] offset:128 sc1
	v_add_u32_e32 v176, 0x16000, v176
	v_mul_f32_e32 v162, 0xbfb8aa3b, v18
	v_mul_f32_e32 v163, 0xbfb8aa3b, v19
	v_mul_f32_e32 v164, 0xbfb8aa3b, v20
	v_mul_f32_e32 v165, 0xbfb8aa3b, v21
	v_exp_f32_e32 v162, v162
	v_exp_f32_e32 v163, v163
	v_exp_f32_e32 v164, v164
	v_exp_f32_e32 v165, v165
	v_add_f32_e32 v162, 1.0, v162
	v_add_f32_e32 v163, 1.0, v163
	v_add_f32_e32 v164, 1.0, v164
	v_add_f32_e32 v165, 1.0, v165
	v_rcp_f32_e32 v162, v162
	v_rcp_f32_e32 v163, v163
	v_rcp_f32_e32 v164, v164
	v_rcp_f32_e32 v165, v165
	v_mul_f32_e32 v162, v18, v162
	v_mul_f32_e32 v163, v19, v163
	v_mul_f32_e32 v164, v20, v164
	v_mul_f32_e32 v165, v21, v165
	v_mul_f32_e32 v162, v26, v162
	v_mul_f32_e32 v163, v27, v163
	v_mul_f32_e32 v164, v28, v164
	v_mul_f32_e32 v165, v29, v165
	v_cvt_pk_bf16_f32 v168, v162, v163
	v_cvt_pk_bf16_f32 v169, v164, v165
	v_mul_f32_e32 v162, 0xbfb8aa3b, v22
	v_mul_f32_e32 v163, 0xbfb8aa3b, v23
	v_mul_f32_e32 v164, 0xbfb8aa3b, v24
	v_mul_f32_e32 v165, 0xbfb8aa3b, v25
	v_exp_f32_e32 v162, v162
	v_exp_f32_e32 v163, v163
	v_exp_f32_e32 v164, v164
	v_exp_f32_e32 v165, v165
	v_add_f32_e32 v162, 1.0, v162
	v_add_f32_e32 v163, 1.0, v163
	v_add_f32_e32 v164, 1.0, v164
	v_add_f32_e32 v165, 1.0, v165
	v_rcp_f32_e32 v162, v162
	v_rcp_f32_e32 v163, v163
	v_rcp_f32_e32 v164, v164
	v_rcp_f32_e32 v165, v165
	v_mul_f32_e32 v162, v22, v162
	v_mul_f32_e32 v163, v23, v163
	v_mul_f32_e32 v164, v24, v164
	v_mul_f32_e32 v165, v25, v165
	v_mul_f32_e32 v162, v30, v162
	v_mul_f32_e32 v163, v31, v163
	v_mul_f32_e32 v164, v32, v164
	v_mul_f32_e32 v165, v33, v165
	v_cvt_pk_bf16_f32 v170, v162, v163
	v_cvt_pk_bf16_f32 v171, v164, v165
	s_nop 1
	v_permlane16_swap_b32_e32 v168, v170
	v_permlane16_swap_b32_e32 v169, v171
	global_store_dwordx4 v176, v[168:171], s[4:5] offset:0 sc1
	v_mul_f32_e32 v162, 0xbfb8aa3b, v82
	v_mul_f32_e32 v163, 0xbfb8aa3b, v83
	v_mul_f32_e32 v164, 0xbfb8aa3b, v84
	v_mul_f32_e32 v165, 0xbfb8aa3b, v85
	v_exp_f32_e32 v162, v162
	v_exp_f32_e32 v163, v163
	v_exp_f32_e32 v164, v164
	v_exp_f32_e32 v165, v165
	v_add_f32_e32 v162, 1.0, v162
	v_add_f32_e32 v163, 1.0, v163
	v_add_f32_e32 v164, 1.0, v164
	v_add_f32_e32 v165, 1.0, v165
	v_rcp_f32_e32 v162, v162
	v_rcp_f32_e32 v163, v163
	v_rcp_f32_e32 v164, v164
	v_rcp_f32_e32 v165, v165
	v_mul_f32_e32 v162, v82, v162
	v_mul_f32_e32 v163, v83, v163
	v_mul_f32_e32 v164, v84, v164
	v_mul_f32_e32 v165, v85, v165
	v_mul_f32_e32 v162, v90, v162
	v_mul_f32_e32 v163, v91, v163
	v_mul_f32_e32 v164, v92, v164
	v_mul_f32_e32 v165, v93, v165
	v_cvt_pk_bf16_f32 v172, v162, v163
	v_cvt_pk_bf16_f32 v173, v164, v165
	v_mul_f32_e32 v162, 0xbfb8aa3b, v86
	v_mul_f32_e32 v163, 0xbfb8aa3b, v87
	v_mul_f32_e32 v164, 0xbfb8aa3b, v88
	v_mul_f32_e32 v165, 0xbfb8aa3b, v89
	v_exp_f32_e32 v162, v162
	v_exp_f32_e32 v163, v163
	v_exp_f32_e32 v164, v164
	v_exp_f32_e32 v165, v165
	v_add_f32_e32 v162, 1.0, v162
	v_add_f32_e32 v163, 1.0, v163
	v_add_f32_e32 v164, 1.0, v164
	v_add_f32_e32 v165, 1.0, v165
	v_rcp_f32_e32 v162, v162
	v_rcp_f32_e32 v163, v163
	v_rcp_f32_e32 v164, v164
	v_rcp_f32_e32 v165, v165
	v_mul_f32_e32 v162, v86, v162
	v_mul_f32_e32 v163, v87, v163
	v_mul_f32_e32 v164, v88, v164
	v_mul_f32_e32 v165, v89, v165
	v_mul_f32_e32 v162, v94, v162
	v_mul_f32_e32 v163, v95, v163
	v_mul_f32_e32 v164, v96, v164
	v_mul_f32_e32 v165, v97, v165
	v_cvt_pk_bf16_f32 v174, v162, v163
	v_cvt_pk_bf16_f32 v175, v164, v165
	s_nop 1
	v_permlane16_swap_b32_e32 v172, v174
	v_permlane16_swap_b32_e32 v173, v175
	global_store_dwordx4 v176, v[172:175], s[4:5] offset:128 sc1
	v_add_u32_e32 v176, 0x16000, v176
	v_mul_f32_e32 v162, 0xbfb8aa3b, v34
	v_mul_f32_e32 v163, 0xbfb8aa3b, v35
	v_mul_f32_e32 v164, 0xbfb8aa3b, v36
	v_mul_f32_e32 v165, 0xbfb8aa3b, v37
	v_exp_f32_e32 v162, v162
	v_exp_f32_e32 v163, v163
	v_exp_f32_e32 v164, v164
	v_exp_f32_e32 v165, v165
	v_add_f32_e32 v162, 1.0, v162
	v_add_f32_e32 v163, 1.0, v163
	v_add_f32_e32 v164, 1.0, v164
	v_add_f32_e32 v165, 1.0, v165
	v_rcp_f32_e32 v162, v162
	v_rcp_f32_e32 v163, v163
	v_rcp_f32_e32 v164, v164
	v_rcp_f32_e32 v165, v165
	v_mul_f32_e32 v162, v34, v162
	v_mul_f32_e32 v163, v35, v163
	v_mul_f32_e32 v164, v36, v164
	v_mul_f32_e32 v165, v37, v165
	v_mul_f32_e32 v162, v42, v162
	v_mul_f32_e32 v163, v43, v163
	v_mul_f32_e32 v164, v44, v164
	v_mul_f32_e32 v165, v45, v165
	v_cvt_pk_bf16_f32 v168, v162, v163
	v_cvt_pk_bf16_f32 v169, v164, v165
	v_mul_f32_e32 v162, 0xbfb8aa3b, v38
	v_mul_f32_e32 v163, 0xbfb8aa3b, v39
	v_mul_f32_e32 v164, 0xbfb8aa3b, v40
	v_mul_f32_e32 v165, 0xbfb8aa3b, v41
	v_exp_f32_e32 v162, v162
	v_exp_f32_e32 v163, v163
	v_exp_f32_e32 v164, v164
	v_exp_f32_e32 v165, v165
	v_add_f32_e32 v162, 1.0, v162
	v_add_f32_e32 v163, 1.0, v163
	v_add_f32_e32 v164, 1.0, v164
	v_add_f32_e32 v165, 1.0, v165
	v_rcp_f32_e32 v162, v162
	v_rcp_f32_e32 v163, v163
	v_rcp_f32_e32 v164, v164
	v_rcp_f32_e32 v165, v165
	v_mul_f32_e32 v162, v38, v162
	v_mul_f32_e32 v163, v39, v163
	v_mul_f32_e32 v164, v40, v164
	v_mul_f32_e32 v165, v41, v165
	v_mul_f32_e32 v162, v46, v162
	v_mul_f32_e32 v163, v47, v163
	v_mul_f32_e32 v164, v48, v164
	v_mul_f32_e32 v165, v49, v165
	v_cvt_pk_bf16_f32 v170, v162, v163
	v_cvt_pk_bf16_f32 v171, v164, v165
	s_nop 1
	v_permlane16_swap_b32_e32 v168, v170
	v_permlane16_swap_b32_e32 v169, v171
	global_store_dwordx4 v176, v[168:171], s[4:5] offset:0 sc1
	v_mul_f32_e32 v162, 0xbfb8aa3b, v98
	v_mul_f32_e32 v163, 0xbfb8aa3b, v99
	v_mul_f32_e32 v164, 0xbfb8aa3b, v100
	v_mul_f32_e32 v165, 0xbfb8aa3b, v101
	v_exp_f32_e32 v162, v162
	v_exp_f32_e32 v163, v163
	v_exp_f32_e32 v164, v164
	v_exp_f32_e32 v165, v165
	v_add_f32_e32 v162, 1.0, v162
	v_add_f32_e32 v163, 1.0, v163
	v_add_f32_e32 v164, 1.0, v164
	v_add_f32_e32 v165, 1.0, v165
	v_rcp_f32_e32 v162, v162
	v_rcp_f32_e32 v163, v163
	v_rcp_f32_e32 v164, v164
	v_rcp_f32_e32 v165, v165
	v_mul_f32_e32 v162, v98, v162
	v_mul_f32_e32 v163, v99, v163
	v_mul_f32_e32 v164, v100, v164
	v_mul_f32_e32 v165, v101, v165
	v_mul_f32_e32 v162, v106, v162
	v_mul_f32_e32 v163, v107, v163
	v_mul_f32_e32 v164, v108, v164
	v_mul_f32_e32 v165, v109, v165
	v_cvt_pk_bf16_f32 v172, v162, v163
	v_cvt_pk_bf16_f32 v173, v164, v165
	v_mul_f32_e32 v162, 0xbfb8aa3b, v102
	v_mul_f32_e32 v163, 0xbfb8aa3b, v103
	v_mul_f32_e32 v164, 0xbfb8aa3b, v104
	v_mul_f32_e32 v165, 0xbfb8aa3b, v105
	v_exp_f32_e32 v162, v162
	v_exp_f32_e32 v163, v163
	v_exp_f32_e32 v164, v164
	v_exp_f32_e32 v165, v165
	v_add_f32_e32 v162, 1.0, v162
	v_add_f32_e32 v163, 1.0, v163
	v_add_f32_e32 v164, 1.0, v164
	v_add_f32_e32 v165, 1.0, v165
	v_rcp_f32_e32 v162, v162
	v_rcp_f32_e32 v163, v163
	v_rcp_f32_e32 v164, v164
	v_rcp_f32_e32 v165, v165
	v_mul_f32_e32 v162, v102, v162
	v_mul_f32_e32 v163, v103, v163
	v_mul_f32_e32 v164, v104, v164
	v_mul_f32_e32 v165, v105, v165
	v_mul_f32_e32 v162, v110, v162
	v_mul_f32_e32 v163, v111, v163
	v_mul_f32_e32 v164, v112, v164
	v_mul_f32_e32 v165, v113, v165
	v_cvt_pk_bf16_f32 v174, v162, v163
	v_cvt_pk_bf16_f32 v175, v164, v165
	s_nop 1
	v_permlane16_swap_b32_e32 v172, v174
	v_permlane16_swap_b32_e32 v173, v175
	global_store_dwordx4 v176, v[172:175], s[4:5] offset:128 sc1
	v_add_u32_e32 v176, 0x16000, v176
	v_mul_f32_e32 v162, 0xbfb8aa3b, v50
	v_mul_f32_e32 v163, 0xbfb8aa3b, v51
	v_mul_f32_e32 v164, 0xbfb8aa3b, v52
	v_mul_f32_e32 v165, 0xbfb8aa3b, v53
	v_exp_f32_e32 v162, v162
	v_exp_f32_e32 v163, v163
	v_exp_f32_e32 v164, v164
	v_exp_f32_e32 v165, v165
	v_add_f32_e32 v162, 1.0, v162
	v_add_f32_e32 v163, 1.0, v163
	v_add_f32_e32 v164, 1.0, v164
	v_add_f32_e32 v165, 1.0, v165
	v_rcp_f32_e32 v162, v162
	v_rcp_f32_e32 v163, v163
	v_rcp_f32_e32 v164, v164
	v_rcp_f32_e32 v165, v165
	v_mul_f32_e32 v162, v50, v162
	v_mul_f32_e32 v163, v51, v163
	v_mul_f32_e32 v164, v52, v164
	v_mul_f32_e32 v165, v53, v165
	v_mul_f32_e32 v162, v58, v162
	v_mul_f32_e32 v163, v59, v163
	v_mul_f32_e32 v164, v60, v164
	v_mul_f32_e32 v165, v61, v165
	v_cvt_pk_bf16_f32 v168, v162, v163
	v_cvt_pk_bf16_f32 v169, v164, v165
	v_mul_f32_e32 v162, 0xbfb8aa3b, v54
	v_mul_f32_e32 v163, 0xbfb8aa3b, v55
	v_mul_f32_e32 v164, 0xbfb8aa3b, v56
	v_mul_f32_e32 v165, 0xbfb8aa3b, v57
	v_exp_f32_e32 v162, v162
	v_exp_f32_e32 v163, v163
	v_exp_f32_e32 v164, v164
	v_exp_f32_e32 v165, v165
	v_add_f32_e32 v162, 1.0, v162
	v_add_f32_e32 v163, 1.0, v163
	v_add_f32_e32 v164, 1.0, v164
	v_add_f32_e32 v165, 1.0, v165
	v_rcp_f32_e32 v162, v162
	v_rcp_f32_e32 v163, v163
	v_rcp_f32_e32 v164, v164
	v_rcp_f32_e32 v165, v165
	v_mul_f32_e32 v162, v54, v162
	v_mul_f32_e32 v163, v55, v163
	v_mul_f32_e32 v164, v56, v164
	v_mul_f32_e32 v165, v57, v165
	v_mul_f32_e32 v162, v62, v162
	v_mul_f32_e32 v163, v63, v163
	v_mul_f32_e32 v164, v64, v164
	v_mul_f32_e32 v165, v65, v165
	v_cvt_pk_bf16_f32 v170, v162, v163
	v_cvt_pk_bf16_f32 v171, v164, v165
	s_nop 1
	v_permlane16_swap_b32_e32 v168, v170
	v_permlane16_swap_b32_e32 v169, v171
	global_store_dwordx4 v176, v[168:171], s[4:5] offset:0 sc1
	v_mul_f32_e32 v162, 0xbfb8aa3b, v114
	v_mul_f32_e32 v163, 0xbfb8aa3b, v115
	v_mul_f32_e32 v164, 0xbfb8aa3b, v116
	v_mul_f32_e32 v165, 0xbfb8aa3b, v117
	v_exp_f32_e32 v162, v162
	v_exp_f32_e32 v163, v163
	v_exp_f32_e32 v164, v164
	v_exp_f32_e32 v165, v165
	v_add_f32_e32 v162, 1.0, v162
	v_add_f32_e32 v163, 1.0, v163
	v_add_f32_e32 v164, 1.0, v164
	v_add_f32_e32 v165, 1.0, v165
	v_rcp_f32_e32 v162, v162
	v_rcp_f32_e32 v163, v163
	v_rcp_f32_e32 v164, v164
	v_rcp_f32_e32 v165, v165
	v_mul_f32_e32 v162, v114, v162
	v_mul_f32_e32 v163, v115, v163
	v_mul_f32_e32 v164, v116, v164
	v_mul_f32_e32 v165, v117, v165
	v_mul_f32_e32 v162, v122, v162
	v_mul_f32_e32 v163, v123, v163
	v_mul_f32_e32 v164, v124, v164
	v_mul_f32_e32 v165, v125, v165
	v_cvt_pk_bf16_f32 v172, v162, v163
	v_cvt_pk_bf16_f32 v173, v164, v165
	v_mul_f32_e32 v162, 0xbfb8aa3b, v118
	v_mul_f32_e32 v163, 0xbfb8aa3b, v119
	v_mul_f32_e32 v164, 0xbfb8aa3b, v120
	v_mul_f32_e32 v165, 0xbfb8aa3b, v121
	v_exp_f32_e32 v162, v162
	v_exp_f32_e32 v163, v163
	v_exp_f32_e32 v164, v164
	v_exp_f32_e32 v165, v165
	v_add_f32_e32 v162, 1.0, v162
	v_add_f32_e32 v163, 1.0, v163
	v_add_f32_e32 v164, 1.0, v164
	v_add_f32_e32 v165, 1.0, v165
	v_rcp_f32_e32 v162, v162
	v_rcp_f32_e32 v163, v163
	v_rcp_f32_e32 v164, v164
	v_rcp_f32_e32 v165, v165
	v_mul_f32_e32 v162, v118, v162
	v_mul_f32_e32 v163, v119, v163
	v_mul_f32_e32 v164, v120, v164
	v_mul_f32_e32 v165, v121, v165
	v_mul_f32_e32 v162, v126, v162
	v_mul_f32_e32 v163, v127, v163
	v_mul_f32_e32 v164, v128, v164
	v_mul_f32_e32 v165, v129, v165
	v_cvt_pk_bf16_f32 v174, v162, v163
	v_cvt_pk_bf16_f32 v175, v164, v165
	s_nop 1
	v_permlane16_swap_b32_e32 v172, v174
	v_permlane16_swap_b32_e32 v173, v175
	global_store_dwordx4 v176, v[172:175], s[4:5] offset:128 sc1
	s_add_u32 s10, s10, 32
	s_cmp_lt_u32 s10, 64
	s_cbranch_scc1 .Lg2_a_item1
	s_cmp_lt_u32 s15, 8
	s_cbranch_scc0 .Lg2_a_noleft6
	s_lshr_b32 s12, s15, 2
	s_add_u32 s12, s12, 4
	s_mov_b32 s11, 10
	s_and_b32 s16, s15, 3
	s_lshl_b32 s16, s16, 6
	s_and_b32 s17, s14, 3
	s_mul_i32 s17, s17, 6
	s_add_u32 s12, s12, s17
	s_lshl_b32 s12, s12, 8
	s_add_u32 s12, s12, s16
	s_lshr_b32 s17, s14, 2
	s_mul_i32 s17, s17, 22
	s_lshl_b32 s11, s11, 1
	s_add_u32 s11, s11, s17
	s_lshl_b32 s16, s12, 11
	s_add_u32 s0, s24, s16
	s_addc_u32 s1, s25, 0
	s_lshl_b32 s16, s11, 18
	s_add_u32 s2, s40, s16
	s_addc_u32 s3, s41, 0
	s_mul_i32 s16, s12, 0x1600
	s_lshl_b32 s17, s11, 7
	s_add_u32 s16, s16, s17
	s_add_u32 s4, s26, s16
	s_addc_u32 s5, s27, 0
	v_lshrrev_b32_e32 v141, 7, v142
	v_lshlrev_b32_e32 v139, 12, v141
	v_sub_u32_e32 v134, v134, v139
	v_lshl_add_u32 v134, v141, 10, v134
	v_mul_u32_u24_e32 v139, 0x42000, v141
	v_sub_u32_e32 v138, v138, v139
	v_lshrrev_b32_e32 v141, 8, v142
	v_lshlrev_b32_e32 v141, 17, v141
	v_sub_u32_e32 v141, v136, v141
	s_and_b32 s17, s6, 0xfff
	s_add_u32 m0, s17, 0x0
	s_nop 0
	global_load_lds_dwordx4 v141, s[0:1]
	s_add_u32 m0, s6, 0x4000
	s_nop 0
	global_load_lds_dwordx4 v136, s[2:3]
	s_add_u32 m0, s6, 0x6000
	s_nop 0
	global_load_lds_dwordx4 v137, s[2:3]
	s_add_u32 s0, s0, 64
	s_addc_u32 s1, s1, 0
	s_add_u32 s2, s2, 64
	s_addc_u32 s3, s3, 0
	s_add_u32 m0, s17, 0x8000
	s_nop 0
	global_load_lds_dwordx4 v141, s[0:1]
	s_add_u32 m0, s6, 0xc000
	s_nop 0
	global_load_lds_dwordx4 v136, s[2:3]
	s_add_u32 m0, s6, 0xe000
	s_nop 0
	global_load_lds_dwordx4 v137, s[2:3]
	s_add_u32 s0, s0, 64
	s_addc_u32 s1, s1, 0
	s_add_u32 s2, s2, 64
	s_addc_u32 s3, s3, 0
	s_add_u32 m0, s17, 0x10000
	s_nop 0
	global_load_lds_dwordx4 v141, s[0:1]
	s_add_u32 m0, s6, 0x14000
	s_nop 0
	global_load_lds_dwordx4 v136, s[2:3]
	s_add_u32 m0, s6, 0x16000
	s_nop 0
	global_load_lds_dwordx4 v137, s[2:3]
	s_add_u32 s0, s0, 64
	s_addc_u32 s1, s1, 0
	s_add_u32 s2, s2, 64
	s_addc_u32 s3, s3, 0
	v_mov_b32_e32 v2, 0
	v_mov_b32_e32 v3, 0
	v_mov_b32_e32 v4, 0
	v_mov_b32_e32 v5, 0
	v_mov_b32_e32 v6, 0
	v_mov_b32_e32 v7, 0
	v_mov_b32_e32 v8, 0
	v_mov_b32_e32 v9, 0
	v_mov_b32_e32 v10, 0
	v_mov_b32_e32 v11, 0
	v_mov_b32_e32 v12, 0
	v_mov_b32_e32 v13, 0
	v_mov_b32_e32 v14, 0
	v_mov_b32_e32 v15, 0
	v_mov_b32_e32 v16, 0
	v_mov_b32_e32 v17, 0
	v_mov_b32_e32 v66, 0
	v_mov_b32_e32 v67, 0
	v_mov_b32_e32 v68, 0
	v_mov_b32_e32 v69, 0
	v_mov_b32_e32 v70, 0
	v_mov_b32_e32 v71, 0
	v_mov_b32_e32 v72, 0
	v_mov_b32_e32 v73, 0
	v_mov_b32_e32 v74, 0
	v_mov_b32_e32 v75, 0
	v_mov_b32_e32 v76, 0
	v_mov_b32_e32 v77, 0
	v_mov_b32_e32 v78, 0
	v_mov_b32_e32 v79, 0
	v_mov_b32_e32 v80, 0
	v_mov_b32_e32 v81, 0
	s_bitcmp1_b32 s6, 12
	s_cbranch_scc1 .Lg2_a_grpB7
	s_mov_b32 s7, 7

.Lg2_a_kdone8:
	s_nop 7
	s_nop 1
	v_mov_b32_e32 v176, v138
	v_mul_f32_e32 v162, 0xbfb8aa3b, v2
	v_mul_f32_e32 v163, 0xbfb8aa3b, v3
	v_mul_f32_e32 v164, 0xbfb8aa3b, v4
	v_mul_f32_e32 v165, 0xbfb8aa3b, v5
	v_exp_f32_e32 v162, v162
	v_exp_f32_e32 v163, v163
	v_exp_f32_e32 v164, v164
	v_exp_f32_e32 v165, v165
	v_add_f32_e32 v162, 1.0, v162
	v_add_f32_e32 v163, 1.0, v163
	v_add_f32_e32 v164, 1.0, v164
	v_add_f32_e32 v165, 1.0, v165
	v_rcp_f32_e32 v162, v162
	v_rcp_f32_e32 v163, v163
	v_rcp_f32_e32 v164, v164
	v_rcp_f32_e32 v165, v165
	v_mul_f32_e32 v162, v2, v162
	v_mul_f32_e32 v163, v3, v163
	v_mul_f32_e32 v164, v4, v164
	v_mul_f32_e32 v165, v5, v165
	v_mul_f32_e32 v162, v10, v162
	v_mul_f32_e32 v163, v11, v163
	v_mul_f32_e32 v164, v12, v164
	v_mul_f32_e32 v165, v13, v165
	v_cvt_pk_bf16_f32 v168, v162, v163
	v_cvt_pk_bf16_f32 v169, v164, v165
	v_mul_f32_e32 v162, 0xbfb8aa3b, v6
	v_mul_f32_e32 v163, 0xbfb8aa3b, v7
	v_mul_f32_e32 v164, 0xbfb8aa3b, v8
	v_mul_f32_e32 v165, 0xbfb8aa3b, v9
	v_exp_f32_e32 v162, v162
	v_exp_f32_e32 v163, v163
	v_exp_f32_e32 v164, v164
	v_exp_f32_e32 v165, v165
	v_add_f32_e32 v162, 1.0, v162
	v_add_f32_e32 v163, 1.0, v163
	v_add_f32_e32 v164, 1.0, v164
	v_add_f32_e32 v165, 1.0, v165
	v_rcp_f32_e32 v162, v162
	v_rcp_f32_e32 v163, v163
	v_rcp_f32_e32 v164, v164
	v_rcp_f32_e32 v165, v165
	v_mul_f32_e32 v162, v6, v162
	v_mul_f32_e32 v163, v7, v163
	v_mul_f32_e32 v164, v8, v164
	v_mul_f32_e32 v165, v9, v165
	v_mul_f32_e32 v162, v14, v162
	v_mul_f32_e32 v163, v15, v163
	v_mul_f32_e32 v164, v16, v164
	v_mul_f32_e32 v165, v17, v165
	v_cvt_pk_bf16_f32 v170, v162, v163
	v_cvt_pk_bf16_f32 v171, v164, v165
	s_nop 1
	v_permlane16_swap_b32_e32 v168, v170
	v_permlane16_swap_b32_e32 v169, v171
	global_store_dwordx4 v176, v[168:171], s[4:5] offset:0 sc1
	v_mul_f32_e32 v162, 0xbfb8aa3b, v66
	v_mul_f32_e32 v163, 0xbfb8aa3b, v67
	v_mul_f32_e32 v164, 0xbfb8aa3b, v68
	v_mul_f32_e32 v165, 0xbfb8aa3b, v69
	v_exp_f32_e32 v162, v162
	v_exp_f32_e32 v163, v163
	v_exp_f32_e32 v164, v164
	v_exp_f32_e32 v165, v165
	v_add_f32_e32 v162, 1.0, v162
	v_add_f32_e32 v163, 1.0, v163
	v_add_f32_e32 v164, 1.0, v164
	v_add_f32_e32 v165, 1.0, v165
	v_rcp_f32_e32 v162, v162
	v_rcp_f32_e32 v163, v163
	v_rcp_f32_e32 v164, v164
	v_rcp_f32_e32 v165, v165
	v_mul_f32_e32 v162, v66, v162
	v_mul_f32_e32 v163, v67, v163
	v_mul_f32_e32 v164, v68, v164
	v_mul_f32_e32 v165, v69, v165
	v_mul_f32_e32 v162, v74, v162
	v_mul_f32_e32 v163, v75, v163
	v_mul_f32_e32 v164, v76, v164
	v_mul_f32_e32 v165, v77, v165
	v_cvt_pk_bf16_f32 v172, v162, v163
	v_cvt_pk_bf16_f32 v173, v164, v165
	v_mul_f32_e32 v162, 0xbfb8aa3b, v70
	v_mul_f32_e32 v163, 0xbfb8aa3b, v71
	v_mul_f32_e32 v164, 0xbfb8aa3b, v72
	v_mul_f32_e32 v165, 0xbfb8aa3b, v73
	v_exp_f32_e32 v162, v162
	v_exp_f32_e32 v163, v163
	v_exp_f32_e32 v164, v164
	v_exp_f32_e32 v165, v165
	v_add_f32_e32 v162, 1.0, v162
	v_add_f32_e32 v163, 1.0, v163
	v_add_f32_e32 v164, 1.0, v164
	v_add_f32_e32 v165, 1.0, v165
	v_rcp_f32_e32 v162, v162
	v_rcp_f32_e32 v163, v163
	v_rcp_f32_e32 v164, v164
	v_rcp_f32_e32 v165, v165
	v_mul_f32_e32 v162, v70, v162
	v_mul_f32_e32 v163, v71, v163
	v_mul_f32_e32 v164, v72, v164
	v_mul_f32_e32 v165, v73, v165
	v_mul_f32_e32 v162, v78, v162
	v_mul_f32_e32 v163, v79, v163
	v_mul_f32_e32 v164, v80, v164
	v_mul_f32_e32 v165, v81, v165
	v_cvt_pk_bf16_f32 v174, v162, v163
	v_cvt_pk_bf16_f32 v175, v164, v165
	s_nop 1
	v_permlane16_swap_b32_e32 v172, v174
	v_permlane16_swap_b32_e32 v173, v175
	global_store_dwordx4 v176, v[172:175], s[4:5] offset:128 sc1

.LBB0_72:
	v_readlane_b32 s4, v217, 0
	v_readlane_b32 s5, v214, 57
	v_readlane_b32 s38, v217, 1
	v_readlane_b32 s39, v217, 2
	v_lshrrev_b32_e32 v197, 6, v142
	s_sub_u32 s38, s38, 0xd0
	s_subb_u32 s39, s39, 0
	v_readfirstlane_b32 s6, v197
	s_load_dwordx2 s[38:39], s[38:39], 0x40
	v_and_b32_e32 v194, 63, v142
	v_lshlrev_b32_e32 v195, 3, v194
	v_lshlrev_b32_e32 v194, 4, v194
	v_mov_b32_e32 v196, 0x358637bd
	s_lshr_b32 s7, s4, 3
	s_lshl_b32 s7, s7, 3
	s_add_u32 s7, s7, s6
	s_and_b32 s10, s4, 7
	s_mul_i32 s10, s10, 192
	s_add_u32 s11, s7, 0
	s_mul_i32 s12, s11, 43691
	s_lshr_b32 s12, s12, 23
	s_mul_i32 s12, s12, 1344
	s_add_u32 s11, s11, s12
	s_add_u32 s98, s11, s10
	s_add_u32 s11, s7, 256
	s_mul_i32 s12, s11, 43691
	s_lshr_b32 s12, s12, 23
	s_mul_i32 s12, s12, 1344
	s_add_u32 s11, s11, s12
	s_add_u32 s99, s11, s10
	s_add_u32 s11, s7, 512
	s_mul_i32 s12, s11, 43691
	s_lshr_b32 s12, s12, 23
	s_mul_i32 s12, s12, 1344
	s_add_u32 s11, s11, s12
	s_add_u32 s17, s11, s10
	s_waitcnt lgkmcnt(0)
	s_lshl_b32 s11, s98, 12
	s_add_u32 s68, s48, s11
	s_addc_u32 s69, s49, 0
	global_load_dwordx4 v[2:5], v194, s[68:69] offset:0
	global_load_dwordx4 v[6:9], v194, s[68:69] offset:1024
	global_load_dwordx4 v[10:13], v194, s[68:69] offset:2048
	global_load_dwordx4 v[14:17], v194, s[68:69] offset:3072
	s_lshl_b32 s11, s99, 12
	s_add_u32 s70, s48, s11
	s_addc_u32 s71, s49, 0
	global_load_dwordx4 v[18:21], v194, s[70:71] offset:0
	global_load_dwordx4 v[22:25], v194, s[70:71] offset:1024
	global_load_dwordx4 v[26:29], v194, s[70:71] offset:2048
	global_load_dwordx4 v[30:33], v194, s[70:71] offset:3072
	s_lshl_b32 s11, s17, 12
	s_add_u32 s72, s48, s11
	s_addc_u32 s73, s49, 0
	global_load_dwordx4 v[34:37], v194, s[72:73] offset:0
	global_load_dwordx4 v[38:41], v194, s[72:73] offset:1024
	global_load_dwordx4 v[42:45], v194, s[72:73] offset:2048
	global_load_dwordx4 v[46:49], v194, s[72:73] offset:3072
	s_mov_b32 s42, s17
	s_mul_i32 s11, s5, 3
	s_add_u32 s11, s11, 2
	s_lshl_b32 s11, s11, 12
	s_add_u32 s38, s38, s11
	s_addc_u32 s39, s39, 0
	global_load_dwordx4 v[50:53], v194, s[38:39] offset:0
	global_load_dwordx4 v[54:57], v194, s[38:39] offset:1024
	global_load_dwordx4 v[58:61], v194, s[38:39] offset:2048
	global_load_dwordx4 v[62:65], v194, s[38:39] offset:3072
	s_sub_u32 s11, s98, 0x1000
	s_lshr_b32 s11, s11, 10
	s_add_u32 s11, s11, 1
	s_cmp_lt_u32 s98, 0x1000
	s_cselect_b32 s11, 0, s11
	s_mul_i32 s12, s5, 3
	s_add_u32 s11, s11, s12
	s_mul_i32 s11, s11, 0x9000
	s_add_u32 s11, s11, 0x6000
	s_add_u32 s74, s34, s11
	s_addc_u32 s75, s35, 0
	s_add_u32 s80, s74, 0x1000
	s_addc_u32 s81, s75, 0
	global_load_dwordx4 v[66:69], v194, s[74:75] offset:0
	global_load_dwordx4 v[70:73], v194, s[74:75] offset:1024
	global_load_dwordx4 v[74:77], v194, s[74:75] offset:2048
	global_load_dwordx4 v[78:81], v194, s[74:75] offset:3072
	global_load_dwordx4 v[114:117], v194, s[80:81] offset:0
	global_load_dwordx4 v[118:121], v194, s[80:81] offset:1024
	global_load_dwordx4 v[122:125], v194, s[80:81] offset:2048
	global_load_dwordx4 v[126:129], v194, s[80:81] offset:3072
	s_sub_u32 s11, s99, 0x1000
	s_lshr_b32 s11, s11, 10
	s_add_u32 s11, s11, 1
	s_cmp_lt_u32 s99, 0x1000
	s_cselect_b32 s11, 0, s11
	s_mul_i32 s12, s5, 3
	s_add_u32 s11, s11, s12
	s_mul_i32 s11, s11, 0x9000
	s_add_u32 s11, s11, 0x6000
	s_add_u32 s76, s34, s11
	s_addc_u32 s77, s35, 0
	s_add_u32 s82, s76, 0x1000
	s_addc_u32 s83, s77, 0
	global_load_dwordx4 v[82:85], v194, s[76:77] offset:0
	global_load_dwordx4 v[86:89], v194, s[76:77] offset:1024
	global_load_dwordx4 v[90:93], v194, s[76:77] offset:2048
	global_load_dwordx4 v[94:97], v194, s[76:77] offset:3072
	global_load_dwordx4 v[162:165], v194, s[82:83] offset:0
	global_load_dwordx4 v[166:169], v194, s[82:83] offset:1024
	global_load_dwordx4 v[170:173], v194, s[82:83] offset:2048
	global_load_dwordx4 v[174:177], v194, s[82:83] offset:3072
	s_sub_u32 s11, s42, 0x1000
	s_lshr_b32 s11, s11, 10
	s_add_u32 s11, s11, 1
	s_cmp_lt_u32 s42, 0x1000
	s_cselect_b32 s11, 0, s11
	s_mul_i32 s12, s5, 3
	s_add_u32 s11, s11, s12
	s_mul_i32 s11, s11, 0x9000
	s_add_u32 s11, s11, 0x6000
	s_add_u32 s78, s34, s11
	s_addc_u32 s79, s35, 0
	s_add_u32 s92, s78, 0x1000
	s_addc_u32 s93, s79, 0
	global_load_dwordx4 v[98:101], v194, s[78:79] offset:0
	global_load_dwordx4 v[102:105], v194, s[78:79] offset:1024
	global_load_dwordx4 v[106:109], v194, s[78:79] offset:2048
	global_load_dwordx4 v[110:113], v194, s[78:79] offset:3072
	global_load_dwordx4 v[178:181], v194, s[92:93] offset:0
	global_load_dwordx4 v[182:185], v194, s[92:93] offset:1024
	global_load_dwordx4 v[186:189], v194, s[92:93] offset:2048
	global_load_dwordx4 v[190:193], v194, s[92:93] offset:3072
	s_waitcnt vmcnt(28)
	s_lshl_b32 s11, s98, 11
	s_add_u32 s68, s24, s11
	s_addc_u32 s69, s25, 0
	s_lshl_b32 s11, s99, 11
	s_add_u32 s70, s24, s11
	s_addc_u32 s71, s25, 0
	s_lshl_b32 s11, s42, 11
	s_add_u32 s72, s24, s11
	s_addc_u32 s73, s25, 0
	v_mul_f32_e32 v198, v2, v2
	v_mul_f32_e32 v199, v18, v18
	v_mul_f32_e32 v200, v34, v34
	v_fmac_f32_e32 v198, v3, v3
	v_fmac_f32_e32 v199, v19, v19
	v_fmac_f32_e32 v200, v35, v35
	v_fmac_f32_e32 v198, v4, v4
	v_fmac_f32_e32 v199, v20, v20
	v_fmac_f32_e32 v200, v36, v36
	v_fmac_f32_e32 v198, v5, v5
	v_fmac_f32_e32 v199, v21, v21
	v_fmac_f32_e32 v200, v37, v37
	v_fmac_f32_e32 v198, v6, v6
	v_fmac_f32_e32 v199, v22, v22
	v_fmac_f32_e32 v200, v38, v38
	v_fmac_f32_e32 v198, v7, v7
	v_fmac_f32_e32 v199, v23, v23
	v_fmac_f32_e32 v200, v39, v39
	v_fmac_f32_e32 v198, v8, v8
	v_fmac_f32_e32 v199, v24, v24
	v_fmac_f32_e32 v200, v40, v40
	v_fmac_f32_e32 v198, v9, v9
	v_fmac_f32_e32 v199, v25, v25
	v_fmac_f32_e32 v200, v41, v41
	v_fmac_f32_e32 v198, v10, v10
	v_fmac_f32_e32 v199, v26, v26
	v_fmac_f32_e32 v200, v42, v42
	v_fmac_f32_e32 v198, v11, v11
	v_fmac_f32_e32 v199, v27, v27
	v_fmac_f32_e32 v200, v43, v43
	v_fmac_f32_e32 v198, v12, v12
	v_fmac_f32_e32 v199, v28, v28
	v_fmac_f32_e32 v200, v44, v44
	v_fmac_f32_e32 v198, v13, v13
	v_fmac_f32_e32 v199, v29, v29
	v_fmac_f32_e32 v200, v45, v45
	v_fmac_f32_e32 v198, v14, v14
	v_fmac_f32_e32 v199, v30, v30
	v_fmac_f32_e32 v200, v46, v46
	v_fmac_f32_e32 v198, v15, v15
	v_fmac_f32_e32 v199, v31, v31
	v_fmac_f32_e32 v200, v47, v47
	v_fmac_f32_e32 v198, v16, v16
	v_fmac_f32_e32 v199, v32, v32
	v_fmac_f32_e32 v200, v48, v48
	v_fmac_f32_e32 v198, v17, v17
	v_fmac_f32_e32 v199, v33, v33
	v_fmac_f32_e32 v200, v49, v49
	s_nop 1
	v_add_f32_dpp v198, v198, v198 quad_perm:[1,0,3,2] row_mask:0xf bank_mask:0xf
	v_add_f32_dpp v199, v199, v199 quad_perm:[1,0,3,2] row_mask:0xf bank_mask:0xf
	v_add_f32_dpp v200, v200, v200 quad_perm:[1,0,3,2] row_mask:0xf bank_mask:0xf
	s_nop 1
	v_add_f32_dpp v198, v198, v198 quad_perm:[2,3,0,1] row_mask:0xf bank_mask:0xf
	v_add_f32_dpp v199, v199, v199 quad_perm:[2,3,0,1] row_mask:0xf bank_mask:0xf
	v_add_f32_dpp v200, v200, v200 quad_perm:[2,3,0,1] row_mask:0xf bank_mask:0xf
	s_nop 1
	v_add_f32_dpp v198, v198, v198 row_half_mirror row_mask:0xf bank_mask:0xf
	v_add_f32_dpp v199, v199, v199 row_half_mirror row_mask:0xf bank_mask:0xf
	v_add_f32_dpp v200, v200, v200 row_half_mirror row_mask:0xf bank_mask:0xf
	s_nop 1
	v_add_f32_dpp v198, v198, v198 row_mirror row_mask:0xf bank_mask:0xf
	v_add_f32_dpp v199, v199, v199 row_mirror row_mask:0xf bank_mask:0xf
	v_add_f32_dpp v200, v200, v200 row_mirror row_mask:0xf bank_mask:0xf
	s_nop 1
	v_add_f32_dpp v198, v198, v198 row_bcast:15 row_mask:0xa bank_mask:0xf
	v_add_f32_dpp v199, v199, v199 row_bcast:15 row_mask:0xa bank_mask:0xf
	v_add_f32_dpp v200, v200, v200 row_bcast:15 row_mask:0xa bank_mask:0xf
	s_nop 1
	v_add_f32_dpp v198, v198, v198 row_bcast:31 row_mask:0xc bank_mask:0xf
	v_add_f32_dpp v199, v199, v199 row_bcast:31 row_mask:0xc bank_mask:0xf
	v_add_f32_dpp v200, v200, v200 row_bcast:31 row_mask:0xc bank_mask:0xf
	s_nop 1
	v_readlane_b32 s32, v198, 63
	v_readlane_b32 s20, v199, 63
	v_readlane_b32 s94, v200, 63
	s_nop 0
	v_mov_b32_e32 v201, s32
	v_mov_b32_e32 v202, s20
	v_mov_b32_e32 v203, s94
	v_fmamk_f32 v201, v201, 0x3a800000, v196
	v_fmamk_f32 v202, v202, 0x3a800000, v196
	v_fmamk_f32 v203, v203, 0x3a800000, v196
	v_rsq_f32_e32 v201, v201
	v_rsq_f32_e32 v202, v202
	v_rsq_f32_e32 v203, v203
	s_waitcnt vmcnt(0)
	v_mul_f32_e32 v204, v2, v201
	v_mul_f32_e32 v205, v3, v201
	v_mul_f32_e32 v206, v4, v201
	v_mul_f32_e32 v207, v5, v201
	v_mul_f32_e32 v204, v50, v204
	v_mul_f32_e32 v205, v51, v205
	v_mul_f32_e32 v206, v52, v206
	v_mul_f32_e32 v207, v53, v207
	v_add_f32_e32 v114, 1.0, v114
	v_add_f32_e32 v115, 1.0, v115
	v_add_f32_e32 v116, 1.0, v116
	v_add_f32_e32 v117, 1.0, v117
	v_fma_f32 v204, v114, v204, v66
	v_fma_f32 v205, v115, v205, v67
	v_fma_f32 v206, v116, v206, v68
	v_fma_f32 v207, v117, v207, v69
	v_cvt_pk_bf16_f32 v208, v204, v205
	v_cvt_pk_bf16_f32 v209, v206, v207
	global_store_dwordx2 v195, v[208:209], s[68:69] offset:0
	v_mul_f32_e32 v204, v6, v201
	v_mul_f32_e32 v205, v7, v201
	v_mul_f32_e32 v206, v8, v201
	v_mul_f32_e32 v207, v9, v201
	v_mul_f32_e32 v204, v54, v204
	v_mul_f32_e32 v205, v55, v205
	v_mul_f32_e32 v206, v56, v206
	v_mul_f32_e32 v207, v57, v207
	v_add_f32_e32 v118, 1.0, v118
	v_add_f32_e32 v119, 1.0, v119
	v_add_f32_e32 v120, 1.0, v120
	v_add_f32_e32 v121, 1.0, v121
	v_fma_f32 v204, v118, v204, v70
	v_fma_f32 v205, v119, v205, v71
	v_fma_f32 v206, v120, v206, v72
	v_fma_f32 v207, v121, v207, v73
	v_cvt_pk_bf16_f32 v210, v204, v205
	v_cvt_pk_bf16_f32 v211, v206, v207
	global_store_dwordx2 v195, v[210:211], s[68:69] offset:512
	v_mul_f32_e32 v204, v10, v201
	v_mul_f32_e32 v205, v11, v201
	v_mul_f32_e32 v206, v12, v201
	v_mul_f32_e32 v207, v13, v201
	v_mul_f32_e32 v204, v58, v204
	v_mul_f32_e32 v205, v59, v205
	v_mul_f32_e32 v206, v60, v206
	v_mul_f32_e32 v207, v61, v207
	v_add_f32_e32 v122, 1.0, v122
	v_add_f32_e32 v123, 1.0, v123
	v_add_f32_e32 v124, 1.0, v124
	v_add_f32_e32 v125, 1.0, v125
	v_fma_f32 v204, v122, v204, v74
	v_fma_f32 v205, v123, v205, v75
	v_fma_f32 v206, v124, v206, v76
	v_fma_f32 v207, v125, v207, v77
	v_cvt_pk_bf16_f32 v208, v204, v205
	v_cvt_pk_bf16_f32 v209, v206, v207
	global_store_dwordx2 v195, v[208:209], s[68:69] offset:1024
	v_mul_f32_e32 v204, v14, v201
	v_mul_f32_e32 v205, v15, v201
	v_mul_f32_e32 v206, v16, v201
	v_mul_f32_e32 v207, v17, v201
	v_mul_f32_e32 v204, v62, v204
	v_mul_f32_e32 v205, v63, v205
	v_mul_f32_e32 v206, v64, v206
	v_mul_f32_e32 v207, v65, v207
	v_add_f32_e32 v126, 1.0, v126
	v_add_f32_e32 v127, 1.0, v127
	v_add_f32_e32 v128, 1.0, v128
	v_add_f32_e32 v129, 1.0, v129
	v_fma_f32 v204, v126, v204, v78
	v_fma_f32 v205, v127, v205, v79
	v_fma_f32 v206, v128, v206, v80
	v_fma_f32 v207, v129, v207, v81
	v_cvt_pk_bf16_f32 v210, v204, v205
	v_cvt_pk_bf16_f32 v211, v206, v207
	global_store_dwordx2 v195, v[210:211], s[68:69] offset:1536
	v_mul_f32_e32 v204, v18, v202
	v_mul_f32_e32 v205, v19, v202
	v_mul_f32_e32 v206, v20, v202
	v_mul_f32_e32 v207, v21, v202
	v_mul_f32_e32 v204, v50, v204
	v_mul_f32_e32 v205, v51, v205
	v_mul_f32_e32 v206, v52, v206
	v_mul_f32_e32 v207, v53, v207
	v_add_f32_e32 v162, 1.0, v162
	v_add_f32_e32 v163, 1.0, v163
	v_add_f32_e32 v164, 1.0, v164
	v_add_f32_e32 v165, 1.0, v165
	v_fma_f32 v204, v162, v204, v82
	v_fma_f32 v205, v163, v205, v83
	v_fma_f32 v206, v164, v206, v84
	v_fma_f32 v207, v165, v207, v85
	v_cvt_pk_bf16_f32 v208, v204, v205
	v_cvt_pk_bf16_f32 v209, v206, v207
	global_store_dwordx2 v195, v[208:209], s[70:71] offset:0
	v_mul_f32_e32 v204, v22, v202
	v_mul_f32_e32 v205, v23, v202
	v_mul_f32_e32 v206, v24, v202
	v_mul_f32_e32 v207, v25, v202
	v_mul_f32_e32 v204, v54, v204
	v_mul_f32_e32 v205, v55, v205
	v_mul_f32_e32 v206, v56, v206
	v_mul_f32_e32 v207, v57, v207
	v_add_f32_e32 v166, 1.0, v166
	v_add_f32_e32 v167, 1.0, v167
	v_add_f32_e32 v168, 1.0, v168
	v_add_f32_e32 v169, 1.0, v169
	v_fma_f32 v204, v166, v204, v86
	v_fma_f32 v205, v167, v205, v87
	v_fma_f32 v206, v168, v206, v88
	v_fma_f32 v207, v169, v207, v89
	v_cvt_pk_bf16_f32 v210, v204, v205
	v_cvt_pk_bf16_f32 v211, v206, v207
	global_store_dwordx2 v195, v[210:211], s[70:71] offset:512
	v_mul_f32_e32 v204, v26, v202
	v_mul_f32_e32 v205, v27, v202
	v_mul_f32_e32 v206, v28, v202
	v_mul_f32_e32 v207, v29, v202
	v_mul_f32_e32 v204, v58, v204
	v_mul_f32_e32 v205, v59, v205
	v_mul_f32_e32 v206, v60, v206
	v_mul_f32_e32 v207, v61, v207
	v_add_f32_e32 v170, 1.0, v170
	v_add_f32_e32 v171, 1.0, v171
	v_add_f32_e32 v172, 1.0, v172
	v_add_f32_e32 v173, 1.0, v173
	v_fma_f32 v204, v170, v204, v90
	v_fma_f32 v205, v171, v205, v91
	v_fma_f32 v206, v172, v206, v92
	v_fma_f32 v207, v173, v207, v93
	v_cvt_pk_bf16_f32 v208, v204, v205
	v_cvt_pk_bf16_f32 v209, v206, v207
	global_store_dwordx2 v195, v[208:209], s[70:71] offset:1024
	v_mul_f32_e32 v204, v30, v202
	v_mul_f32_e32 v205, v31, v202
	v_mul_f32_e32 v206, v32, v202
	v_mul_f32_e32 v207, v33, v202
	v_mul_f32_e32 v204, v62, v204
	v_mul_f32_e32 v205, v63, v205
	v_mul_f32_e32 v206, v64, v206
	v_mul_f32_e32 v207, v65, v207
	v_add_f32_e32 v174, 1.0, v174
	v_add_f32_e32 v175, 1.0, v175
	v_add_f32_e32 v176, 1.0, v176
	v_add_f32_e32 v177, 1.0, v177
	v_fma_f32 v204, v174, v204, v94
	v_fma_f32 v205, v175, v205, v95
	v_fma_f32 v206, v176, v206, v96
	v_fma_f32 v207, v177, v207, v97
	v_cvt_pk_bf16_f32 v210, v204, v205
	v_cvt_pk_bf16_f32 v211, v206, v207
	global_store_dwordx2 v195, v[210:211], s[70:71] offset:1536
	v_mul_f32_e32 v204, v34, v203
	v_mul_f32_e32 v205, v35, v203
	v_mul_f32_e32 v206, v36, v203
	v_mul_f32_e32 v207, v37, v203
	v_mul_f32_e32 v204, v50, v204
	v_mul_f32_e32 v205, v51, v205
	v_mul_f32_e32 v206, v52, v206
	v_mul_f32_e32 v207, v53, v207
	v_add_f32_e32 v178, 1.0, v178
	v_add_f32_e32 v179, 1.0, v179
	v_add_f32_e32 v180, 1.0, v180
	v_add_f32_e32 v181, 1.0, v181
	v_fma_f32 v204, v178, v204, v98
	v_fma_f32 v205, v179, v205, v99
	v_fma_f32 v206, v180, v206, v100
	v_fma_f32 v207, v181, v207, v101
	v_cvt_pk_bf16_f32 v208, v204, v205
	v_cvt_pk_bf16_f32 v209, v206, v207
	global_store_dwordx2 v195, v[208:209], s[72:73] offset:0
	v_mul_f32_e32 v204, v38, v203
	v_mul_f32_e32 v205, v39, v203
	v_mul_f32_e32 v206, v40, v203
	v_mul_f32_e32 v207, v41, v203
	v_mul_f32_e32 v204, v54, v204
	v_mul_f32_e32 v205, v55, v205
	v_mul_f32_e32 v206, v56, v206
	v_mul_f32_e32 v207, v57, v207
	v_add_f32_e32 v182, 1.0, v182
	v_add_f32_e32 v183, 1.0, v183
	v_add_f32_e32 v184, 1.0, v184
	v_add_f32_e32 v185, 1.0, v185
	v_fma_f32 v204, v182, v204, v102
	v_fma_f32 v205, v183, v205, v103
	v_fma_f32 v206, v184, v206, v104
	v_fma_f32 v207, v185, v207, v105
	v_cvt_pk_bf16_f32 v210, v204, v205
	v_cvt_pk_bf16_f32 v211, v206, v207
	global_store_dwordx2 v195, v[210:211], s[72:73] offset:512
	v_mul_f32_e32 v204, v42, v203
	v_mul_f32_e32 v205, v43, v203
	v_mul_f32_e32 v206, v44, v203
	v_mul_f32_e32 v207, v45, v203
	v_mul_f32_e32 v204, v58, v204
	v_mul_f32_e32 v205, v59, v205
	v_mul_f32_e32 v206, v60, v206
	v_mul_f32_e32 v207, v61, v207
	v_add_f32_e32 v186, 1.0, v186
	v_add_f32_e32 v187, 1.0, v187
	v_add_f32_e32 v188, 1.0, v188
	v_add_f32_e32 v189, 1.0, v189
	v_fma_f32 v204, v186, v204, v106
	v_fma_f32 v205, v187, v205, v107
	v_fma_f32 v206, v188, v206, v108
	v_fma_f32 v207, v189, v207, v109
	v_cvt_pk_bf16_f32 v208, v204, v205
	v_cvt_pk_bf16_f32 v209, v206, v207
	global_store_dwordx2 v195, v[208:209], s[72:73] offset:1024
	v_mul_f32_e32 v204, v46, v203
	v_mul_f32_e32 v205, v47, v203
	v_mul_f32_e32 v206, v48, v203
	v_mul_f32_e32 v207, v49, v203
	v_mul_f32_e32 v204, v62, v204
	v_mul_f32_e32 v205, v63, v205
	v_mul_f32_e32 v206, v64, v206
	v_mul_f32_e32 v207, v65, v207
	v_add_f32_e32 v190, 1.0, v190
	v_add_f32_e32 v191, 1.0, v191
	v_add_f32_e32 v192, 1.0, v192
	v_add_f32_e32 v193, 1.0, v193
	v_fma_f32 v204, v190, v204, v110
	v_fma_f32 v205, v191, v205, v111
	v_fma_f32 v206, v192, v206, v112
	v_fma_f32 v207, v193, v207, v113
	v_cvt_pk_bf16_f32 v210, v204, v205
	v_cvt_pk_bf16_f32 v211, v206, v207
	global_store_dwordx2 v195, v[210:211], s[72:73] offset:1536
	s_branch .LBB0_96

.LBB0_100:
	s_waitcnt vmcnt(5)
	s_barrier
	s_mul_i32 s8, s3, 0xc000
	v_add_u32_e32 v63, s8, v60
	v_add_u32_e32 v66, 0x2000, v63
	v_readfirstlane_b32 s8, v63
	v_lshl_add_u64 v[64:65], v[58:59], 0, s[6:7]
	s_mov_b32 m0, s8
	v_readfirstlane_b32 s8, v66
	v_add_u32_e32 v66, 0x4000, v63
	global_load_lds_dwordx4 v[64:65], off
	v_lshl_add_u64 v[64:65], v[56:57], 0, s[6:7]
	s_mov_b32 m0, s8
	v_readfirstlane_b32 s8, v66
	v_add_u32_e32 v66, 0x8000, v63
	global_load_lds_dwordx4 v[64:65], off
	v_lshl_add_u64 v[64:65], v[54:55], 0, s[6:7]
	s_mov_b32 m0, s8
	v_readfirstlane_b32 s8, v66
	v_add_u32_e32 v63, 0xa000, v63
	global_load_lds_dwordx4 v[64:65], off
	v_lshl_add_u64 v[64:65], v[52:53], 0, s[6:7]
	s_mov_b32 m0, s8
	v_readfirstlane_b32 s8, v63
	global_load_lds_dwordx4 v[64:65], off
	v_lshl_add_u64 v[64:65], v[50:51], 0, s[6:7]
	s_mov_b32 m0, s8
	s_mul_i32 s8, s5, 0xc000
	global_load_lds_dwordx4 v[64:65], off
	v_add_u32_e32 v63, s8, v62
	ds_read_b128 v[64:67], v63 offset:0
	ds_read_b128 v[68:71], v63 offset:2048
	ds_read_b128 v[72:75], v63 offset:4096
	v_add_u32_e32 v116, s8, v61
	ds_read_b128 v[76:79], v116 offset:0
	ds_read_b128 v[80:83], v116 offset:2048
	ds_read_b128 v[84:87], v116 offset:4096
	ds_read_b128 v[88:91], v116 offset:6144
	ds_read_b128 v[92:95], v63 offset:1024
	ds_read_b128 v[96:99], v63 offset:3072
	ds_read_b128 v[100:103], v63 offset:5120
	ds_read_b128 v[104:107], v116 offset:1024
	ds_read_b128 v[108:111], v116 offset:3072
	ds_read_b128 v[112:115], v116 offset:5120
	ds_read_b128 v[116:119], v116 offset:7168
	s_waitcnt lgkmcnt(7)
	s_nop 0
	v_mfma_f32_16x16x32_bf16 v[46:49], v[76:79], v[64:67], v[46:49]
	v_mfma_f32_16x16x32_bf16 v[42:45], v[80:83], v[64:67], v[42:45]
	v_mfma_f32_16x16x32_bf16 v[38:41], v[84:87], v[64:67], v[38:41]
	v_mfma_f32_16x16x32_bf16 v[34:37], v[88:91], v[64:67], v[34:37]
	v_mfma_f32_16x16x32_bf16 v[30:33], v[76:79], v[68:71], v[30:33]
	v_mfma_f32_16x16x32_bf16 v[26:29], v[80:83], v[68:71], v[26:29]
	v_mfma_f32_16x16x32_bf16 v[22:25], v[84:87], v[68:71], v[22:25]
	v_mfma_f32_16x16x32_bf16 v[18:21], v[88:91], v[68:71], v[18:21]
	v_mfma_f32_16x16x32_bf16 v[14:17], v[76:79], v[72:75], v[14:17]
	v_mfma_f32_16x16x32_bf16 v[10:13], v[80:83], v[72:75], v[10:13]
	v_mfma_f32_16x16x32_bf16 v[6:9], v[84:87], v[72:75], v[6:9]
	v_mfma_f32_16x16x32_bf16 v[2:5], v[88:91], v[72:75], v[2:5]
	s_waitcnt lgkmcnt(0)
	v_mfma_f32_16x16x32_bf16 v[46:49], v[104:107], v[92:95], v[46:49]
	v_mfma_f32_16x16x32_bf16 v[42:45], v[108:111], v[92:95], v[42:45]
	v_mfma_f32_16x16x32_bf16 v[38:41], v[112:115], v[92:95], v[38:41]
	v_mfma_f32_16x16x32_bf16 v[34:37], v[116:119], v[92:95], v[34:37]
	v_mfma_f32_16x16x32_bf16 v[30:33], v[104:107], v[96:99], v[30:33]
	v_mfma_f32_16x16x32_bf16 v[26:29], v[108:111], v[96:99], v[26:29]
	v_mfma_f32_16x16x32_bf16 v[22:25], v[112:115], v[96:99], v[22:25]
	v_mfma_f32_16x16x32_bf16 v[18:21], v[116:119], v[96:99], v[18:21]
	v_mfma_f32_16x16x32_bf16 v[14:17], v[104:107], v[100:103], v[14:17]
	v_mfma_f32_16x16x32_bf16 v[10:13], v[108:111], v[100:103], v[10:13]
	v_mfma_f32_16x16x32_bf16 v[6:9], v[112:115], v[100:103], v[6:9]
	v_mfma_f32_16x16x32_bf16 v[2:5], v[116:119], v[100:103], v[2:5]
	s_add_i32 s8, s5, 1
	s_cmp_lg_u32 s5, 2
	s_cselect_b32 s5, s8, 0
	s_add_i32 s8, s3, 1
	s_cmp_lg_u32 s3, 2
	s_cselect_b32 s3, s8, 0
	s_add_u32 s6, s6, 0x80
	s_addc_u32 s7, s7, 0
	s_cmpk_lg_i32 s6, 0x700
	s_cbranch_scc1 .LBB0_100
	s_waitcnt vmcnt(5)
	s_barrier
	v_add_u32_e32 v58, 0x18000, v62
	ds_read_b128 v[50:53], v58 offset:0
	ds_read_b128 v[54:57], v58 offset:2048
	ds_read_b128 v[64:67], v58 offset:4096
	v_add_u32_e32 v59, 0x18000, v61
	ds_read_b128 v[68:71], v59 offset:0
	ds_read_b128 v[72:75], v59 offset:2048
	ds_read_b128 v[76:79], v59 offset:4096
	ds_read_b128 v[80:83], v59 offset:6144
	ds_read_b128 v[84:87], v58 offset:1024
	ds_read_b128 v[88:91], v58 offset:3072
	ds_read_b128 v[92:95], v58 offset:5120
	ds_read_b128 v[96:99], v59 offset:1024
	ds_read_b128 v[100:103], v59 offset:3072
	ds_read_b128 v[104:107], v59 offset:5120
	ds_read_b128 v[108:111], v59 offset:7168
	v_and_b32_e32 v112, 64, v0
	s_waitcnt lgkmcnt(7)
	v_mfma_f32_16x16x32_bf16 v[46:49], v[68:71], v[50:53], v[46:49]
	v_mfma_f32_16x16x32_bf16 v[42:45], v[72:75], v[50:53], v[42:45]
	v_mfma_f32_16x16x32_bf16 v[38:41], v[76:79], v[50:53], v[38:41]
	v_mfma_f32_16x16x32_bf16 v[34:37], v[80:83], v[50:53], v[34:37]
	v_mfma_f32_16x16x32_bf16 v[30:33], v[68:71], v[54:57], v[30:33]
	v_mfma_f32_16x16x32_bf16 v[26:29], v[72:75], v[54:57], v[26:29]
	v_mfma_f32_16x16x32_bf16 v[22:25], v[76:79], v[54:57], v[22:25]
	v_mfma_f32_16x16x32_bf16 v[18:21], v[80:83], v[54:57], v[18:21]
	v_mfma_f32_16x16x32_bf16 v[14:17], v[68:71], v[64:67], v[14:17]
	v_mfma_f32_16x16x32_bf16 v[10:13], v[72:75], v[64:67], v[10:13]
	v_mfma_f32_16x16x32_bf16 v[6:9], v[76:79], v[64:67], v[6:9]
	v_mfma_f32_16x16x32_bf16 v[2:5], v[80:83], v[64:67], v[2:5]
	s_waitcnt lgkmcnt(0)
	v_mfma_f32_16x16x32_bf16 v[46:49], v[96:99], v[84:87], v[46:49]
	v_mfma_f32_16x16x32_bf16 v[42:45], v[100:103], v[84:87], v[42:45]
	v_mfma_f32_16x16x32_bf16 v[38:41], v[104:107], v[84:87], v[38:41]
	v_mfma_f32_16x16x32_bf16 v[34:37], v[108:111], v[84:87], v[34:37]
	v_mfma_f32_16x16x32_bf16 v[30:33], v[96:99], v[88:91], v[30:33]
	v_mfma_f32_16x16x32_bf16 v[26:29], v[100:103], v[88:91], v[26:29]
	v_mfma_f32_16x16x32_bf16 v[22:25], v[104:107], v[88:91], v[22:25]
	v_mfma_f32_16x16x32_bf16 v[18:21], v[108:111], v[88:91], v[18:21]
	v_mfma_f32_16x16x32_bf16 v[14:17], v[96:99], v[92:95], v[14:17]
	v_mfma_f32_16x16x32_bf16 v[10:13], v[100:103], v[92:95], v[10:13]
	v_mfma_f32_16x16x32_bf16 v[6:9], v[104:107], v[92:95], v[6:9]
	v_mfma_f32_16x16x32_bf16 v[2:5], v[108:111], v[92:95], v[2:5]
	s_waitcnt vmcnt(0)
	v_ashrrev_i32_e32 v108, 7, v0
	s_barrier
	ds_read_b128 v[50:53], v62 offset:0
	ds_read_b128 v[54:57], v62 offset:2048
	ds_read_b128 v[64:67], v62 offset:4096
	ds_read_b128 v[68:71], v61 offset:0
	ds_read_b128 v[72:75], v61 offset:2048
	ds_read_b128 v[76:79], v61 offset:4096
	ds_read_b128 v[80:83], v61 offset:6144
	ds_read_b128 v[84:87], v62 offset:1024
	ds_read_b128 v[88:91], v62 offset:3072
	ds_read_b128 v[92:95], v62 offset:5120
	ds_read_b128 v[96:99], v61 offset:1024
	ds_read_b128 v[100:103], v61 offset:3072
	ds_read_b128 v[104:107], v61 offset:5120
	ds_read_b128 v[58:61], v61 offset:7168
	s_waitcnt lgkmcnt(7)
	s_nop 0
	v_mfma_f32_16x16x32_bf16 v[46:49], v[68:71], v[50:53], v[46:49]
	v_mfma_f32_16x16x32_bf16 v[42:45], v[72:75], v[50:53], v[42:45]
	v_mfma_f32_16x16x32_bf16 v[38:41], v[76:79], v[50:53], v[38:41]
	v_mfma_f32_16x16x32_bf16 v[34:37], v[80:83], v[50:53], v[34:37]
	v_mfma_f32_16x16x32_bf16 v[30:33], v[68:71], v[54:57], v[30:33]
	v_mfma_f32_16x16x32_bf16 v[26:29], v[72:75], v[54:57], v[26:29]
	v_mfma_f32_16x16x32_bf16 v[22:25], v[76:79], v[54:57], v[22:25]
	v_mfma_f32_16x16x32_bf16 v[18:21], v[80:83], v[54:57], v[18:21]
	v_mfma_f32_16x16x32_bf16 v[14:17], v[68:71], v[64:67], v[14:17]
	v_mfma_f32_16x16x32_bf16 v[10:13], v[72:75], v[64:67], v[10:13]
	v_mfma_f32_16x16x32_bf16 v[6:9], v[76:79], v[64:67], v[6:9]
	v_mfma_f32_16x16x32_bf16 v[2:5], v[80:83], v[64:67], v[2:5]
	s_waitcnt lgkmcnt(0)
	v_mfma_f32_16x16x32_bf16 v[46:49], v[96:99], v[84:87], v[46:49]
	v_mfma_f32_16x16x32_bf16 v[42:45], v[100:103], v[84:87], v[42:45]
	v_mfma_f32_16x16x32_bf16 v[50:53], v[104:107], v[84:87], v[38:41]
	v_mfma_f32_16x16x32_bf16 v[54:57], v[58:61], v[84:87], v[34:37]
	v_mfma_f32_16x16x32_bf16 v[62:65], v[96:99], v[88:91], v[30:33]
	v_mfma_f32_16x16x32_bf16 v[66:69], v[100:103], v[88:91], v[26:29]
	v_mfma_f32_16x16x32_bf16 v[22:25], v[104:107], v[88:91], v[22:25]
	v_mfma_f32_16x16x32_bf16 v[18:21], v[58:61], v[88:91], v[18:21]
	v_mfma_f32_16x16x32_bf16 v[14:17], v[96:99], v[92:95], v[14:17]
	v_mfma_f32_16x16x32_bf16 v[10:13], v[100:103], v[92:95], v[10:13]
	v_mfma_f32_16x16x32_bf16 v[6:9], v[104:107], v[92:95], v[6:9]
	v_mfma_f32_16x16x32_bf16 v[2:5], v[58:61], v[92:95], v[2:5]
	s_nop 7
	v_readlane_b32 s68, v214, 57
	s_and_b32 s2, s17, 31
	s_mul_i32 s2, s2, 192
	s_lshr_b32 s3, s17, 5
	s_lshl_b32 s3, s3, 7
	s_mul_i32 s10, s68, 0x1b000
	s_add_u32 s10, s10, 0x5000
	s_add_u32 s38, s34, s10
	s_addc_u32 s39, s35, 0
	v_lshrrev_b32_e32 v128, 6, v142
	v_and_b32_e32 v129, 1, v128
	v_lshrrev_b32_e32 v128, 1, v128
	v_lshlrev_b32_e32 v70, 6, v129
	v_lshrrev_b32_e32 v129, 4, v142
	v_and_b32_e32 v129, 3, v129
	v_lshl_add_u32 v70, v129, 2, v70
	v_add_u32_e32 v70, s3, v70
	v_lshlrev_b32_e32 v70, 2, v70
	v_mul_u32_u24_e32 v71, 48, v128
	v_and_b32_e32 v129, 15, v142
	v_add3_u32 v71, v71, v129, s2
	v_add_u32_e32 v128, 0, v71
	v_lshl_add_u32 v141, v128, 12, v70
	v_add_u32_e32 v129, 0xfffff000, v128
	v_lshrrev_b32_e32 v129, 10, v129
	v_add_u32_e32 v129, 1, v129
	v_cmp_gt_u32_e32 vcc, 0x1000, v128
	v_cndmask_b32_e64 v129, v129, 0, vcc
	v_mul_u32_u24_e32 v129, 0x9000, v129
	v_add_u32_e32 v134, v129, v70
	global_load_dwordx4 v[72:75], v134, s[38:39] offset:0
	global_load_dwordx4 v[76:79], v134, s[38:39] offset:64
	global_load_dwordx4 v[80:83], v134, s[38:39] offset:128
	global_load_dwordx4 v[84:87], v134, s[38:39] offset:192
	v_add_u32_e32 v128, 16, v71
	v_lshl_add_u32 v162, v128, 12, v70
	v_add_u32_e32 v129, 0xfffff000, v128
	v_lshrrev_b32_e32 v129, 10, v129
	v_add_u32_e32 v129, 1, v129
	v_cmp_gt_u32_e32 vcc, 0x1000, v128
	v_cndmask_b32_e64 v129, v129, 0, vcc
	v_mul_u32_u24_e32 v129, 0x9000, v129
	v_add_u32_e32 v135, v129, v70
	global_load_dwordx4 v[88:91], v135, s[38:39] offset:0
	global_load_dwordx4 v[92:95], v135, s[38:39] offset:64
	global_load_dwordx4 v[96:99], v135, s[38:39] offset:128
	global_load_dwordx4 v[100:103], v135, s[38:39] offset:192
	v_add_u32_e32 v128, 32, v71
	v_lshl_add_u32 v163, v128, 12, v70
	v_add_u32_e32 v129, 0xfffff000, v128
	v_lshrrev_b32_e32 v129, 10, v129
	v_add_u32_e32 v129, 1, v129
	v_cmp_gt_u32_e32 vcc, 0x1000, v128
	v_cndmask_b32_e64 v129, v129, 0, vcc
	v_mul_u32_u24_e32 v129, 0x9000, v129
	v_add_u32_e32 v140, v129, v70
	global_load_dwordx4 v[104:107], v140, s[38:39] offset:0
	global_load_dwordx4 v[108:111], v140, s[38:39] offset:64
	global_load_dwordx4 v[112:115], v140, s[38:39] offset:128
	global_load_dwordx4 v[116:119], v140, s[38:39] offset:192
	global_load_dwordx4 v[120:123], v141, s[48:49] offset:0
	global_load_dwordx4 v[124:127], v141, s[48:49] offset:64
	global_load_dwordx4 v[136:139], v141, s[48:49] offset:128
	global_load_dwordx4 v[164:167], v141, s[48:49] offset:192
	global_load_dwordx4 v[168:171], v162, s[48:49] offset:0
	global_load_dwordx4 v[172:175], v162, s[48:49] offset:64
	global_load_dwordx4 v[176:179], v162, s[48:49] offset:128
	global_load_dwordx4 v[180:183], v162, s[48:49] offset:192
	global_load_dwordx4 v[184:187], v163, s[48:49] offset:0
	global_load_dwordx4 v[188:191], v163, s[48:49] offset:64
	global_load_dwordx4 v[192:195], v163, s[48:49] offset:128
	global_load_dwordx4 v[196:199], v163, s[48:49] offset:192
	s_waitcnt vmcnt(0)
	v_fma_f32 v120, v46, v72, v120
	v_fma_f32 v121, v47, v73, v121
	v_fma_f32 v122, v48, v74, v122
	v_fma_f32 v123, v49, v75, v123
	global_store_dwordx4 v141, v[120:123], s[48:49] offset:0
	v_fma_f32 v124, v42, v76, v124
	v_fma_f32 v125, v43, v77, v125
	v_fma_f32 v126, v44, v78, v126
	v_fma_f32 v127, v45, v79, v127
	global_store_dwordx4 v141, v[124:127], s[48:49] offset:64
	v_fma_f32 v136, v50, v80, v136
	v_fma_f32 v137, v51, v81, v137
	v_fma_f32 v138, v52, v82, v138
	v_fma_f32 v139, v53, v83, v139
	global_store_dwordx4 v141, v[136:139], s[48:49] offset:128
	v_fma_f32 v164, v54, v84, v164
	v_fma_f32 v165, v55, v85, v165
	v_fma_f32 v166, v56, v86, v166
	v_fma_f32 v167, v57, v87, v167
	global_store_dwordx4 v141, v[164:167], s[48:49] offset:192
	v_fma_f32 v168, v62, v88, v168
	v_fma_f32 v169, v63, v89, v169
	v_fma_f32 v170, v64, v90, v170
	v_fma_f32 v171, v65, v91, v171
	global_store_dwordx4 v162, v[168:171], s[48:49] offset:0
	v_fma_f32 v172, v66, v92, v172
	v_fma_f32 v173, v67, v93, v173
	v_fma_f32 v174, v68, v94, v174
	v_fma_f32 v175, v69, v95, v175
	global_store_dwordx4 v162, v[172:175], s[48:49] offset:64
	v_fma_f32 v176, v22, v96, v176
	v_fma_f32 v177, v23, v97, v177
	v_fma_f32 v178, v24, v98, v178
	v_fma_f32 v179, v25, v99, v179
	global_store_dwordx4 v162, v[176:179], s[48:49] offset:128
	v_fma_f32 v180, v18, v100, v180
	v_fma_f32 v181, v19, v101, v181
	v_fma_f32 v182, v20, v102, v182
	v_fma_f32 v183, v21, v103, v183
	global_store_dwordx4 v162, v[180:183], s[48:49] offset:192
	v_fma_f32 v184, v14, v104, v184
	v_fma_f32 v185, v15, v105, v185
	v_fma_f32 v186, v16, v106, v186
	v_fma_f32 v187, v17, v107, v187
	global_store_dwordx4 v163, v[184:187], s[48:49] offset:0
	v_fma_f32 v188, v10, v108, v188
	v_fma_f32 v189, v11, v109, v189
	v_fma_f32 v190, v12, v110, v190
	v_fma_f32 v191, v13, v111, v191
	global_store_dwordx4 v163, v[188:191], s[48:49] offset:64
	v_fma_f32 v192, v6, v112, v192
	v_fma_f32 v193, v7, v113, v193
	v_fma_f32 v194, v8, v114, v194
	v_fma_f32 v195, v9, v115, v195
	global_store_dwordx4 v163, v[192:195], s[48:49] offset:128
	v_fma_f32 v196, v2, v116, v196
	v_fma_f32 v197, v3, v117, v197
	v_fma_f32 v198, v4, v118, v198
	v_fma_f32 v199, v5, v119, v199
	global_store_dwordx4 v163, v[196:199], s[48:49] offset:192
	s_add_i32 s17, s17, s84
	s_cmpk_gt_i32 s17, 0xff
	s_cbranch_scc0 .LBB0_99

.LBB0_372:
	s_andn2_b64 vcc, exec, s[0:1]
	s_cbranch_vccnz .LBB0_397
	v_readlane_b32 s4, v217, 0
	v_readlane_b32 s5, v214, 57
	v_readlane_b32 s38, v217, 1
	v_readlane_b32 s39, v217, 2
	v_lshrrev_b32_e32 v197, 6, v142
	s_sub_u32 s38, s38, 0xd0
	s_subb_u32 s39, s39, 0
	v_readfirstlane_b32 s6, v197
	s_load_dwordx2 s[38:39], s[38:39], 0x40
	v_and_b32_e32 v194, 63, v142
	v_lshlrev_b32_e32 v195, 3, v194
	v_lshlrev_b32_e32 v194, 4, v194
	v_mov_b32_e32 v196, 0x358637bd
	s_lshr_b32 s7, s4, 3
	s_lshl_b32 s7, s7, 3
	s_add_u32 s7, s7, s6
	s_and_b32 s10, s4, 7
	s_mul_i32 s10, s10, 192
	s_add_u32 s11, s7, 0
	s_mul_i32 s12, s11, 43691
	s_lshr_b32 s12, s12, 23
	s_mul_i32 s12, s12, 1344
	s_add_u32 s11, s11, s12
	s_add_u32 s98, s11, s10
	s_add_u32 s11, s7, 256
	s_mul_i32 s12, s11, 43691
	s_lshr_b32 s12, s12, 23
	s_mul_i32 s12, s12, 1344
	s_add_u32 s11, s11, s12
	s_add_u32 s99, s11, s10
	s_add_u32 s11, s7, 512
	s_mul_i32 s12, s11, 43691
	s_lshr_b32 s12, s12, 23
	s_mul_i32 s12, s12, 1344
	s_add_u32 s11, s11, s12
	s_add_u32 s17, s11, s10
	s_waitcnt lgkmcnt(0)
	s_lshl_b32 s11, s98, 12
	s_add_u32 s68, s48, s11
	s_addc_u32 s69, s49, 0
	global_load_dwordx4 v[2:5], v194, s[68:69] offset:0
	global_load_dwordx4 v[6:9], v194, s[68:69] offset:1024
	global_load_dwordx4 v[10:13], v194, s[68:69] offset:2048
	global_load_dwordx4 v[14:17], v194, s[68:69] offset:3072
	s_lshl_b32 s11, s99, 12
	s_add_u32 s70, s48, s11
	s_addc_u32 s71, s49, 0
	global_load_dwordx4 v[18:21], v194, s[70:71] offset:0
	global_load_dwordx4 v[22:25], v194, s[70:71] offset:1024
	global_load_dwordx4 v[26:29], v194, s[70:71] offset:2048
	global_load_dwordx4 v[30:33], v194, s[70:71] offset:3072
	s_lshl_b32 s11, s17, 12
	s_add_u32 s72, s48, s11
	s_addc_u32 s73, s49, 0
	global_load_dwordx4 v[34:37], v194, s[72:73] offset:0
	global_load_dwordx4 v[38:41], v194, s[72:73] offset:1024
	global_load_dwordx4 v[42:45], v194, s[72:73] offset:2048
	global_load_dwordx4 v[46:49], v194, s[72:73] offset:3072
	s_mov_b32 s42, s17
	s_mul_i32 s11, s5, 3
	s_add_u32 s11, s11, 1
	s_lshl_b32 s11, s11, 12
	s_add_u32 s38, s38, s11
	s_addc_u32 s39, s39, 0
	global_load_dwordx4 v[50:53], v194, s[38:39] offset:0
	global_load_dwordx4 v[54:57], v194, s[38:39] offset:1024
	global_load_dwordx4 v[58:61], v194, s[38:39] offset:2048
	global_load_dwordx4 v[62:65], v194, s[38:39] offset:3072
	s_sub_u32 s11, s98, 0x1000
	s_lshr_b32 s11, s11, 10
	s_add_u32 s11, s11, 1
	s_cmp_lt_u32 s98, 0x1000
	s_cselect_b32 s11, 0, s11
	s_mul_i32 s12, s5, 3
	s_add_u32 s11, s11, s12
	s_mul_i32 s11, s11, 0x9000
	s_add_u32 s11, s11, 0x3000
	s_add_u32 s74, s34, s11
	s_addc_u32 s75, s35, 0
	s_add_u32 s80, s74, 0x1000
	s_addc_u32 s81, s75, 0
	global_load_dwordx4 v[66:69], v194, s[74:75] offset:0
	global_load_dwordx4 v[70:73], v194, s[74:75] offset:1024
	global_load_dwordx4 v[74:77], v194, s[74:75] offset:2048
	global_load_dwordx4 v[78:81], v194, s[74:75] offset:3072
	global_load_dwordx4 v[114:117], v194, s[80:81] offset:0
	global_load_dwordx4 v[118:121], v194, s[80:81] offset:1024
	global_load_dwordx4 v[122:125], v194, s[80:81] offset:2048
	global_load_dwordx4 v[126:129], v194, s[80:81] offset:3072
	s_sub_u32 s11, s99, 0x1000
	s_lshr_b32 s11, s11, 10
	s_add_u32 s11, s11, 1
	s_cmp_lt_u32 s99, 0x1000
	s_cselect_b32 s11, 0, s11
	s_mul_i32 s12, s5, 3
	s_add_u32 s11, s11, s12
	s_mul_i32 s11, s11, 0x9000
	s_add_u32 s11, s11, 0x3000
	s_add_u32 s76, s34, s11
	s_addc_u32 s77, s35, 0
	s_add_u32 s82, s76, 0x1000
	s_addc_u32 s83, s77, 0
	global_load_dwordx4 v[82:85], v194, s[76:77] offset:0
	global_load_dwordx4 v[86:89], v194, s[76:77] offset:1024
	global_load_dwordx4 v[90:93], v194, s[76:77] offset:2048
	global_load_dwordx4 v[94:97], v194, s[76:77] offset:3072
	global_load_dwordx4 v[162:165], v194, s[82:83] offset:0
	global_load_dwordx4 v[166:169], v194, s[82:83] offset:1024
	global_load_dwordx4 v[170:173], v194, s[82:83] offset:2048
	global_load_dwordx4 v[174:177], v194, s[82:83] offset:3072
	s_sub_u32 s11, s42, 0x1000
	s_lshr_b32 s11, s11, 10
	s_add_u32 s11, s11, 1
	s_cmp_lt_u32 s42, 0x1000
	s_cselect_b32 s11, 0, s11
	s_mul_i32 s12, s5, 3
	s_add_u32 s11, s11, s12
	s_mul_i32 s11, s11, 0x9000
	s_add_u32 s11, s11, 0x3000
	s_add_u32 s78, s34, s11
	s_addc_u32 s79, s35, 0
	s_add_u32 s92, s78, 0x1000
	s_addc_u32 s93, s79, 0
	global_load_dwordx4 v[98:101], v194, s[78:79] offset:0
	global_load_dwordx4 v[102:105], v194, s[78:79] offset:1024
	global_load_dwordx4 v[106:109], v194, s[78:79] offset:2048
	global_load_dwordx4 v[110:113], v194, s[78:79] offset:3072
	global_load_dwordx4 v[178:181], v194, s[92:93] offset:0
	global_load_dwordx4 v[182:185], v194, s[92:93] offset:1024
	global_load_dwordx4 v[186:189], v194, s[92:93] offset:2048
	global_load_dwordx4 v[190:193], v194, s[92:93] offset:3072
	s_waitcnt vmcnt(28)
	s_lshl_b32 s11, s98, 11
	s_add_u32 s68, s24, s11
	s_addc_u32 s69, s25, 0
	s_lshl_b32 s11, s99, 11
	s_add_u32 s70, s24, s11
	s_addc_u32 s71, s25, 0
	s_lshl_b32 s11, s42, 11
	s_add_u32 s72, s24, s11
	s_addc_u32 s73, s25, 0
	v_mul_f32_e32 v198, v2, v2
	v_mul_f32_e32 v199, v18, v18
	v_mul_f32_e32 v200, v34, v34
	v_fmac_f32_e32 v198, v3, v3
	v_fmac_f32_e32 v199, v19, v19
	v_fmac_f32_e32 v200, v35, v35
	v_fmac_f32_e32 v198, v4, v4
	v_fmac_f32_e32 v199, v20, v20
	v_fmac_f32_e32 v200, v36, v36
	v_fmac_f32_e32 v198, v5, v5
	v_fmac_f32_e32 v199, v21, v21
	v_fmac_f32_e32 v200, v37, v37
	v_fmac_f32_e32 v198, v6, v6
	v_fmac_f32_e32 v199, v22, v22
	v_fmac_f32_e32 v200, v38, v38
	v_fmac_f32_e32 v198, v7, v7
	v_fmac_f32_e32 v199, v23, v23
	v_fmac_f32_e32 v200, v39, v39
	v_fmac_f32_e32 v198, v8, v8
	v_fmac_f32_e32 v199, v24, v24
	v_fmac_f32_e32 v200, v40, v40
	v_fmac_f32_e32 v198, v9, v9
	v_fmac_f32_e32 v199, v25, v25
	v_fmac_f32_e32 v200, v41, v41
	v_fmac_f32_e32 v198, v10, v10
	v_fmac_f32_e32 v199, v26, v26
	v_fmac_f32_e32 v200, v42, v42
	v_fmac_f32_e32 v198, v11, v11
	v_fmac_f32_e32 v199, v27, v27
	v_fmac_f32_e32 v200, v43, v43
	v_fmac_f32_e32 v198, v12, v12
	v_fmac_f32_e32 v199, v28, v28
	v_fmac_f32_e32 v200, v44, v44
	v_fmac_f32_e32 v198, v13, v13
	v_fmac_f32_e32 v199, v29, v29
	v_fmac_f32_e32 v200, v45, v45
	v_fmac_f32_e32 v198, v14, v14
	v_fmac_f32_e32 v199, v30, v30
	v_fmac_f32_e32 v200, v46, v46
	v_fmac_f32_e32 v198, v15, v15
	v_fmac_f32_e32 v199, v31, v31
	v_fmac_f32_e32 v200, v47, v47
	v_fmac_f32_e32 v198, v16, v16
	v_fmac_f32_e32 v199, v32, v32
	v_fmac_f32_e32 v200, v48, v48
	v_fmac_f32_e32 v198, v17, v17
	v_fmac_f32_e32 v199, v33, v33
	v_fmac_f32_e32 v200, v49, v49
	s_nop 1
	v_add_f32_dpp v198, v198, v198 quad_perm:[1,0,3,2] row_mask:0xf bank_mask:0xf
	v_add_f32_dpp v199, v199, v199 quad_perm:[1,0,3,2] row_mask:0xf bank_mask:0xf
	v_add_f32_dpp v200, v200, v200 quad_perm:[1,0,3,2] row_mask:0xf bank_mask:0xf
	s_nop 1
	v_add_f32_dpp v198, v198, v198 quad_perm:[2,3,0,1] row_mask:0xf bank_mask:0xf
	v_add_f32_dpp v199, v199, v199 quad_perm:[2,3,0,1] row_mask:0xf bank_mask:0xf
	v_add_f32_dpp v200, v200, v200 quad_perm:[2,3,0,1] row_mask:0xf bank_mask:0xf
	s_nop 1
	v_add_f32_dpp v198, v198, v198 row_half_mirror row_mask:0xf bank_mask:0xf
	v_add_f32_dpp v199, v199, v199 row_half_mirror row_mask:0xf bank_mask:0xf
	v_add_f32_dpp v200, v200, v200 row_half_mirror row_mask:0xf bank_mask:0xf
	s_nop 1
	v_add_f32_dpp v198, v198, v198 row_mirror row_mask:0xf bank_mask:0xf
	v_add_f32_dpp v199, v199, v199 row_mirror row_mask:0xf bank_mask:0xf
	v_add_f32_dpp v200, v200, v200 row_mirror row_mask:0xf bank_mask:0xf
	s_nop 1
	v_add_f32_dpp v198, v198, v198 row_bcast:15 row_mask:0xa bank_mask:0xf
	v_add_f32_dpp v199, v199, v199 row_bcast:15 row_mask:0xa bank_mask:0xf
	v_add_f32_dpp v200, v200, v200 row_bcast:15 row_mask:0xa bank_mask:0xf
	s_nop 1
	v_add_f32_dpp v198, v198, v198 row_bcast:31 row_mask:0xc bank_mask:0xf
	v_add_f32_dpp v199, v199, v199 row_bcast:31 row_mask:0xc bank_mask:0xf
	v_add_f32_dpp v200, v200, v200 row_bcast:31 row_mask:0xc bank_mask:0xf
	s_nop 1
	v_readlane_b32 s32, v198, 63
	v_readlane_b32 s20, v199, 63
	v_readlane_b32 s94, v200, 63
	s_nop 0
	v_mov_b32_e32 v201, s32
	v_mov_b32_e32 v202, s20
	v_mov_b32_e32 v203, s94
	v_fmamk_f32 v201, v201, 0x3a800000, v196
	v_fmamk_f32 v202, v202, 0x3a800000, v196
	v_fmamk_f32 v203, v203, 0x3a800000, v196
	v_rsq_f32_e32 v201, v201
	v_rsq_f32_e32 v202, v202
	v_rsq_f32_e32 v203, v203
	s_waitcnt vmcnt(0)
	v_mul_f32_e32 v204, v2, v201
	v_mul_f32_e32 v205, v3, v201
	v_mul_f32_e32 v206, v4, v201
	v_mul_f32_e32 v207, v5, v201
	v_mul_f32_e32 v204, v50, v204
	v_mul_f32_e32 v205, v51, v205
	v_mul_f32_e32 v206, v52, v206
	v_mul_f32_e32 v207, v53, v207
	v_add_f32_e32 v114, 1.0, v114
	v_add_f32_e32 v115, 1.0, v115
	v_add_f32_e32 v116, 1.0, v116
	v_add_f32_e32 v117, 1.0, v117
	v_fma_f32 v204, v114, v204, v66
	v_fma_f32 v205, v115, v205, v67
	v_fma_f32 v206, v116, v206, v68
	v_fma_f32 v207, v117, v207, v69
	v_cvt_pk_bf16_f32 v208, v204, v205
	v_cvt_pk_bf16_f32 v209, v206, v207
	global_store_dwordx2 v195, v[208:209], s[68:69] offset:0
	v_mul_f32_e32 v204, v6, v201
	v_mul_f32_e32 v205, v7, v201
	v_mul_f32_e32 v206, v8, v201
	v_mul_f32_e32 v207, v9, v201
	v_mul_f32_e32 v204, v54, v204
	v_mul_f32_e32 v205, v55, v205
	v_mul_f32_e32 v206, v56, v206
	v_mul_f32_e32 v207, v57, v207
	v_add_f32_e32 v118, 1.0, v118
	v_add_f32_e32 v119, 1.0, v119
	v_add_f32_e32 v120, 1.0, v120
	v_add_f32_e32 v121, 1.0, v121
	v_fma_f32 v204, v118, v204, v70
	v_fma_f32 v205, v119, v205, v71
	v_fma_f32 v206, v120, v206, v72
	v_fma_f32 v207, v121, v207, v73
	v_cvt_pk_bf16_f32 v210, v204, v205
	v_cvt_pk_bf16_f32 v211, v206, v207
	global_store_dwordx2 v195, v[210:211], s[68:69] offset:512
	v_mul_f32_e32 v204, v10, v201
	v_mul_f32_e32 v205, v11, v201
	v_mul_f32_e32 v206, v12, v201
	v_mul_f32_e32 v207, v13, v201
	v_mul_f32_e32 v204, v58, v204
	v_mul_f32_e32 v205, v59, v205
	v_mul_f32_e32 v206, v60, v206
	v_mul_f32_e32 v207, v61, v207
	v_add_f32_e32 v122, 1.0, v122
	v_add_f32_e32 v123, 1.0, v123
	v_add_f32_e32 v124, 1.0, v124
	v_add_f32_e32 v125, 1.0, v125
	v_fma_f32 v204, v122, v204, v74
	v_fma_f32 v205, v123, v205, v75
	v_fma_f32 v206, v124, v206, v76
	v_fma_f32 v207, v125, v207, v77
	v_cvt_pk_bf16_f32 v208, v204, v205
	v_cvt_pk_bf16_f32 v209, v206, v207
	global_store_dwordx2 v195, v[208:209], s[68:69] offset:1024
	v_mul_f32_e32 v204, v14, v201
	v_mul_f32_e32 v205, v15, v201
	v_mul_f32_e32 v206, v16, v201
	v_mul_f32_e32 v207, v17, v201
	v_mul_f32_e32 v204, v62, v204
	v_mul_f32_e32 v205, v63, v205
	v_mul_f32_e32 v206, v64, v206
	v_mul_f32_e32 v207, v65, v207
	v_add_f32_e32 v126, 1.0, v126
	v_add_f32_e32 v127, 1.0, v127
	v_add_f32_e32 v128, 1.0, v128
	v_add_f32_e32 v129, 1.0, v129
	v_fma_f32 v204, v126, v204, v78
	v_fma_f32 v205, v127, v205, v79
	v_fma_f32 v206, v128, v206, v80
	v_fma_f32 v207, v129, v207, v81
	v_cvt_pk_bf16_f32 v210, v204, v205
	v_cvt_pk_bf16_f32 v211, v206, v207
	global_store_dwordx2 v195, v[210:211], s[68:69] offset:1536
	v_mul_f32_e32 v204, v18, v202
	v_mul_f32_e32 v205, v19, v202
	v_mul_f32_e32 v206, v20, v202
	v_mul_f32_e32 v207, v21, v202
	v_mul_f32_e32 v204, v50, v204
	v_mul_f32_e32 v205, v51, v205
	v_mul_f32_e32 v206, v52, v206
	v_mul_f32_e32 v207, v53, v207
	v_add_f32_e32 v162, 1.0, v162
	v_add_f32_e32 v163, 1.0, v163
	v_add_f32_e32 v164, 1.0, v164
	v_add_f32_e32 v165, 1.0, v165
	v_fma_f32 v204, v162, v204, v82
	v_fma_f32 v205, v163, v205, v83
	v_fma_f32 v206, v164, v206, v84
	v_fma_f32 v207, v165, v207, v85
	v_cvt_pk_bf16_f32 v208, v204, v205
	v_cvt_pk_bf16_f32 v209, v206, v207
	global_store_dwordx2 v195, v[208:209], s[70:71] offset:0
	v_mul_f32_e32 v204, v22, v202
	v_mul_f32_e32 v205, v23, v202
	v_mul_f32_e32 v206, v24, v202
	v_mul_f32_e32 v207, v25, v202
	v_mul_f32_e32 v204, v54, v204
	v_mul_f32_e32 v205, v55, v205
	v_mul_f32_e32 v206, v56, v206
	v_mul_f32_e32 v207, v57, v207
	v_add_f32_e32 v166, 1.0, v166
	v_add_f32_e32 v167, 1.0, v167
	v_add_f32_e32 v168, 1.0, v168
	v_add_f32_e32 v169, 1.0, v169
	v_fma_f32 v204, v166, v204, v86
	v_fma_f32 v205, v167, v205, v87
	v_fma_f32 v206, v168, v206, v88
	v_fma_f32 v207, v169, v207, v89
	v_cvt_pk_bf16_f32 v210, v204, v205
	v_cvt_pk_bf16_f32 v211, v206, v207
	global_store_dwordx2 v195, v[210:211], s[70:71] offset:512
	v_mul_f32_e32 v204, v26, v202
	v_mul_f32_e32 v205, v27, v202
	v_mul_f32_e32 v206, v28, v202
	v_mul_f32_e32 v207, v29, v202
	v_mul_f32_e32 v204, v58, v204
	v_mul_f32_e32 v205, v59, v205
	v_mul_f32_e32 v206, v60, v206
	v_mul_f32_e32 v207, v61, v207
	v_add_f32_e32 v170, 1.0, v170
	v_add_f32_e32 v171, 1.0, v171
	v_add_f32_e32 v172, 1.0, v172
	v_add_f32_e32 v173, 1.0, v173
	v_fma_f32 v204, v170, v204, v90
	v_fma_f32 v205, v171, v205, v91
	v_fma_f32 v206, v172, v206, v92
	v_fma_f32 v207, v173, v207, v93
	v_cvt_pk_bf16_f32 v208, v204, v205
	v_cvt_pk_bf16_f32 v209, v206, v207
	global_store_dwordx2 v195, v[208:209], s[70:71] offset:1024
	v_mul_f32_e32 v204, v30, v202
	v_mul_f32_e32 v205, v31, v202
	v_mul_f32_e32 v206, v32, v202
	v_mul_f32_e32 v207, v33, v202
	v_mul_f32_e32 v204, v62, v204
	v_mul_f32_e32 v205, v63, v205
	v_mul_f32_e32 v206, v64, v206
	v_mul_f32_e32 v207, v65, v207
	v_add_f32_e32 v174, 1.0, v174
	v_add_f32_e32 v175, 1.0, v175
	v_add_f32_e32 v176, 1.0, v176
	v_add_f32_e32 v177, 1.0, v177
	v_fma_f32 v204, v174, v204, v94
	v_fma_f32 v205, v175, v205, v95
	v_fma_f32 v206, v176, v206, v96
	v_fma_f32 v207, v177, v207, v97
	v_cvt_pk_bf16_f32 v210, v204, v205
	v_cvt_pk_bf16_f32 v211, v206, v207
	global_store_dwordx2 v195, v[210:211], s[70:71] offset:1536
	v_mul_f32_e32 v204, v34, v203
	v_mul_f32_e32 v205, v35, v203
	v_mul_f32_e32 v206, v36, v203
	v_mul_f32_e32 v207, v37, v203
	v_mul_f32_e32 v204, v50, v204
	v_mul_f32_e32 v205, v51, v205
	v_mul_f32_e32 v206, v52, v206
	v_mul_f32_e32 v207, v53, v207
	v_add_f32_e32 v178, 1.0, v178
	v_add_f32_e32 v179, 1.0, v179
	v_add_f32_e32 v180, 1.0, v180
	v_add_f32_e32 v181, 1.0, v181
	v_fma_f32 v204, v178, v204, v98
	v_fma_f32 v205, v179, v205, v99
	v_fma_f32 v206, v180, v206, v100
	v_fma_f32 v207, v181, v207, v101
	v_cvt_pk_bf16_f32 v208, v204, v205
	v_cvt_pk_bf16_f32 v209, v206, v207
	global_store_dwordx2 v195, v[208:209], s[72:73] offset:0
	v_mul_f32_e32 v204, v38, v203
	v_mul_f32_e32 v205, v39, v203
	v_mul_f32_e32 v206, v40, v203
	v_mul_f32_e32 v207, v41, v203
	v_mul_f32_e32 v204, v54, v204
	v_mul_f32_e32 v205, v55, v205
	v_mul_f32_e32 v206, v56, v206
	v_mul_f32_e32 v207, v57, v207
	v_add_f32_e32 v182, 1.0, v182
	v_add_f32_e32 v183, 1.0, v183
	v_add_f32_e32 v184, 1.0, v184
	v_add_f32_e32 v185, 1.0, v185
	v_fma_f32 v204, v182, v204, v102
	v_fma_f32 v205, v183, v205, v103
	v_fma_f32 v206, v184, v206, v104
	v_fma_f32 v207, v185, v207, v105
	v_cvt_pk_bf16_f32 v210, v204, v205
	v_cvt_pk_bf16_f32 v211, v206, v207
	global_store_dwordx2 v195, v[210:211], s[72:73] offset:512
	v_mul_f32_e32 v204, v42, v203
	v_mul_f32_e32 v205, v43, v203
	v_mul_f32_e32 v206, v44, v203
	v_mul_f32_e32 v207, v45, v203
	v_mul_f32_e32 v204, v58, v204
	v_mul_f32_e32 v205, v59, v205
	v_mul_f32_e32 v206, v60, v206
	v_mul_f32_e32 v207, v61, v207
	v_add_f32_e32 v186, 1.0, v186
	v_add_f32_e32 v187, 1.0, v187
	v_add_f32_e32 v188, 1.0, v188
	v_add_f32_e32 v189, 1.0, v189
	v_fma_f32 v204, v186, v204, v106
	v_fma_f32 v205, v187, v205, v107
	v_fma_f32 v206, v188, v206, v108
	v_fma_f32 v207, v189, v207, v109
	v_cvt_pk_bf16_f32 v208, v204, v205
	v_cvt_pk_bf16_f32 v209, v206, v207
	global_store_dwordx2 v195, v[208:209], s[72:73] offset:1024
	v_mul_f32_e32 v204, v46, v203
	v_mul_f32_e32 v205, v47, v203
	v_mul_f32_e32 v206, v48, v203
	v_mul_f32_e32 v207, v49, v203
	v_mul_f32_e32 v204, v62, v204
	v_mul_f32_e32 v205, v63, v205
	v_mul_f32_e32 v206, v64, v206
	v_mul_f32_e32 v207, v65, v207
	v_add_f32_e32 v190, 1.0, v190
	v_add_f32_e32 v191, 1.0, v191
	v_add_f32_e32 v192, 1.0, v192
	v_add_f32_e32 v193, 1.0, v193
	v_fma_f32 v204, v190, v204, v110
	v_fma_f32 v205, v191, v205, v111
	v_fma_f32 v206, v192, v206, v112
	v_fma_f32 v207, v193, v207, v113
	v_cvt_pk_bf16_f32 v210, v204, v205
	v_cvt_pk_bf16_f32 v211, v206, v207
	global_store_dwordx2 v195, v[210:211], s[72:73] offset:1536
	s_branch .LBB0_397

.LBB0_402:
	s_waitcnt vmcnt(5)
	s_barrier
	s_mul_i32 s2, s12, 0xc000
	v_add_u32_e32 v63, s2, v60
	v_add_u32_e32 v66, 0x2000, v63
	v_readfirstlane_b32 s2, v63
	v_lshl_add_u64 v[64:65], s[48:49], 0, v[58:59]
	s_mov_b32 m0, s2
	v_readfirstlane_b32 s2, v66
	v_add_u32_e32 v66, 0x4000, v63
	global_load_lds_dwordx4 v[64:65], off
	v_lshl_add_u64 v[64:65], s[48:49], 0, v[56:57]
	s_mov_b32 m0, s2
	v_readfirstlane_b32 s2, v66
	v_add_u32_e32 v66, 0x8000, v63
	global_load_lds_dwordx4 v[64:65], off
	v_lshl_add_u64 v[64:65], s[48:49], 0, v[54:55]
	s_mov_b32 m0, s2
	v_readfirstlane_b32 s2, v66
	v_add_u32_e32 v63, 0xa000, v63
	global_load_lds_dwordx4 v[64:65], off
	v_lshl_add_u64 v[64:65], s[48:49], 0, v[52:53]
	s_mov_b32 m0, s2
	v_readfirstlane_b32 s2, v63
	global_load_lds_dwordx4 v[64:65], off
	v_lshl_add_u64 v[64:65], s[48:49], 0, v[50:51]
	s_mov_b32 m0, s2
	s_mul_i32 s2, s1, 0xc000
	global_load_lds_dwordx4 v[64:65], off
	v_add_u32_e32 v63, s2, v61
	ds_read_b128 v[64:67], v63 offset:0
	ds_read_b128 v[68:71], v63 offset:2048
	ds_read_b128 v[72:75], v63 offset:4096
	v_add_u32_e32 v116, s2, v62
	ds_read_b128 v[76:79], v116 offset:0
	ds_read_b128 v[80:83], v116 offset:2048
	ds_read_b128 v[84:87], v116 offset:4096
	ds_read_b128 v[88:91], v116 offset:6144
	ds_read_b128 v[92:95], v63 offset:1024
	ds_read_b128 v[96:99], v63 offset:3072
	ds_read_b128 v[100:103], v63 offset:5120
	ds_read_b128 v[104:107], v116 offset:1024
	ds_read_b128 v[108:111], v116 offset:3072
	ds_read_b128 v[112:115], v116 offset:5120
	ds_read_b128 v[116:119], v116 offset:7168
	s_waitcnt lgkmcnt(7)
	s_nop 0
	v_mfma_f32_16x16x32_bf16 v[46:49], v[76:79], v[64:67], v[46:49]
	v_mfma_f32_16x16x32_bf16 v[42:45], v[80:83], v[64:67], v[42:45]
	v_mfma_f32_16x16x32_bf16 v[38:41], v[84:87], v[64:67], v[38:41]
	v_mfma_f32_16x16x32_bf16 v[34:37], v[88:91], v[64:67], v[34:37]
	v_mfma_f32_16x16x32_bf16 v[30:33], v[76:79], v[68:71], v[30:33]
	v_mfma_f32_16x16x32_bf16 v[26:29], v[80:83], v[68:71], v[26:29]
	v_mfma_f32_16x16x32_bf16 v[22:25], v[84:87], v[68:71], v[22:25]
	v_mfma_f32_16x16x32_bf16 v[18:21], v[88:91], v[68:71], v[18:21]
	v_mfma_f32_16x16x32_bf16 v[14:17], v[76:79], v[72:75], v[14:17]
	v_mfma_f32_16x16x32_bf16 v[10:13], v[80:83], v[72:75], v[10:13]
	v_mfma_f32_16x16x32_bf16 v[6:9], v[84:87], v[72:75], v[6:9]
	v_mfma_f32_16x16x32_bf16 v[2:5], v[88:91], v[72:75], v[2:5]
	s_waitcnt lgkmcnt(0)
	v_mfma_f32_16x16x32_bf16 v[46:49], v[104:107], v[92:95], v[46:49]
	v_mfma_f32_16x16x32_bf16 v[42:45], v[108:111], v[92:95], v[42:45]
	v_mfma_f32_16x16x32_bf16 v[38:41], v[112:115], v[92:95], v[38:41]
	v_mfma_f32_16x16x32_bf16 v[34:37], v[116:119], v[92:95], v[34:37]
	v_mfma_f32_16x16x32_bf16 v[30:33], v[104:107], v[96:99], v[30:33]
	v_mfma_f32_16x16x32_bf16 v[26:29], v[108:111], v[96:99], v[26:29]
	v_mfma_f32_16x16x32_bf16 v[22:25], v[112:115], v[96:99], v[22:25]
	v_mfma_f32_16x16x32_bf16 v[18:21], v[116:119], v[96:99], v[18:21]
	v_mfma_f32_16x16x32_bf16 v[14:17], v[104:107], v[100:103], v[14:17]
	v_mfma_f32_16x16x32_bf16 v[10:13], v[108:111], v[100:103], v[10:13]
	v_mfma_f32_16x16x32_bf16 v[6:9], v[112:115], v[100:103], v[6:9]
	v_mfma_f32_16x16x32_bf16 v[2:5], v[116:119], v[100:103], v[2:5]
	s_add_i32 s2, s1, 1
	s_cmp_lg_u32 s1, 2
	s_cselect_b32 s1, s2, 0
	s_add_i32 s2, s12, 1
	s_cmp_lg_u32 s12, 2
	s_cselect_b32 s12, s2, 0
	s_add_i32 s0, s0, -1
	v_lshl_add_u64 v[50:51], v[50:51], 0, s[30:31]
	v_lshl_add_u64 v[52:53], v[52:53], 0, s[30:31]
	v_lshl_add_u64 v[54:55], v[54:55], 0, s[30:31]
	v_lshl_add_u64 v[56:57], v[56:57], 0, s[30:31]
	s_cmp_lg_u32 s0, 0
	v_lshl_add_u64 v[58:59], v[58:59], 0, s[30:31]
	s_cbranch_scc1 .LBB0_402
	s_waitcnt vmcnt(5)
	s_mulk_i32 s11, 0xc0
	s_barrier
	ds_read_b128 v[50:53], v61 offset:0
	ds_read_b128 v[54:57], v61 offset:2048
	ds_read_b128 v[64:67], v61 offset:4096
	ds_read_b128 v[68:71], v62 offset:0
	ds_read_b128 v[72:75], v62 offset:2048
	ds_read_b128 v[76:79], v62 offset:4096
	ds_read_b128 v[80:83], v62 offset:6144
	ds_read_b128 v[84:87], v61 offset:1024
	ds_read_b128 v[88:91], v61 offset:3072
	ds_read_b128 v[92:95], v61 offset:5120
	ds_read_b128 v[96:99], v62 offset:1024
	ds_read_b128 v[100:103], v62 offset:3072
	ds_read_b128 v[104:107], v62 offset:5120
	ds_read_b128 v[108:111], v62 offset:7168
	v_and_b32_e32 v112, 64, v0
	s_waitcnt lgkmcnt(7)
	v_mfma_f32_16x16x32_bf16 v[46:49], v[68:71], v[50:53], v[46:49]
	v_mfma_f32_16x16x32_bf16 v[42:45], v[72:75], v[50:53], v[42:45]
	v_mfma_f32_16x16x32_bf16 v[38:41], v[76:79], v[50:53], v[38:41]
	v_mfma_f32_16x16x32_bf16 v[34:37], v[80:83], v[50:53], v[34:37]
	v_mfma_f32_16x16x32_bf16 v[30:33], v[68:71], v[54:57], v[30:33]
	v_mfma_f32_16x16x32_bf16 v[26:29], v[72:75], v[54:57], v[26:29]
	v_mfma_f32_16x16x32_bf16 v[22:25], v[76:79], v[54:57], v[22:25]
	v_mfma_f32_16x16x32_bf16 v[18:21], v[80:83], v[54:57], v[18:21]
	v_mfma_f32_16x16x32_bf16 v[14:17], v[68:71], v[64:67], v[14:17]
	v_mfma_f32_16x16x32_bf16 v[10:13], v[72:75], v[64:67], v[10:13]
	v_mfma_f32_16x16x32_bf16 v[6:9], v[76:79], v[64:67], v[6:9]
	v_mfma_f32_16x16x32_bf16 v[2:5], v[80:83], v[64:67], v[2:5]
	s_waitcnt lgkmcnt(0)
	v_mfma_f32_16x16x32_bf16 v[46:49], v[96:99], v[84:87], v[46:49]
	v_mfma_f32_16x16x32_bf16 v[42:45], v[100:103], v[84:87], v[42:45]
	v_mfma_f32_16x16x32_bf16 v[38:41], v[104:107], v[84:87], v[38:41]
	v_mfma_f32_16x16x32_bf16 v[34:37], v[108:111], v[84:87], v[34:37]
	v_mfma_f32_16x16x32_bf16 v[30:33], v[96:99], v[88:91], v[30:33]
	v_mfma_f32_16x16x32_bf16 v[26:29], v[100:103], v[88:91], v[26:29]
	v_mfma_f32_16x16x32_bf16 v[22:25], v[104:107], v[88:91], v[22:25]
	v_mfma_f32_16x16x32_bf16 v[18:21], v[108:111], v[88:91], v[18:21]
	v_mfma_f32_16x16x32_bf16 v[14:17], v[96:99], v[92:95], v[14:17]
	v_mfma_f32_16x16x32_bf16 v[10:13], v[100:103], v[92:95], v[10:13]
	v_mfma_f32_16x16x32_bf16 v[6:9], v[104:107], v[92:95], v[6:9]
	v_mfma_f32_16x16x32_bf16 v[2:5], v[108:111], v[92:95], v[2:5]
	s_waitcnt vmcnt(0)
	v_ashrrev_i32_e32 v106, 7, v0
	s_barrier
	v_add_u32_e32 v86, 0xc000, v61
	ds_read_b128 v[50:53], v86 offset:0
	ds_read_b128 v[54:57], v86 offset:2048
	ds_read_b128 v[58:61], v86 offset:4096
	v_add_u32_e32 v102, 0xc000, v62
	ds_read_b128 v[62:65], v102 offset:0
	ds_read_b128 v[66:69], v102 offset:2048
	ds_read_b128 v[70:73], v102 offset:4096
	ds_read_b128 v[74:77], v102 offset:6144
	ds_read_b128 v[78:81], v86 offset:1024
	ds_read_b128 v[82:85], v86 offset:3072
	ds_read_b128 v[86:89], v86 offset:5120
	ds_read_b128 v[90:93], v102 offset:1024
	ds_read_b128 v[94:97], v102 offset:3072
	ds_read_b128 v[98:101], v102 offset:5120
	ds_read_b128 v[102:105], v102 offset:7168
	s_waitcnt lgkmcnt(7)
	s_nop 0
	v_mfma_f32_16x16x32_bf16 v[46:49], v[62:65], v[50:53], v[46:49]
	v_mfma_f32_16x16x32_bf16 v[42:45], v[66:69], v[50:53], v[42:45]
	v_mfma_f32_16x16x32_bf16 v[38:41], v[70:73], v[50:53], v[38:41]
	v_mfma_f32_16x16x32_bf16 v[34:37], v[74:77], v[50:53], v[34:37]
	v_mfma_f32_16x16x32_bf16 v[30:33], v[62:65], v[54:57], v[30:33]
	v_mfma_f32_16x16x32_bf16 v[26:29], v[66:69], v[54:57], v[26:29]
	v_mfma_f32_16x16x32_bf16 v[22:25], v[70:73], v[54:57], v[22:25]
	v_mfma_f32_16x16x32_bf16 v[18:21], v[74:77], v[54:57], v[18:21]
	v_mfma_f32_16x16x32_bf16 v[14:17], v[62:65], v[58:61], v[14:17]
	v_mfma_f32_16x16x32_bf16 v[10:13], v[66:69], v[58:61], v[10:13]
	v_mfma_f32_16x16x32_bf16 v[6:9], v[70:73], v[58:61], v[6:9]
	v_mfma_f32_16x16x32_bf16 v[2:5], v[74:77], v[58:61], v[2:5]
	s_waitcnt lgkmcnt(0)
	v_mfma_f32_16x16x32_bf16 v[48:51], v[90:93], v[78:81], v[46:49]
	v_mfma_f32_16x16x32_bf16 v[52:55], v[94:97], v[78:81], v[42:45]
	v_mfma_f32_16x16x32_bf16 v[56:59], v[98:101], v[78:81], v[38:41]
	v_mfma_f32_16x16x32_bf16 v[34:37], v[102:105], v[78:81], v[34:37]
	v_mfma_f32_16x16x32_bf16 v[30:33], v[90:93], v[82:85], v[30:33]
	v_mfma_f32_16x16x32_bf16 v[26:29], v[94:97], v[82:85], v[26:29]
	v_mfma_f32_16x16x32_bf16 v[22:25], v[98:101], v[82:85], v[22:25]
	v_mfma_f32_16x16x32_bf16 v[18:21], v[102:105], v[82:85], v[18:21]
	v_mfma_f32_16x16x32_bf16 v[14:17], v[90:93], v[86:89], v[14:17]
	v_mfma_f32_16x16x32_bf16 v[10:13], v[94:97], v[86:89], v[10:13]
	v_mfma_f32_16x16x32_bf16 v[6:9], v[98:101], v[86:89], v[6:9]
	v_mfma_f32_16x16x32_bf16 v[2:5], v[102:105], v[86:89], v[2:5]
	s_nop 7
	v_readlane_b32 s68, v214, 57
	s_and_b32 s2, s9, 31
	s_mul_i32 s2, s2, 192
	s_lshr_b32 s3, s9, 5
	s_lshl_b32 s3, s3, 7
	s_mul_i32 s10, s68, 0x1b000
	s_add_u32 s10, s10, 0x2000
	s_add_u32 s38, s34, s10
	s_addc_u32 s39, s35, 0
	v_lshrrev_b32_e32 v128, 6, v142
	v_and_b32_e32 v129, 1, v128
	v_lshrrev_b32_e32 v128, 1, v128
	v_lshlrev_b32_e32 v66, 6, v129
	v_lshrrev_b32_e32 v129, 4, v142
	v_and_b32_e32 v129, 3, v129
	v_lshl_add_u32 v66, v129, 2, v66
	v_add_u32_e32 v66, s3, v66
	v_lshlrev_b32_e32 v66, 2, v66
	v_mul_u32_u24_e32 v67, 48, v128
	v_and_b32_e32 v129, 15, v142
	v_add3_u32 v67, v67, v129, s2
	v_add_u32_e32 v128, 0, v67
	v_lshl_add_u32 v141, v128, 12, v66
	v_add_u32_e32 v129, 0xfffff000, v128
	v_lshrrev_b32_e32 v129, 10, v129
	v_add_u32_e32 v129, 1, v129
	v_cmp_gt_u32_e32 vcc, 0x1000, v128
	v_cndmask_b32_e64 v129, v129, 0, vcc
	v_mul_u32_u24_e32 v129, 0x9000, v129
	v_add_u32_e32 v134, v129, v66
	global_load_dwordx4 v[68:71], v134, s[38:39] offset:0
	global_load_dwordx4 v[72:75], v134, s[38:39] offset:64
	global_load_dwordx4 v[76:79], v134, s[38:39] offset:128
	global_load_dwordx4 v[80:83], v134, s[38:39] offset:192
	v_add_u32_e32 v128, 16, v67
	v_lshl_add_u32 v162, v128, 12, v66
	v_add_u32_e32 v129, 0xfffff000, v128
	v_lshrrev_b32_e32 v129, 10, v129
	v_add_u32_e32 v129, 1, v129
	v_cmp_gt_u32_e32 vcc, 0x1000, v128
	v_cndmask_b32_e64 v129, v129, 0, vcc
	v_mul_u32_u24_e32 v129, 0x9000, v129
	v_add_u32_e32 v135, v129, v66
	global_load_dwordx4 v[84:87], v135, s[38:39] offset:0
	global_load_dwordx4 v[88:91], v135, s[38:39] offset:64
	global_load_dwordx4 v[92:95], v135, s[38:39] offset:128
	global_load_dwordx4 v[96:99], v135, s[38:39] offset:192
	v_add_u32_e32 v128, 32, v67
	v_lshl_add_u32 v163, v128, 12, v66
	v_add_u32_e32 v129, 0xfffff000, v128
	v_lshrrev_b32_e32 v129, 10, v129
	v_add_u32_e32 v129, 1, v129
	v_cmp_gt_u32_e32 vcc, 0x1000, v128
	v_cndmask_b32_e64 v129, v129, 0, vcc
	v_mul_u32_u24_e32 v129, 0x9000, v129
	v_add_u32_e32 v140, v129, v66
	global_load_dwordx4 v[100:103], v140, s[38:39] offset:0
	global_load_dwordx4 v[104:107], v140, s[38:39] offset:64
	global_load_dwordx4 v[108:111], v140, s[38:39] offset:128
	global_load_dwordx4 v[112:115], v140, s[38:39] offset:192
	s_cmp_lg_u32 s68, 0
	s_cbranch_scc1 .Lres_d0_ws
	v_readlane_b32 s10, v217, 1
	v_readlane_b32 s11, v217, 2
	s_sub_u32 s10, s10, 0xd0
	s_subb_u32 s11, s11, 0
	s_load_dwordx4 s[40:43], s[10:11], 0x0
	s_waitcnt lgkmcnt(0)
	s_sub_u32 s42, s42, 0x1000000
	s_subb_u32 s43, s43, 0
	v_add_u32_e32 v128, 0, v67
	v_cmp_gt_u32_e32 vcc, 0x1000, v128
	v_mov_b32_e32 v196, s42
	v_mov_b32_e32 v197, s43
	v_mov_b32_e32 v198, s40
	v_mov_b32_e32 v199, s41
	v_cndmask_b32_e32 v196, v196, v198, vcc
	v_cndmask_b32_e32 v197, v197, v199, vcc
	v_add_co_u32_e32 v200, vcc, v196, v141
	s_nop 1
	v_addc_co_u32_e32 v201, vcc, 0, v197, vcc
	global_load_dwordx4 v[116:119], v[200:201], off offset:0
	global_load_dwordx4 v[120:123], v[200:201], off offset:64
	global_load_dwordx4 v[124:127], v[200:201], off offset:128
	global_load_dwordx4 v[136:139], v[200:201], off offset:192
	v_add_u32_e32 v128, 16, v67
	v_cmp_gt_u32_e32 vcc, 0x1000, v128
	v_mov_b32_e32 v196, s42
	v_mov_b32_e32 v197, s43
	v_mov_b32_e32 v198, s40
	v_mov_b32_e32 v199, s41
	v_cndmask_b32_e32 v196, v196, v198, vcc
	v_cndmask_b32_e32 v197, v197, v199, vcc
	v_add_co_u32_e32 v202, vcc, v196, v162
	s_nop 1
	v_addc_co_u32_e32 v203, vcc, 0, v197, vcc
	global_load_dwordx4 v[164:167], v[202:203], off offset:0
	global_load_dwordx4 v[168:171], v[202:203], off offset:64
	global_load_dwordx4 v[172:175], v[202:203], off offset:128
	global_load_dwordx4 v[176:179], v[202:203], off offset:192
	v_add_u32_e32 v128, 32, v67
	v_cmp_gt_u32_e32 vcc, 0x1000, v128
	v_mov_b32_e32 v196, s42
	v_mov_b32_e32 v197, s43
	v_mov_b32_e32 v198, s40
	v_mov_b32_e32 v199, s41
	v_cndmask_b32_e32 v196, v196, v198, vcc
	v_cndmask_b32_e32 v197, v197, v199, vcc
	v_add_co_u32_e32 v204, vcc, v196, v163
	s_nop 1
	v_addc_co_u32_e32 v205, vcc, 0, v197, vcc
	global_load_dwordx4 v[180:183], v[204:205], off offset:0
	global_load_dwordx4 v[184:187], v[204:205], off offset:64
	global_load_dwordx4 v[188:191], v[204:205], off offset:128
	global_load_dwordx4 v[192:195], v[204:205], off offset:192
	s_branch .Lres_d0_ld
.Lres_d0_ws:
	global_load_dwordx4 v[116:119], v141, s[48:49] offset:0
	global_load_dwordx4 v[120:123], v141, s[48:49] offset:64
	global_load_dwordx4 v[124:127], v141, s[48:49] offset:128
	global_load_dwordx4 v[136:139], v141, s[48:49] offset:192
	global_load_dwordx4 v[164:167], v162, s[48:49] offset:0
	global_load_dwordx4 v[168:171], v162, s[48:49] offset:64
	global_load_dwordx4 v[172:175], v162, s[48:49] offset:128
	global_load_dwordx4 v[176:179], v162, s[48:49] offset:192
	global_load_dwordx4 v[180:183], v163, s[48:49] offset:0
	global_load_dwordx4 v[184:187], v163, s[48:49] offset:64
	global_load_dwordx4 v[188:191], v163, s[48:49] offset:128
	global_load_dwordx4 v[192:195], v163, s[48:49] offset:192
.Lres_d0_ld:
	s_waitcnt vmcnt(0)
	v_mul_f32_e32 v68, 0.5, v68
	v_mul_f32_e32 v69, 0.5, v69
	v_mul_f32_e32 v70, 0.5, v70
	v_mul_f32_e32 v71, 0.5, v71
	v_fma_f32 v116, v48, v68, v116
	v_fma_f32 v117, v49, v69, v117
	v_fma_f32 v118, v50, v70, v118
	v_fma_f32 v119, v51, v71, v119
	global_store_dwordx4 v141, v[116:119], s[48:49] offset:0
	v_mul_f32_e32 v72, 0.5, v72
	v_mul_f32_e32 v73, 0.5, v73
	v_mul_f32_e32 v74, 0.5, v74
	v_mul_f32_e32 v75, 0.5, v75
	v_fma_f32 v120, v52, v72, v120
	v_fma_f32 v121, v53, v73, v121
	v_fma_f32 v122, v54, v74, v122
	v_fma_f32 v123, v55, v75, v123
	global_store_dwordx4 v141, v[120:123], s[48:49] offset:64
	v_mul_f32_e32 v76, 0.5, v76
	v_mul_f32_e32 v77, 0.5, v77
	v_mul_f32_e32 v78, 0.5, v78
	v_mul_f32_e32 v79, 0.5, v79
	v_fma_f32 v124, v56, v76, v124
	v_fma_f32 v125, v57, v77, v125
	v_fma_f32 v126, v58, v78, v126
	v_fma_f32 v127, v59, v79, v127
	global_store_dwordx4 v141, v[124:127], s[48:49] offset:128
	v_mul_f32_e32 v80, 0.5, v80
	v_mul_f32_e32 v81, 0.5, v81
	v_mul_f32_e32 v82, 0.5, v82
	v_mul_f32_e32 v83, 0.5, v83
	v_fma_f32 v136, v34, v80, v136
	v_fma_f32 v137, v35, v81, v137
	v_fma_f32 v138, v36, v82, v138
	v_fma_f32 v139, v37, v83, v139
	global_store_dwordx4 v141, v[136:139], s[48:49] offset:192
	v_mul_f32_e32 v84, 0.5, v84
	v_mul_f32_e32 v85, 0.5, v85
	v_mul_f32_e32 v86, 0.5, v86
	v_mul_f32_e32 v87, 0.5, v87
	v_fma_f32 v164, v30, v84, v164
	v_fma_f32 v165, v31, v85, v165
	v_fma_f32 v166, v32, v86, v166
	v_fma_f32 v167, v33, v87, v167
	global_store_dwordx4 v162, v[164:167], s[48:49] offset:0
	v_mul_f32_e32 v88, 0.5, v88
	v_mul_f32_e32 v89, 0.5, v89
	v_mul_f32_e32 v90, 0.5, v90
	v_mul_f32_e32 v91, 0.5, v91
	v_fma_f32 v168, v26, v88, v168
	v_fma_f32 v169, v27, v89, v169
	v_fma_f32 v170, v28, v90, v170
	v_fma_f32 v171, v29, v91, v171
	global_store_dwordx4 v162, v[168:171], s[48:49] offset:64
	v_mul_f32_e32 v92, 0.5, v92
	v_mul_f32_e32 v93, 0.5, v93
	v_mul_f32_e32 v94, 0.5, v94
	v_mul_f32_e32 v95, 0.5, v95
	v_fma_f32 v172, v22, v92, v172
	v_fma_f32 v173, v23, v93, v173
	v_fma_f32 v174, v24, v94, v174
	v_fma_f32 v175, v25, v95, v175
	global_store_dwordx4 v162, v[172:175], s[48:49] offset:128
	v_mul_f32_e32 v96, 0.5, v96
	v_mul_f32_e32 v97, 0.5, v97
	v_mul_f32_e32 v98, 0.5, v98
	v_mul_f32_e32 v99, 0.5, v99
	v_fma_f32 v176, v18, v96, v176
	v_fma_f32 v177, v19, v97, v177
	v_fma_f32 v178, v20, v98, v178
	v_fma_f32 v179, v21, v99, v179
	global_store_dwordx4 v162, v[176:179], s[48:49] offset:192
	v_mul_f32_e32 v100, 0.5, v100
	v_mul_f32_e32 v101, 0.5, v101
	v_mul_f32_e32 v102, 0.5, v102
	v_mul_f32_e32 v103, 0.5, v103
	v_fma_f32 v180, v14, v100, v180
	v_fma_f32 v181, v15, v101, v181
	v_fma_f32 v182, v16, v102, v182
	v_fma_f32 v183, v17, v103, v183
	global_store_dwordx4 v163, v[180:183], s[48:49] offset:0
	v_mul_f32_e32 v104, 0.5, v104
	v_mul_f32_e32 v105, 0.5, v105
	v_mul_f32_e32 v106, 0.5, v106
	v_mul_f32_e32 v107, 0.5, v107
	v_fma_f32 v184, v10, v104, v184
	v_fma_f32 v185, v11, v105, v185
	v_fma_f32 v186, v12, v106, v186
	v_fma_f32 v187, v13, v107, v187
	global_store_dwordx4 v163, v[184:187], s[48:49] offset:64
	v_mul_f32_e32 v108, 0.5, v108
	v_mul_f32_e32 v109, 0.5, v109
	v_mul_f32_e32 v110, 0.5, v110
	v_mul_f32_e32 v111, 0.5, v111
	v_fma_f32 v188, v6, v108, v188
	v_fma_f32 v189, v7, v109, v189
	v_fma_f32 v190, v8, v110, v190
	v_fma_f32 v191, v9, v111, v191
	global_store_dwordx4 v163, v[188:191], s[48:49] offset:128
	v_mul_f32_e32 v112, 0.5, v112
	v_mul_f32_e32 v113, 0.5, v113
	v_mul_f32_e32 v114, 0.5, v114
	v_mul_f32_e32 v115, 0.5, v115
	v_fma_f32 v192, v2, v112, v192
	v_fma_f32 v193, v3, v113, v193
	v_fma_f32 v194, v4, v114, v194
	v_fma_f32 v195, v5, v115, v195
	global_store_dwordx4 v163, v[192:195], s[48:49] offset:192
	s_add_i32 s9, s9, s84
	s_cmpk_gt_i32 s9, 0xff
	s_cbranch_scc0 .LBB0_401

.LBB0_405:
	s_andn2_b64 vcc, exec, s[0:1]
	s_mov_b64 s[2:3], 0
	s_cbranch_vccnz .LBB0_417
	s_cmp_gt_i32 s21, 0
	s_mov_b64 s[0:1], -1
	s_cbranch_scc0 .LBB0_429
	v_readlane_b32 s11, v217, 0
	v_readlane_b32 s12, v214, 57
	s_and_b32 s14, s11, 7
	s_lshr_b32 s15, s11, 3
	s_mul_hi_u32 s16, s12, 0x3500000
	s_mul_i32 s12, s12, 0x3500000
	s_add_u32 s40, s48, s12
	s_addc_u32 s41, s49, s16
	s_add_u32 s40, s40, 0xf5ce000
	s_addc_u32 s41, s41, 0
	v_and_b32_e32 v141, 15, v142
	v_lshrrev_b32_e32 v139, 4, v142
	v_and_b32_e32 v139, 3, v139
	v_lshlrev_b32_e32 v140, 6, v141
	v_lshl_add_u32 v140, v139, 4, v140
	v_lshrrev_b32_e32 v139, 3, v141
	v_lshlrev_b32_e32 v139, 5, v139
	v_xor_b32_e32 v135, v140, v139
	v_lshrrev_b32_e32 v139, 7, v142
	v_lshl_add_u32 v134, v139, 12, v135
	v_lshrrev_b32_e32 v139, 6, v142
	v_and_b32_e32 v139, 1, v139
	v_lshl_add_u32 v135, v139, 12, v135
	v_add_u32_e32 v135, 0x4000, v135
	v_and_b32_e32 v141, 63, v142
	v_lshrrev_b32_e32 v139, 2, v141
	v_lshrrev_b32_e32 v140, 6, v142
	v_lshl_add_u32 v139, v140, 4, v139
	v_lshlrev_b32_e32 v139, 11, v139
	v_and_b32_e32 v140, 3, v141
	v_lshlrev_b32_e32 v140, 4, v140
	v_lshrrev_b32_e32 v141, 5, v141
	v_lshlrev_b32_e32 v141, 5, v141
	v_xor_b32_e32 v140, v140, v141
	v_add_u32_e32 v136, v139, v140
	v_add_u32_e32 v137, 0x40000, v136
	v_lshrrev_b32_e32 v139, 7, v142
	v_and_b32_e32 v141, 15, v142
	v_lshl_add_u32 v139, v139, 6, v141
	v_mul_u32_u24_e32 v139, 0x1600, v139
	v_lshrrev_b32_e32 v140, 6, v142
	v_and_b32_e32 v140, 1, v140
	v_lshlrev_b32_e32 v140, 6, v140
	v_lshrrev_b32_e32 v141, 4, v142
	v_and_b32_e32 v141, 3, v141
	v_lshl_add_u32 v140, v141, 3, v140
	v_add_u32_e32 v138, v139, v140
	v_and_b32_e32 v141, 1, v141
	v_mul_u32_u24_e32 v141, 24, v141
	v_add_u32_e32 v138, v138, v141
	v_lshlrev_b32_e32 v161, 11, v142
	v_lshrrev_b32_e32 v141, 6, v142
	v_lshlrev_b32_e32 v141, 10, v141
	s_nop 0
	v_readfirstlane_b32 s6, v141
	s_mov_b32 s10, s15

.LBB0_435:
	s_waitcnt vmcnt(5)
	s_barrier
	s_mul_i32 s12, s10, 0xc000
	v_add_u32_e32 v63, s12, v60
	v_add_u32_e32 v66, 0x2000, v63
	v_readfirstlane_b32 s12, v63
	v_lshl_add_u64 v[64:65], v[58:59], 0, s[2:3]
	s_mov_b32 m0, s12
	v_readfirstlane_b32 s12, v66
	v_add_u32_e32 v66, 0x4000, v63
	global_load_lds_dwordx4 v[64:65], off
	v_lshl_add_u64 v[64:65], v[56:57], 0, s[2:3]
	s_mov_b32 m0, s12
	v_readfirstlane_b32 s12, v66
	v_add_u32_e32 v66, 0x8000, v63
	global_load_lds_dwordx4 v[64:65], off
	v_lshl_add_u64 v[64:65], v[54:55], 0, s[2:3]
	s_mov_b32 m0, s12
	v_readfirstlane_b32 s12, v66
	v_add_u32_e32 v63, 0xa000, v63
	global_load_lds_dwordx4 v[64:65], off
	v_lshl_add_u64 v[64:65], v[52:53], 0, s[2:3]
	s_mov_b32 m0, s12
	v_readfirstlane_b32 s12, v63
	global_load_lds_dwordx4 v[64:65], off
	v_lshl_add_u64 v[64:65], v[50:51], 0, s[2:3]
	s_mov_b32 m0, s12
	s_mul_i32 s12, s11, 0xc000
	global_load_lds_dwordx4 v[64:65], off
	v_add_u32_e32 v63, s12, v61
	ds_read_b128 v[64:67], v63 offset:0
	ds_read_b128 v[68:71], v63 offset:2048
	ds_read_b128 v[72:75], v63 offset:4096
	v_add_u32_e32 v116, s12, v62
	ds_read_b128 v[76:79], v116 offset:0
	ds_read_b128 v[80:83], v116 offset:2048
	ds_read_b128 v[84:87], v116 offset:4096
	ds_read_b128 v[88:91], v116 offset:6144
	ds_read_b128 v[92:95], v63 offset:1024
	ds_read_b128 v[96:99], v63 offset:3072
	ds_read_b128 v[100:103], v63 offset:5120
	ds_read_b128 v[104:107], v116 offset:1024
	ds_read_b128 v[108:111], v116 offset:3072
	ds_read_b128 v[112:115], v116 offset:5120
	ds_read_b128 v[116:119], v116 offset:7168
	s_waitcnt lgkmcnt(7)
	s_nop 0
	v_mfma_f32_16x16x32_bf16 v[46:49], v[76:79], v[64:67], v[46:49]
	v_mfma_f32_16x16x32_bf16 v[42:45], v[80:83], v[64:67], v[42:45]
	v_mfma_f32_16x16x32_bf16 v[38:41], v[84:87], v[64:67], v[38:41]
	v_mfma_f32_16x16x32_bf16 v[34:37], v[88:91], v[64:67], v[34:37]
	v_mfma_f32_16x16x32_bf16 v[30:33], v[76:79], v[68:71], v[30:33]
	v_mfma_f32_16x16x32_bf16 v[26:29], v[80:83], v[68:71], v[26:29]
	v_mfma_f32_16x16x32_bf16 v[22:25], v[84:87], v[68:71], v[22:25]
	v_mfma_f32_16x16x32_bf16 v[18:21], v[88:91], v[68:71], v[18:21]
	v_mfma_f32_16x16x32_bf16 v[14:17], v[76:79], v[72:75], v[14:17]
	v_mfma_f32_16x16x32_bf16 v[10:13], v[80:83], v[72:75], v[10:13]
	v_mfma_f32_16x16x32_bf16 v[6:9], v[84:87], v[72:75], v[6:9]
	v_mfma_f32_16x16x32_bf16 v[2:5], v[88:91], v[72:75], v[2:5]
	s_waitcnt lgkmcnt(0)
	v_mfma_f32_16x16x32_bf16 v[46:49], v[104:107], v[92:95], v[46:49]
	v_mfma_f32_16x16x32_bf16 v[42:45], v[108:111], v[92:95], v[42:45]
	v_mfma_f32_16x16x32_bf16 v[38:41], v[112:115], v[92:95], v[38:41]
	v_mfma_f32_16x16x32_bf16 v[34:37], v[116:119], v[92:95], v[34:37]
	v_mfma_f32_16x16x32_bf16 v[30:33], v[104:107], v[96:99], v[30:33]
	v_mfma_f32_16x16x32_bf16 v[26:29], v[108:111], v[96:99], v[26:29]
	v_mfma_f32_16x16x32_bf16 v[22:25], v[112:115], v[96:99], v[22:25]
	v_mfma_f32_16x16x32_bf16 v[18:21], v[116:119], v[96:99], v[18:21]
	v_mfma_f32_16x16x32_bf16 v[14:17], v[104:107], v[100:103], v[14:17]
	v_mfma_f32_16x16x32_bf16 v[10:13], v[108:111], v[100:103], v[10:13]
	v_mfma_f32_16x16x32_bf16 v[6:9], v[112:115], v[100:103], v[6:9]
	v_mfma_f32_16x16x32_bf16 v[2:5], v[116:119], v[100:103], v[2:5]
	s_add_i32 s12, s11, 1
	s_cmp_lg_u32 s11, 2
	s_cselect_b32 s11, s12, 0
	s_add_i32 s12, s10, 1
	s_cmp_lg_u32 s10, 2
	s_cselect_b32 s10, s12, 0
	s_add_u32 s2, s2, 0x80
	s_addc_u32 s3, s3, 0
	s_cmpk_lg_i32 s2, 0x1500
	s_cbranch_scc1 .LBB0_435
	s_waitcnt vmcnt(5)
	s_mulk_i32 s9, 0xc0
	s_barrier
	ds_read_b128 v[50:53], v61 offset:0
	ds_read_b128 v[54:57], v61 offset:2048
	ds_read_b128 v[64:67], v61 offset:4096
	ds_read_b128 v[68:71], v62 offset:0
	ds_read_b128 v[72:75], v62 offset:2048
	ds_read_b128 v[76:79], v62 offset:4096
	ds_read_b128 v[80:83], v62 offset:6144
	ds_read_b128 v[84:87], v61 offset:1024
	ds_read_b128 v[88:91], v61 offset:3072
	ds_read_b128 v[92:95], v61 offset:5120
	ds_read_b128 v[96:99], v62 offset:1024
	ds_read_b128 v[100:103], v62 offset:3072
	ds_read_b128 v[104:107], v62 offset:5120
	ds_read_b128 v[108:111], v62 offset:7168
	v_and_b32_e32 v112, 64, v0
	s_waitcnt lgkmcnt(7)
	v_mfma_f32_16x16x32_bf16 v[46:49], v[68:71], v[50:53], v[46:49]
	v_mfma_f32_16x16x32_bf16 v[42:45], v[72:75], v[50:53], v[42:45]
	v_mfma_f32_16x16x32_bf16 v[38:41], v[76:79], v[50:53], v[38:41]
	v_mfma_f32_16x16x32_bf16 v[34:37], v[80:83], v[50:53], v[34:37]
	v_mfma_f32_16x16x32_bf16 v[30:33], v[68:71], v[54:57], v[30:33]
	v_mfma_f32_16x16x32_bf16 v[26:29], v[72:75], v[54:57], v[26:29]
	v_mfma_f32_16x16x32_bf16 v[22:25], v[76:79], v[54:57], v[22:25]
	v_mfma_f32_16x16x32_bf16 v[18:21], v[80:83], v[54:57], v[18:21]
	v_mfma_f32_16x16x32_bf16 v[14:17], v[68:71], v[64:67], v[14:17]
	v_mfma_f32_16x16x32_bf16 v[10:13], v[72:75], v[64:67], v[10:13]
	v_mfma_f32_16x16x32_bf16 v[6:9], v[76:79], v[64:67], v[6:9]
	v_mfma_f32_16x16x32_bf16 v[2:5], v[80:83], v[64:67], v[2:5]
	s_waitcnt lgkmcnt(0)
	v_mfma_f32_16x16x32_bf16 v[46:49], v[96:99], v[84:87], v[46:49]
	v_mfma_f32_16x16x32_bf16 v[42:45], v[100:103], v[84:87], v[42:45]
	v_mfma_f32_16x16x32_bf16 v[38:41], v[104:107], v[84:87], v[38:41]
	v_mfma_f32_16x16x32_bf16 v[34:37], v[108:111], v[84:87], v[34:37]
	v_mfma_f32_16x16x32_bf16 v[30:33], v[96:99], v[88:91], v[30:33]
	v_mfma_f32_16x16x32_bf16 v[26:29], v[100:103], v[88:91], v[26:29]
	v_mfma_f32_16x16x32_bf16 v[22:25], v[104:107], v[88:91], v[22:25]
	v_mfma_f32_16x16x32_bf16 v[18:21], v[108:111], v[88:91], v[18:21]
	v_mfma_f32_16x16x32_bf16 v[14:17], v[96:99], v[92:95], v[14:17]
	v_mfma_f32_16x16x32_bf16 v[10:13], v[100:103], v[92:95], v[10:13]
	v_mfma_f32_16x16x32_bf16 v[6:9], v[104:107], v[92:95], v[6:9]
	v_mfma_f32_16x16x32_bf16 v[2:5], v[108:111], v[92:95], v[2:5]
	s_waitcnt vmcnt(0)
	v_ashrrev_i32_e32 v106, 7, v0
	s_barrier
	v_add_u32_e32 v86, 0xc000, v61
	ds_read_b128 v[50:53], v86 offset:0
	ds_read_b128 v[54:57], v86 offset:2048
	ds_read_b128 v[58:61], v86 offset:4096
	v_add_u32_e32 v102, 0xc000, v62
	ds_read_b128 v[62:65], v102 offset:0
	ds_read_b128 v[66:69], v102 offset:2048
	ds_read_b128 v[70:73], v102 offset:4096
	ds_read_b128 v[74:77], v102 offset:6144
	ds_read_b128 v[78:81], v86 offset:1024
	ds_read_b128 v[82:85], v86 offset:3072
	ds_read_b128 v[86:89], v86 offset:5120
	ds_read_b128 v[90:93], v102 offset:1024
	ds_read_b128 v[94:97], v102 offset:3072
	ds_read_b128 v[98:101], v102 offset:5120
	ds_read_b128 v[102:105], v102 offset:7168
	s_waitcnt lgkmcnt(7)
	s_nop 0
	v_mfma_f32_16x16x32_bf16 v[46:49], v[62:65], v[50:53], v[46:49]
	v_mfma_f32_16x16x32_bf16 v[42:45], v[66:69], v[50:53], v[42:45]
	v_mfma_f32_16x16x32_bf16 v[38:41], v[70:73], v[50:53], v[38:41]
	v_mfma_f32_16x16x32_bf16 v[34:37], v[74:77], v[50:53], v[34:37]
	v_mfma_f32_16x16x32_bf16 v[30:33], v[62:65], v[54:57], v[30:33]
	v_mfma_f32_16x16x32_bf16 v[26:29], v[66:69], v[54:57], v[26:29]
	v_mfma_f32_16x16x32_bf16 v[22:25], v[70:73], v[54:57], v[22:25]
	v_mfma_f32_16x16x32_bf16 v[18:21], v[74:77], v[54:57], v[18:21]
	v_mfma_f32_16x16x32_bf16 v[14:17], v[62:65], v[58:61], v[14:17]
	v_mfma_f32_16x16x32_bf16 v[10:13], v[66:69], v[58:61], v[10:13]
	v_mfma_f32_16x16x32_bf16 v[6:9], v[70:73], v[58:61], v[6:9]
	v_mfma_f32_16x16x32_bf16 v[2:5], v[74:77], v[58:61], v[2:5]
	s_waitcnt lgkmcnt(0)
	v_mfma_f32_16x16x32_bf16 v[46:49], v[90:93], v[78:81], v[46:49]
	v_mfma_f32_16x16x32_bf16 v[42:45], v[94:97], v[78:81], v[42:45]
	v_mfma_f32_16x16x32_bf16 v[50:53], v[98:101], v[78:81], v[38:41]
	v_mfma_f32_16x16x32_bf16 v[54:57], v[102:105], v[78:81], v[34:37]
	v_mfma_f32_16x16x32_bf16 v[30:33], v[90:93], v[82:85], v[30:33]
	v_mfma_f32_16x16x32_bf16 v[26:29], v[94:97], v[82:85], v[26:29]
	v_mfma_f32_16x16x32_bf16 v[22:25], v[98:101], v[82:85], v[22:25]
	v_mfma_f32_16x16x32_bf16 v[18:21], v[102:105], v[82:85], v[18:21]
	v_mfma_f32_16x16x32_bf16 v[14:17], v[90:93], v[86:89], v[14:17]
	v_mfma_f32_16x16x32_bf16 v[10:13], v[94:97], v[86:89], v[10:13]
	v_mfma_f32_16x16x32_bf16 v[6:9], v[98:101], v[86:89], v[6:9]
	v_mfma_f32_16x16x32_bf16 v[2:5], v[102:105], v[86:89], v[2:5]
	s_nop 7
	v_readlane_b32 s68, v214, 57
	s_and_b32 s2, s7, 31
	s_mul_i32 s2, s2, 192
	s_lshr_b32 s3, s7, 5
	s_lshl_b32 s3, s3, 7
	s_mul_i32 s10, s68, 0x1b000
	s_add_u32 s10, s10, 0x8000
	s_add_u32 s38, s34, s10
	s_addc_u32 s39, s35, 0
	v_lshrrev_b32_e32 v128, 6, v142
	v_and_b32_e32 v129, 1, v128
	v_lshrrev_b32_e32 v128, 1, v128
	v_lshlrev_b32_e32 v66, 6, v129
	v_lshrrev_b32_e32 v129, 4, v142
	v_and_b32_e32 v129, 3, v129
	v_lshl_add_u32 v66, v129, 2, v66
	v_add_u32_e32 v66, s3, v66
	v_lshlrev_b32_e32 v66, 2, v66
	v_mul_u32_u24_e32 v67, 48, v128
	v_and_b32_e32 v129, 15, v142
	v_add3_u32 v67, v67, v129, s2
	v_add_u32_e32 v128, 0, v67
	v_lshl_add_u32 v141, v128, 12, v66
	v_add_u32_e32 v129, 0xfffff000, v128
	v_lshrrev_b32_e32 v129, 10, v129
	v_add_u32_e32 v129, 1, v129
	v_cmp_gt_u32_e32 vcc, 0x1000, v128
	v_cndmask_b32_e64 v129, v129, 0, vcc
	v_mul_u32_u24_e32 v129, 0x9000, v129
	v_add_u32_e32 v134, v129, v66
	global_load_dwordx4 v[68:71], v134, s[38:39] offset:0
	global_load_dwordx4 v[72:75], v134, s[38:39] offset:64
	global_load_dwordx4 v[76:79], v134, s[38:39] offset:128
	global_load_dwordx4 v[80:83], v134, s[38:39] offset:192
	v_add_u32_e32 v128, 16, v67
	v_lshl_add_u32 v162, v128, 12, v66
	v_add_u32_e32 v129, 0xfffff000, v128
	v_lshrrev_b32_e32 v129, 10, v129
	v_add_u32_e32 v129, 1, v129
	v_cmp_gt_u32_e32 vcc, 0x1000, v128
	v_cndmask_b32_e64 v129, v129, 0, vcc
	v_mul_u32_u24_e32 v129, 0x9000, v129
	v_add_u32_e32 v135, v129, v66
	global_load_dwordx4 v[84:87], v135, s[38:39] offset:0
	global_load_dwordx4 v[88:91], v135, s[38:39] offset:64
	global_load_dwordx4 v[92:95], v135, s[38:39] offset:128
	global_load_dwordx4 v[96:99], v135, s[38:39] offset:192
	v_add_u32_e32 v128, 32, v67
	v_lshl_add_u32 v163, v128, 12, v66
	v_add_u32_e32 v129, 0xfffff000, v128
	v_lshrrev_b32_e32 v129, 10, v129
	v_add_u32_e32 v129, 1, v129
	v_cmp_gt_u32_e32 vcc, 0x1000, v128
	v_cndmask_b32_e64 v129, v129, 0, vcc
	v_mul_u32_u24_e32 v129, 0x9000, v129
	v_add_u32_e32 v140, v129, v66
	global_load_dwordx4 v[100:103], v140, s[38:39] offset:0
	global_load_dwordx4 v[104:107], v140, s[38:39] offset:64
	global_load_dwordx4 v[108:111], v140, s[38:39] offset:128
	global_load_dwordx4 v[112:115], v140, s[38:39] offset:192
	global_load_dwordx4 v[116:119], v141, s[48:49] offset:0
	global_load_dwordx4 v[120:123], v141, s[48:49] offset:64
	global_load_dwordx4 v[124:127], v141, s[48:49] offset:128
	global_load_dwordx4 v[136:139], v141, s[48:49] offset:192
	global_load_dwordx4 v[164:167], v162, s[48:49] offset:0
	global_load_dwordx4 v[168:171], v162, s[48:49] offset:64
	global_load_dwordx4 v[172:175], v162, s[48:49] offset:128
	global_load_dwordx4 v[176:179], v162, s[48:49] offset:192
	global_load_dwordx4 v[180:183], v163, s[48:49] offset:0
	global_load_dwordx4 v[184:187], v163, s[48:49] offset:64
	global_load_dwordx4 v[188:191], v163, s[48:49] offset:128
	global_load_dwordx4 v[192:195], v163, s[48:49] offset:192
	s_waitcnt vmcnt(0)
	v_mul_f32_e32 v68, 0.5, v68
	v_mul_f32_e32 v69, 0.5, v69
	v_mul_f32_e32 v70, 0.5, v70
	v_mul_f32_e32 v71, 0.5, v71
	v_fma_f32 v116, v46, v68, v116
	v_fma_f32 v117, v47, v69, v117
	v_fma_f32 v118, v48, v70, v118
	v_fma_f32 v119, v49, v71, v119
	global_store_dwordx4 v141, v[116:119], s[48:49] offset:0
	v_mul_f32_e32 v72, 0.5, v72
	v_mul_f32_e32 v73, 0.5, v73
	v_mul_f32_e32 v74, 0.5, v74
	v_mul_f32_e32 v75, 0.5, v75
	v_fma_f32 v120, v42, v72, v120
	v_fma_f32 v121, v43, v73, v121
	v_fma_f32 v122, v44, v74, v122
	v_fma_f32 v123, v45, v75, v123
	global_store_dwordx4 v141, v[120:123], s[48:49] offset:64
	v_mul_f32_e32 v76, 0.5, v76
	v_mul_f32_e32 v77, 0.5, v77
	v_mul_f32_e32 v78, 0.5, v78
	v_mul_f32_e32 v79, 0.5, v79
	v_fma_f32 v124, v50, v76, v124
	v_fma_f32 v125, v51, v77, v125
	v_fma_f32 v126, v52, v78, v126
	v_fma_f32 v127, v53, v79, v127
	global_store_dwordx4 v141, v[124:127], s[48:49] offset:128
	v_mul_f32_e32 v80, 0.5, v80
	v_mul_f32_e32 v81, 0.5, v81
	v_mul_f32_e32 v82, 0.5, v82
	v_mul_f32_e32 v83, 0.5, v83
	v_fma_f32 v136, v54, v80, v136
	v_fma_f32 v137, v55, v81, v137
	v_fma_f32 v138, v56, v82, v138
	v_fma_f32 v139, v57, v83, v139
	global_store_dwordx4 v141, v[136:139], s[48:49] offset:192
	v_mul_f32_e32 v84, 0.5, v84
	v_mul_f32_e32 v85, 0.5, v85
	v_mul_f32_e32 v86, 0.5, v86
	v_mul_f32_e32 v87, 0.5, v87
	v_fma_f32 v164, v30, v84, v164
	v_fma_f32 v165, v31, v85, v165
	v_fma_f32 v166, v32, v86, v166
	v_fma_f32 v167, v33, v87, v167
	global_store_dwordx4 v162, v[164:167], s[48:49] offset:0
	v_mul_f32_e32 v88, 0.5, v88
	v_mul_f32_e32 v89, 0.5, v89
	v_mul_f32_e32 v90, 0.5, v90
	v_mul_f32_e32 v91, 0.5, v91
	v_fma_f32 v168, v26, v88, v168
	v_fma_f32 v169, v27, v89, v169
	v_fma_f32 v170, v28, v90, v170
	v_fma_f32 v171, v29, v91, v171
	global_store_dwordx4 v162, v[168:171], s[48:49] offset:64
	v_mul_f32_e32 v92, 0.5, v92
	v_mul_f32_e32 v93, 0.5, v93
	v_mul_f32_e32 v94, 0.5, v94
	v_mul_f32_e32 v95, 0.5, v95
	v_fma_f32 v172, v22, v92, v172
	v_fma_f32 v173, v23, v93, v173
	v_fma_f32 v174, v24, v94, v174
	v_fma_f32 v175, v25, v95, v175
	global_store_dwordx4 v162, v[172:175], s[48:49] offset:128
	v_mul_f32_e32 v96, 0.5, v96
	v_mul_f32_e32 v97, 0.5, v97
	v_mul_f32_e32 v98, 0.5, v98
	v_mul_f32_e32 v99, 0.5, v99
	v_fma_f32 v176, v18, v96, v176
	v_fma_f32 v177, v19, v97, v177
	v_fma_f32 v178, v20, v98, v178
	v_fma_f32 v179, v21, v99, v179
	global_store_dwordx4 v162, v[176:179], s[48:49] offset:192
	v_mul_f32_e32 v100, 0.5, v100
	v_mul_f32_e32 v101, 0.5, v101
	v_mul_f32_e32 v102, 0.5, v102
	v_mul_f32_e32 v103, 0.5, v103
	v_fma_f32 v180, v14, v100, v180
	v_fma_f32 v181, v15, v101, v181
	v_fma_f32 v182, v16, v102, v182
	v_fma_f32 v183, v17, v103, v183
	global_store_dwordx4 v163, v[180:183], s[48:49] offset:0
	v_mul_f32_e32 v104, 0.5, v104
	v_mul_f32_e32 v105, 0.5, v105
	v_mul_f32_e32 v106, 0.5, v106
	v_mul_f32_e32 v107, 0.5, v107
	v_fma_f32 v184, v10, v104, v184
	v_fma_f32 v185, v11, v105, v185
	v_fma_f32 v186, v12, v106, v186
	v_fma_f32 v187, v13, v107, v187
	global_store_dwordx4 v163, v[184:187], s[48:49] offset:64
	v_mul_f32_e32 v108, 0.5, v108
	v_mul_f32_e32 v109, 0.5, v109
	v_mul_f32_e32 v110, 0.5, v110
	v_mul_f32_e32 v111, 0.5, v111
	v_fma_f32 v188, v6, v108, v188
	v_fma_f32 v189, v7, v109, v189
	v_fma_f32 v190, v8, v110, v190
	v_fma_f32 v191, v9, v111, v191
	global_store_dwordx4 v163, v[188:191], s[48:49] offset:128
	v_mul_f32_e32 v112, 0.5, v112
	v_mul_f32_e32 v113, 0.5, v113
	v_mul_f32_e32 v114, 0.5, v114
	v_mul_f32_e32 v115, 0.5, v115
	v_fma_f32 v192, v2, v112, v192
	v_fma_f32 v193, v3, v113, v193
	v_fma_f32 v194, v4, v114, v194
	v_fma_f32 v195, v5, v115, v195
	global_store_dwordx4 v163, v[192:195], s[48:49] offset:192
	s_add_i32 s7, s7, s84
	s_cmpk_gt_i32 s7, 0xff
	s_cbranch_scc0 .LBB0_434

.LBB0_438:
	s_andn2_b64 vcc, exec, s[2:3]
	s_cbranch_vccnz .LBB0_463
	v_readlane_b32 s4, v217, 0
	v_readlane_b32 s5, v214, 57
	v_readlane_b32 s38, v217, 1
	v_readlane_b32 s39, v217, 2
	v_lshrrev_b32_e32 v197, 6, v142
	s_sub_u32 s38, s38, 0xd0
	s_subb_u32 s39, s39, 0
	v_readfirstlane_b32 s6, v197
	s_load_dwordx4 s[40:43], s[38:39], 0x0
	s_load_dwordx2 s[38:39], s[38:39], 0x40
	v_and_b32_e32 v194, 63, v142
	v_lshlrev_b32_e32 v195, 3, v194
	v_lshlrev_b32_e32 v194, 4, v194
	v_mov_b32_e32 v196, 0x358637bd
	s_lshr_b32 s7, s4, 3
	s_lshl_b32 s7, s7, 3
	s_add_u32 s7, s7, s6
	s_and_b32 s10, s4, 7
	s_mul_i32 s10, s10, 192
	s_add_u32 s11, s7, 0
	s_mul_i32 s12, s11, 43691
	s_lshr_b32 s12, s12, 23
	s_mul_i32 s12, s12, 1344
	s_add_u32 s11, s11, s12
	s_add_u32 s98, s11, s10
	s_add_u32 s11, s7, 256
	s_mul_i32 s12, s11, 43691
	s_lshr_b32 s12, s12, 23
	s_mul_i32 s12, s12, 1344
	s_add_u32 s11, s11, s12
	s_add_u32 s99, s11, s10
	s_add_u32 s11, s7, 512
	s_mul_i32 s12, s11, 43691
	s_lshr_b32 s12, s12, 23
	s_mul_i32 s12, s12, 1344
	s_add_u32 s11, s11, s12
	s_add_u32 s17, s11, s10
	s_waitcnt lgkmcnt(0)
	s_lshl_b32 s11, s98, 12
	s_add_u32 s68, s48, s11
	s_addc_u32 s69, s49, 0
	s_cmp_lg_u32 s5, 0
	s_cbranch_scc1 .Lnrm_n0_x0
	s_add_u32 s68, s40, s11
	s_addc_u32 s69, s41, 0
	s_cmp_lt_u32 s98, 0x1000
	s_cbranch_scc1 .Lnrm_n0_x0
	s_sub_u32 s11, s11, 0x1000000
	s_add_u32 s68, s42, s11
	s_addc_u32 s69, s43, 0
.Lnrm_n0_x0:
	global_load_dwordx4 v[2:5], v194, s[68:69] offset:0
	global_load_dwordx4 v[6:9], v194, s[68:69] offset:1024
	global_load_dwordx4 v[10:13], v194, s[68:69] offset:2048
	global_load_dwordx4 v[14:17], v194, s[68:69] offset:3072
	s_lshl_b32 s11, s99, 12
	s_add_u32 s70, s48, s11
	s_addc_u32 s71, s49, 0
	s_cmp_lg_u32 s5, 0
	s_cbranch_scc1 .Lnrm_n0_x1
	s_add_u32 s70, s40, s11
	s_addc_u32 s71, s41, 0
	s_cmp_lt_u32 s99, 0x1000
	s_cbranch_scc1 .Lnrm_n0_x1
	s_sub_u32 s11, s11, 0x1000000
	s_add_u32 s70, s42, s11
	s_addc_u32 s71, s43, 0
.Lnrm_n0_x1:
	global_load_dwordx4 v[18:21], v194, s[70:71] offset:0
	global_load_dwordx4 v[22:25], v194, s[70:71] offset:1024
	global_load_dwordx4 v[26:29], v194, s[70:71] offset:2048
	global_load_dwordx4 v[30:33], v194, s[70:71] offset:3072
	s_lshl_b32 s11, s17, 12
	s_add_u32 s72, s48, s11
	s_addc_u32 s73, s49, 0
	s_cmp_lg_u32 s5, 0
	s_cbranch_scc1 .Lnrm_n0_x2
	s_add_u32 s72, s40, s11
	s_addc_u32 s73, s41, 0
	s_cmp_lt_u32 s17, 0x1000
	s_cbranch_scc1 .Lnrm_n0_x2
	s_sub_u32 s11, s11, 0x1000000
	s_add_u32 s72, s42, s11
	s_addc_u32 s73, s43, 0
.Lnrm_n0_x2:
	global_load_dwordx4 v[34:37], v194, s[72:73] offset:0
	global_load_dwordx4 v[38:41], v194, s[72:73] offset:1024
	global_load_dwordx4 v[42:45], v194, s[72:73] offset:2048
	global_load_dwordx4 v[46:49], v194, s[72:73] offset:3072
	s_mov_b32 s42, s17
	s_mul_i32 s11, s5, 3
	s_add_u32 s11, s11, 0
	s_lshl_b32 s11, s11, 12
	s_add_u32 s38, s38, s11
	s_addc_u32 s39, s39, 0
	global_load_dwordx4 v[50:53], v194, s[38:39] offset:0
	global_load_dwordx4 v[54:57], v194, s[38:39] offset:1024
	global_load_dwordx4 v[58:61], v194, s[38:39] offset:2048
	global_load_dwordx4 v[62:65], v194, s[38:39] offset:3072
	s_sub_u32 s11, s98, 0x1000
	s_lshr_b32 s11, s11, 10
	s_add_u32 s11, s11, 1
	s_cmp_lt_u32 s98, 0x1000
	s_cselect_b32 s11, 0, s11
	s_mul_i32 s12, s5, 3
	s_add_u32 s11, s11, s12
	s_mul_i32 s11, s11, 0x9000
	s_add_u32 s11, s11, 0x0
	s_add_u32 s74, s34, s11
	s_addc_u32 s75, s35, 0
	s_add_u32 s80, s74, 0x1000
	s_addc_u32 s81, s75, 0
	global_load_dwordx4 v[66:69], v194, s[74:75] offset:0
	global_load_dwordx4 v[70:73], v194, s[74:75] offset:1024
	global_load_dwordx4 v[74:77], v194, s[74:75] offset:2048
	global_load_dwordx4 v[78:81], v194, s[74:75] offset:3072
	global_load_dwordx4 v[114:117], v194, s[80:81] offset:0
	global_load_dwordx4 v[118:121], v194, s[80:81] offset:1024
	global_load_dwordx4 v[122:125], v194, s[80:81] offset:2048
	global_load_dwordx4 v[126:129], v194, s[80:81] offset:3072
	s_sub_u32 s11, s99, 0x1000
	s_lshr_b32 s11, s11, 10
	s_add_u32 s11, s11, 1
	s_cmp_lt_u32 s99, 0x1000
	s_cselect_b32 s11, 0, s11
	s_mul_i32 s12, s5, 3
	s_add_u32 s11, s11, s12
	s_mul_i32 s11, s11, 0x9000
	s_add_u32 s11, s11, 0x0
	s_add_u32 s76, s34, s11
	s_addc_u32 s77, s35, 0
	s_add_u32 s82, s76, 0x1000
	s_addc_u32 s83, s77, 0
	global_load_dwordx4 v[82:85], v194, s[76:77] offset:0
	global_load_dwordx4 v[86:89], v194, s[76:77] offset:1024
	global_load_dwordx4 v[90:93], v194, s[76:77] offset:2048
	global_load_dwordx4 v[94:97], v194, s[76:77] offset:3072
	global_load_dwordx4 v[162:165], v194, s[82:83] offset:0
	global_load_dwordx4 v[166:169], v194, s[82:83] offset:1024
	global_load_dwordx4 v[170:173], v194, s[82:83] offset:2048
	global_load_dwordx4 v[174:177], v194, s[82:83] offset:3072
	s_sub_u32 s11, s42, 0x1000
	s_lshr_b32 s11, s11, 10
	s_add_u32 s11, s11, 1
	s_cmp_lt_u32 s42, 0x1000
	s_cselect_b32 s11, 0, s11
	s_mul_i32 s12, s5, 3
	s_add_u32 s11, s11, s12
	s_mul_i32 s11, s11, 0x9000
	s_add_u32 s11, s11, 0x0
	s_add_u32 s78, s34, s11
	s_addc_u32 s79, s35, 0
	s_add_u32 s92, s78, 0x1000
	s_addc_u32 s93, s79, 0
	global_load_dwordx4 v[98:101], v194, s[78:79] offset:0
	global_load_dwordx4 v[102:105], v194, s[78:79] offset:1024
	global_load_dwordx4 v[106:109], v194, s[78:79] offset:2048
	global_load_dwordx4 v[110:113], v194, s[78:79] offset:3072
	global_load_dwordx4 v[178:181], v194, s[92:93] offset:0
	global_load_dwordx4 v[182:185], v194, s[92:93] offset:1024
	global_load_dwordx4 v[186:189], v194, s[92:93] offset:2048
	global_load_dwordx4 v[190:193], v194, s[92:93] offset:3072
	s_waitcnt vmcnt(28)
	s_lshl_b32 s11, s98, 11
	s_add_u32 s68, s24, s11
	s_addc_u32 s69, s25, 0
	s_lshl_b32 s11, s99, 11
	s_add_u32 s70, s24, s11
	s_addc_u32 s71, s25, 0
	s_lshl_b32 s11, s42, 11
	s_add_u32 s72, s24, s11
	s_addc_u32 s73, s25, 0
	v_mul_f32_e32 v198, v2, v2
	v_mul_f32_e32 v199, v18, v18
	v_mul_f32_e32 v200, v34, v34
	v_fmac_f32_e32 v198, v3, v3
	v_fmac_f32_e32 v199, v19, v19
	v_fmac_f32_e32 v200, v35, v35
	v_fmac_f32_e32 v198, v4, v4
	v_fmac_f32_e32 v199, v20, v20
	v_fmac_f32_e32 v200, v36, v36
	v_fmac_f32_e32 v198, v5, v5
	v_fmac_f32_e32 v199, v21, v21
	v_fmac_f32_e32 v200, v37, v37
	v_fmac_f32_e32 v198, v6, v6
	v_fmac_f32_e32 v199, v22, v22
	v_fmac_f32_e32 v200, v38, v38
	v_fmac_f32_e32 v198, v7, v7
	v_fmac_f32_e32 v199, v23, v23
	v_fmac_f32_e32 v200, v39, v39
	v_fmac_f32_e32 v198, v8, v8
	v_fmac_f32_e32 v199, v24, v24
	v_fmac_f32_e32 v200, v40, v40
	v_fmac_f32_e32 v198, v9, v9
	v_fmac_f32_e32 v199, v25, v25
	v_fmac_f32_e32 v200, v41, v41
	v_fmac_f32_e32 v198, v10, v10
	v_fmac_f32_e32 v199, v26, v26
	v_fmac_f32_e32 v200, v42, v42
	v_fmac_f32_e32 v198, v11, v11
	v_fmac_f32_e32 v199, v27, v27
	v_fmac_f32_e32 v200, v43, v43
	v_fmac_f32_e32 v198, v12, v12
	v_fmac_f32_e32 v199, v28, v28
	v_fmac_f32_e32 v200, v44, v44
	v_fmac_f32_e32 v198, v13, v13
	v_fmac_f32_e32 v199, v29, v29
	v_fmac_f32_e32 v200, v45, v45
	v_fmac_f32_e32 v198, v14, v14
	v_fmac_f32_e32 v199, v30, v30
	v_fmac_f32_e32 v200, v46, v46
	v_fmac_f32_e32 v198, v15, v15
	v_fmac_f32_e32 v199, v31, v31
	v_fmac_f32_e32 v200, v47, v47
	v_fmac_f32_e32 v198, v16, v16
	v_fmac_f32_e32 v199, v32, v32
	v_fmac_f32_e32 v200, v48, v48
	v_fmac_f32_e32 v198, v17, v17
	v_fmac_f32_e32 v199, v33, v33
	v_fmac_f32_e32 v200, v49, v49
	s_nop 1
	v_add_f32_dpp v198, v198, v198 quad_perm:[1,0,3,2] row_mask:0xf bank_mask:0xf
	v_add_f32_dpp v199, v199, v199 quad_perm:[1,0,3,2] row_mask:0xf bank_mask:0xf
	v_add_f32_dpp v200, v200, v200 quad_perm:[1,0,3,2] row_mask:0xf bank_mask:0xf
	s_nop 1
	v_add_f32_dpp v198, v198, v198 quad_perm:[2,3,0,1] row_mask:0xf bank_mask:0xf
	v_add_f32_dpp v199, v199, v199 quad_perm:[2,3,0,1] row_mask:0xf bank_mask:0xf
	v_add_f32_dpp v200, v200, v200 quad_perm:[2,3,0,1] row_mask:0xf bank_mask:0xf
	s_nop 1
	v_add_f32_dpp v198, v198, v198 row_half_mirror row_mask:0xf bank_mask:0xf
	v_add_f32_dpp v199, v199, v199 row_half_mirror row_mask:0xf bank_mask:0xf
	v_add_f32_dpp v200, v200, v200 row_half_mirror row_mask:0xf bank_mask:0xf
	s_nop 1
	v_add_f32_dpp v198, v198, v198 row_mirror row_mask:0xf bank_mask:0xf
	v_add_f32_dpp v199, v199, v199 row_mirror row_mask:0xf bank_mask:0xf
	v_add_f32_dpp v200, v200, v200 row_mirror row_mask:0xf bank_mask:0xf
	s_nop 1
	v_add_f32_dpp v198, v198, v198 row_bcast:15 row_mask:0xa bank_mask:0xf
	v_add_f32_dpp v199, v199, v199 row_bcast:15 row_mask:0xa bank_mask:0xf
	v_add_f32_dpp v200, v200, v200 row_bcast:15 row_mask:0xa bank_mask:0xf
	s_nop 1
	v_add_f32_dpp v198, v198, v198 row_bcast:31 row_mask:0xc bank_mask:0xf
	v_add_f32_dpp v199, v199, v199 row_bcast:31 row_mask:0xc bank_mask:0xf
	v_add_f32_dpp v200, v200, v200 row_bcast:31 row_mask:0xc bank_mask:0xf
	s_nop 1
	v_readlane_b32 s32, v198, 63
	v_readlane_b32 s20, v199, 63
	v_readlane_b32 s94, v200, 63
	s_nop 0
	v_mov_b32_e32 v201, s32
	v_mov_b32_e32 v202, s20
	v_mov_b32_e32 v203, s94
	v_fmamk_f32 v201, v201, 0x3a800000, v196
	v_fmamk_f32 v202, v202, 0x3a800000, v196
	v_fmamk_f32 v203, v203, 0x3a800000, v196
	v_rsq_f32_e32 v201, v201
	v_rsq_f32_e32 v202, v202
	v_rsq_f32_e32 v203, v203
	s_waitcnt vmcnt(0)
	v_mul_f32_e32 v204, v2, v201
	v_mul_f32_e32 v205, v3, v201
	v_mul_f32_e32 v206, v4, v201
	v_mul_f32_e32 v207, v5, v201
	v_mul_f32_e32 v204, v50, v204
	v_mul_f32_e32 v205, v51, v205
	v_mul_f32_e32 v206, v52, v206
	v_mul_f32_e32 v207, v53, v207
	v_add_f32_e32 v114, 1.0, v114
	v_add_f32_e32 v115, 1.0, v115
	v_add_f32_e32 v116, 1.0, v116
	v_add_f32_e32 v117, 1.0, v117
	v_fma_f32 v204, v114, v204, v66
	v_fma_f32 v205, v115, v205, v67
	v_fma_f32 v206, v116, v206, v68
	v_fma_f32 v207, v117, v207, v69
	v_cvt_pk_bf16_f32 v208, v204, v205
	v_cvt_pk_bf16_f32 v209, v206, v207
	global_store_dwordx2 v195, v[208:209], s[68:69] offset:0
	v_mul_f32_e32 v204, v6, v201
	v_mul_f32_e32 v205, v7, v201
	v_mul_f32_e32 v206, v8, v201
	v_mul_f32_e32 v207, v9, v201
	v_mul_f32_e32 v204, v54, v204
	v_mul_f32_e32 v205, v55, v205
	v_mul_f32_e32 v206, v56, v206
	v_mul_f32_e32 v207, v57, v207
	v_add_f32_e32 v118, 1.0, v118
	v_add_f32_e32 v119, 1.0, v119
	v_add_f32_e32 v120, 1.0, v120
	v_add_f32_e32 v121, 1.0, v121
	v_fma_f32 v204, v118, v204, v70
	v_fma_f32 v205, v119, v205, v71
	v_fma_f32 v206, v120, v206, v72
	v_fma_f32 v207, v121, v207, v73
	v_cvt_pk_bf16_f32 v210, v204, v205
	v_cvt_pk_bf16_f32 v211, v206, v207
	global_store_dwordx2 v195, v[210:211], s[68:69] offset:512
	v_mul_f32_e32 v204, v10, v201
	v_mul_f32_e32 v205, v11, v201
	v_mul_f32_e32 v206, v12, v201
	v_mul_f32_e32 v207, v13, v201
	v_mul_f32_e32 v204, v58, v204
	v_mul_f32_e32 v205, v59, v205
	v_mul_f32_e32 v206, v60, v206
	v_mul_f32_e32 v207, v61, v207
	v_add_f32_e32 v122, 1.0, v122
	v_add_f32_e32 v123, 1.0, v123
	v_add_f32_e32 v124, 1.0, v124
	v_add_f32_e32 v125, 1.0, v125
	v_fma_f32 v204, v122, v204, v74
	v_fma_f32 v205, v123, v205, v75
	v_fma_f32 v206, v124, v206, v76
	v_fma_f32 v207, v125, v207, v77
	v_cvt_pk_bf16_f32 v208, v204, v205
	v_cvt_pk_bf16_f32 v209, v206, v207
	global_store_dwordx2 v195, v[208:209], s[68:69] offset:1024
	v_mul_f32_e32 v204, v14, v201
	v_mul_f32_e32 v205, v15, v201
	v_mul_f32_e32 v206, v16, v201
	v_mul_f32_e32 v207, v17, v201
	v_mul_f32_e32 v204, v62, v204
	v_mul_f32_e32 v205, v63, v205
	v_mul_f32_e32 v206, v64, v206
	v_mul_f32_e32 v207, v65, v207
	v_add_f32_e32 v126, 1.0, v126
	v_add_f32_e32 v127, 1.0, v127
	v_add_f32_e32 v128, 1.0, v128
	v_add_f32_e32 v129, 1.0, v129
	v_fma_f32 v204, v126, v204, v78
	v_fma_f32 v205, v127, v205, v79
	v_fma_f32 v206, v128, v206, v80
	v_fma_f32 v207, v129, v207, v81
	v_cvt_pk_bf16_f32 v210, v204, v205
	v_cvt_pk_bf16_f32 v211, v206, v207
	global_store_dwordx2 v195, v[210:211], s[68:69] offset:1536
	v_mul_f32_e32 v204, v18, v202
	v_mul_f32_e32 v205, v19, v202
	v_mul_f32_e32 v206, v20, v202
	v_mul_f32_e32 v207, v21, v202
	v_mul_f32_e32 v204, v50, v204
	v_mul_f32_e32 v205, v51, v205
	v_mul_f32_e32 v206, v52, v206
	v_mul_f32_e32 v207, v53, v207
	v_add_f32_e32 v162, 1.0, v162
	v_add_f32_e32 v163, 1.0, v163
	v_add_f32_e32 v164, 1.0, v164
	v_add_f32_e32 v165, 1.0, v165
	v_fma_f32 v204, v162, v204, v82
	v_fma_f32 v205, v163, v205, v83
	v_fma_f32 v206, v164, v206, v84
	v_fma_f32 v207, v165, v207, v85
	v_cvt_pk_bf16_f32 v208, v204, v205
	v_cvt_pk_bf16_f32 v209, v206, v207
	global_store_dwordx2 v195, v[208:209], s[70:71] offset:0
	v_mul_f32_e32 v204, v22, v202
	v_mul_f32_e32 v205, v23, v202
	v_mul_f32_e32 v206, v24, v202
	v_mul_f32_e32 v207, v25, v202
	v_mul_f32_e32 v204, v54, v204
	v_mul_f32_e32 v205, v55, v205
	v_mul_f32_e32 v206, v56, v206
	v_mul_f32_e32 v207, v57, v207
	v_add_f32_e32 v166, 1.0, v166
	v_add_f32_e32 v167, 1.0, v167
	v_add_f32_e32 v168, 1.0, v168
	v_add_f32_e32 v169, 1.0, v169
	v_fma_f32 v204, v166, v204, v86
	v_fma_f32 v205, v167, v205, v87
	v_fma_f32 v206, v168, v206, v88
	v_fma_f32 v207, v169, v207, v89
	v_cvt_pk_bf16_f32 v210, v204, v205
	v_cvt_pk_bf16_f32 v211, v206, v207
	global_store_dwordx2 v195, v[210:211], s[70:71] offset:512
	v_mul_f32_e32 v204, v26, v202
	v_mul_f32_e32 v205, v27, v202
	v_mul_f32_e32 v206, v28, v202
	v_mul_f32_e32 v207, v29, v202
	v_mul_f32_e32 v204, v58, v204
	v_mul_f32_e32 v205, v59, v205
	v_mul_f32_e32 v206, v60, v206
	v_mul_f32_e32 v207, v61, v207
	v_add_f32_e32 v170, 1.0, v170
	v_add_f32_e32 v171, 1.0, v171
	v_add_f32_e32 v172, 1.0, v172
	v_add_f32_e32 v173, 1.0, v173
	v_fma_f32 v204, v170, v204, v90
	v_fma_f32 v205, v171, v205, v91
	v_fma_f32 v206, v172, v206, v92
	v_fma_f32 v207, v173, v207, v93
	v_cvt_pk_bf16_f32 v208, v204, v205
	v_cvt_pk_bf16_f32 v209, v206, v207
	global_store_dwordx2 v195, v[208:209], s[70:71] offset:1024
	v_mul_f32_e32 v204, v30, v202
	v_mul_f32_e32 v205, v31, v202
	v_mul_f32_e32 v206, v32, v202
	v_mul_f32_e32 v207, v33, v202
	v_mul_f32_e32 v204, v62, v204
	v_mul_f32_e32 v205, v63, v205
	v_mul_f32_e32 v206, v64, v206
	v_mul_f32_e32 v207, v65, v207
	v_add_f32_e32 v174, 1.0, v174
	v_add_f32_e32 v175, 1.0, v175
	v_add_f32_e32 v176, 1.0, v176
	v_add_f32_e32 v177, 1.0, v177
	v_fma_f32 v204, v174, v204, v94
	v_fma_f32 v205, v175, v205, v95
	v_fma_f32 v206, v176, v206, v96
	v_fma_f32 v207, v177, v207, v97
	v_cvt_pk_bf16_f32 v210, v204, v205
	v_cvt_pk_bf16_f32 v211, v206, v207
	global_store_dwordx2 v195, v[210:211], s[70:71] offset:1536
	v_mul_f32_e32 v204, v34, v203
	v_mul_f32_e32 v205, v35, v203
	v_mul_f32_e32 v206, v36, v203
	v_mul_f32_e32 v207, v37, v203
	v_mul_f32_e32 v204, v50, v204
	v_mul_f32_e32 v205, v51, v205
	v_mul_f32_e32 v206, v52, v206
	v_mul_f32_e32 v207, v53, v207
	v_add_f32_e32 v178, 1.0, v178
	v_add_f32_e32 v179, 1.0, v179
	v_add_f32_e32 v180, 1.0, v180
	v_add_f32_e32 v181, 1.0, v181
	v_fma_f32 v204, v178, v204, v98
	v_fma_f32 v205, v179, v205, v99
	v_fma_f32 v206, v180, v206, v100
	v_fma_f32 v207, v181, v207, v101
	v_cvt_pk_bf16_f32 v208, v204, v205
	v_cvt_pk_bf16_f32 v209, v206, v207
	global_store_dwordx2 v195, v[208:209], s[72:73] offset:0
	v_mul_f32_e32 v204, v38, v203
	v_mul_f32_e32 v205, v39, v203
	v_mul_f32_e32 v206, v40, v203
	v_mul_f32_e32 v207, v41, v203
	v_mul_f32_e32 v204, v54, v204
	v_mul_f32_e32 v205, v55, v205
	v_mul_f32_e32 v206, v56, v206
	v_mul_f32_e32 v207, v57, v207
	v_add_f32_e32 v182, 1.0, v182
	v_add_f32_e32 v183, 1.0, v183
	v_add_f32_e32 v184, 1.0, v184
	v_add_f32_e32 v185, 1.0, v185
	v_fma_f32 v204, v182, v204, v102
	v_fma_f32 v205, v183, v205, v103
	v_fma_f32 v206, v184, v206, v104
	v_fma_f32 v207, v185, v207, v105
	v_cvt_pk_bf16_f32 v210, v204, v205
	v_cvt_pk_bf16_f32 v211, v206, v207
	global_store_dwordx2 v195, v[210:211], s[72:73] offset:512
	v_mul_f32_e32 v204, v42, v203
	v_mul_f32_e32 v205, v43, v203
	v_mul_f32_e32 v206, v44, v203
	v_mul_f32_e32 v207, v45, v203
	v_mul_f32_e32 v204, v58, v204
	v_mul_f32_e32 v205, v59, v205
	v_mul_f32_e32 v206, v60, v206
	v_mul_f32_e32 v207, v61, v207
	v_add_f32_e32 v186, 1.0, v186
	v_add_f32_e32 v187, 1.0, v187
	v_add_f32_e32 v188, 1.0, v188
	v_add_f32_e32 v189, 1.0, v189
	v_fma_f32 v204, v186, v204, v106
	v_fma_f32 v205, v187, v205, v107
	v_fma_f32 v206, v188, v206, v108
	v_fma_f32 v207, v189, v207, v109
	v_cvt_pk_bf16_f32 v208, v204, v205
	v_cvt_pk_bf16_f32 v209, v206, v207
	global_store_dwordx2 v195, v[208:209], s[72:73] offset:1024
	v_mul_f32_e32 v204, v46, v203
	v_mul_f32_e32 v205, v47, v203
	v_mul_f32_e32 v206, v48, v203
	v_mul_f32_e32 v207, v49, v203
	v_mul_f32_e32 v204, v62, v204
	v_mul_f32_e32 v205, v63, v205
	v_mul_f32_e32 v206, v64, v206
	v_mul_f32_e32 v207, v65, v207
	v_add_f32_e32 v190, 1.0, v190
	v_add_f32_e32 v191, 1.0, v191
	v_add_f32_e32 v192, 1.0, v192
	v_add_f32_e32 v193, 1.0, v193
	v_fma_f32 v204, v190, v204, v110
	v_fma_f32 v205, v191, v205, v111
	v_fma_f32 v206, v192, v206, v112
	v_fma_f32 v207, v193, v207, v113
	v_cvt_pk_bf16_f32 v210, v204, v205
	v_cvt_pk_bf16_f32 v211, v206, v207
	global_store_dwordx2 v195, v[210:211], s[72:73] offset:1536
	s_branch .LBB0_463

	.amdhsa_kernel _Z10fwd_kernel6Params
		.amdhsa_group_segment_fixed_size 0
		.amdhsa_private_segment_fixed_size 0
		.amdhsa_kernarg_size 464
		.amdhsa_user_sgpr_count 2
		.amdhsa_user_sgpr_dispatch_ptr 0
		.amdhsa_user_sgpr_queue_ptr 0
		.amdhsa_user_sgpr_kernarg_segment_ptr 1
		.amdhsa_user_sgpr_dispatch_id 0
		.amdhsa_user_sgpr_kernarg_preload_length 0
		.amdhsa_user_sgpr_kernarg_preload_offset 0
		.amdhsa_user_sgpr_private_segment_size 0
		.amdhsa_uses_dynamic_stack 0
		.amdhsa_enable_private_segment 0
		.amdhsa_system_sgpr_workgroup_id_x 1
		.amdhsa_system_sgpr_workgroup_id_y 0
		.amdhsa_system_sgpr_workgroup_id_z 0
		.amdhsa_system_sgpr_workgroup_info 0
		.amdhsa_system_vgpr_workitem_id 2
		.amdhsa_next_free_vgpr 256
		.amdhsa_next_free_sgpr 100
		.amdhsa_accum_offset 256
		.amdhsa_reserve_vcc 1
		.amdhsa_float_round_mode_32 0
		.amdhsa_float_round_mode_16_64 0
		.amdhsa_float_denorm_mode_32 3
		.amdhsa_float_denorm_mode_16_64 3
		.amdhsa_dx10_clamp 1
		.amdhsa_ieee_mode 1
		.amdhsa_fp16_overflow 0
		.amdhsa_tg_split 0
		.amdhsa_exception_fp_ieee_invalid_op 0
		.amdhsa_exception_fp_denorm_src 0
		.amdhsa_exception_fp_ieee_div_zero 0
		.amdhsa_exception_fp_ieee_overflow 0
		.amdhsa_exception_fp_ieee_underflow 0
		.amdhsa_exception_fp_ieee_inexact 0
		.amdhsa_exception_int_div_zero 0
	.end_amdhsa_kernel

.Lfunc_end0:
	.size	_Z10fwd_kernel6Params, .Lfunc_end0-_Z10fwd_kernel6Params
	.set _Z10fwd_kernel6Params.num_vgpr, 256
	.set _Z10fwd_kernel6Params.num_agpr, 0
	.set _Z10fwd_kernel6Params.numbered_sgpr, 100
	.set _Z10fwd_kernel6Params.num_named_barrier, 0
	.set _Z10fwd_kernel6Params.private_seg_size, 0
	.set _Z10fwd_kernel6Params.uses_vcc, 1
	.set _Z10fwd_kernel6Params.uses_flat_scratch, 0
	.set _Z10fwd_kernel6Params.has_dyn_sized_stack, 0
	.set _Z10fwd_kernel6Params.has_recursion, 0
	.set _Z10fwd_kernel6Params.has_indirect_call, 0

amdhsa.kernels:
  - .agpr_count:     0
    .args:
      - .offset:         0
        .size:           208
        .value_kind:     by_value
      - .offset:         208
        .size:           4
        .value_kind:     hidden_block_count_x
      - .offset:         212
        .size:           4
        .value_kind:     hidden_block_count_y
      - .offset:         216
        .size:           4
        .value_kind:     hidden_block_count_z
      - .offset:         220
        .size:           2
        .value_kind:     hidden_group_size_x
      - .offset:         222
        .size:           2
        .value_kind:     hidden_group_size_y
      - .offset:         224
        .size:           2
        .value_kind:     hidden_group_size_z
      - .offset:         226
        .size:           2
        .value_kind:     hidden_remainder_x
      - .offset:         228
        .size:           2
        .value_kind:     hidden_remainder_y
      - .offset:         230
        .size:           2
        .value_kind:     hidden_remainder_z
      - .offset:         248
        .size:           8
        .value_kind:     hidden_global_offset_x
      - .offset:         256
        .size:           8
        .value_kind:     hidden_global_offset_y
      - .offset:         264
        .size:           8
        .value_kind:     hidden_global_offset_z
      - .offset:         272
        .size:           2
        .value_kind:     hidden_grid_dims
      - .offset:         296
        .size:           8
        .value_kind:     hidden_multigrid_sync_arg
      - .offset:         328
        .size:           4
        .value_kind:     hidden_dynamic_lds_size
    .group_segment_fixed_size: 0
    .kernarg_segment_align: 8
    .kernarg_segment_size: 464
    .language:       OpenCL C
    .language_version:
      - 2
      - 0
    .max_flat_workgroup_size: 512
    .name:           _Z10fwd_kernel6Params
    .private_segment_fixed_size: 0
    .sgpr_count:     106
    .sgpr_spill_count: 265
    .symbol:         _Z10fwd_kernel6Params.kd
    .uniform_work_group_size: 1
    .uses_dynamic_stack: false
    .vgpr_count:     256
    .vgpr_spill_count: 0
    .wavefront_size: 64
